# ConvGLU GEMM epilogues: 416 dead zero-inits of the DPP row_ror destination registers removed (instruction-selection cleanup, all lanes overwritten by the rotate)
# speedup vs baseline: 1.0097x; 1.0019x over previous
; #define PG8_STAGE(bufoff, gbase, voff) do { _Pragma("unroll") for (int _i = 0; _i < 2; ++_i) \
;         __builtin_amdgcn_global_load_lds((const unsigned*)((const char*)(gbase) + (voff)[_i]), (LAS unsigned*)(lds + (bufoff) + ldsw + _i * 8192), 16, 0, 0); } while (0)
; #define PG8_LDA(dst, b, h) do { _Pragma("unroll") for (int m = 0; m < 4; ++m) _Pragma("unroll") for (int k = 0; k < 2; ++k) dst[m][k] = *(const LAS bf16x8*)(lds + PG8_SA(b, h) + aoff + m * 2048 + k * 1024); } while (0)
; #define PG8_LDB(dst, b, h) do { _Pragma("unroll") for (int n = 0; n < 2; ++n) _Pragma("unroll") for (int k = 0; k < 2; ++k) dst[n][k] = *(const LAS bf16x8*)(lds + PG8_SB(b, h) + boff + n * 2048 + k * 1024); } while (0)
; #define PG8_WAIT_V(n) asm volatile("s_waitcnt vmcnt(" #n ")" ::: "memory")
; #define PG8_WAIT_L(n) asm volatile("s_waitcnt lgkmcnt(" #n ")" ::: "memory")
; #define PG8_BAR __builtin_amdgcn_s_barrier()
; #define PG8_SCHED __builtin_amdgcn_sched_barrier(0)
; template <class Map, class Epi>
; DI void gemm_phase(LAS unsigned char* lds, const Map& MP, const Epi& E, const int nM, const int nN, const int K, const int lda, const int ldb) {
;     ...
;             PG8_LDB(B0, 0, 0); PG8_SCHED; PG8_LDA(At, 0, 0); PG8_STAGE(PG8_SA(1, 1), a1 + hstepA, voffA);
;             PG8_WAIT_L(8); PG8_BAR; PG8_WAIT_L(0); PG8_MMA(0, 0, At, B0); PG8_BAR; PG8_SCHED;
;             PG8_LDB(B1, 0, 1); PG8_STAGE(PG8_SB(0, 0), b2, voffB);
;             PG8_BAR; PG8_WAIT_L(0); PG8_MMA(0, 1, At, B1); PG8_BAR;
;             PG8_LDA(At, 0, 1); PG8_STAGE(PG8_SA(0, 0), a2, voffA);
;             PG8_BAR; PG8_WAIT_L(0); PG8_MMA(1, 0, At, B0); PG8_BAR; PG8_SCHED;
;             PG8_STAGE(PG8_SB(0, 1), b2 + hstepB, voffB);
;             PG8_WAIT_V(6); PG8_BAR; PG8_MMA(1, 1, At, B1); PG8_BAR;
;             PG8_LDB(B0, 1, 0); PG8_SCHED; PG8_LDA(At, 1, 0); PG8_STAGE(PG8_SA(0, 1), a2 + hstepA, voffA);
;             PG8_WAIT_L(8); PG8_BAR; PG8_WAIT_L(0); PG8_MMA(0, 0, At, B0); PG8_BAR; PG8_SCHED;
;             PG8_LDB(B1, 1, 1); PG8_STAGE(PG8_SB(1, 0), b3, voffB);
;             PG8_BAR; PG8_WAIT_L(0); PG8_MMA(0, 1, At, B1); PG8_BAR;
;             PG8_LDA(At, 1, 1); PG8_STAGE(PG8_SA(1, 0), a3, voffA);
;             PG8_BAR; PG8_WAIT_L(0); PG8_MMA(1, 0, At, B0); PG8_BAR; PG8_SCHED;
;             PG8_STAGE(PG8_SB(1, 1), b3 + hstepB, voffB);
;             PG8_WAIT_V(6); PG8_BAR; PG8_MMA(1, 1, At, B1); PG8_BAR;
.LBB1_380:
	s_add_u32 s28, s44, 0xfff80080
	s_addc_u32 s29, s45, -1
	s_cmp_eq_u32 vcc_hi, 28
	s_cselect_b32 s47, s23, s29
	s_cselect_b32 s46, s61, s28
	s_cselect_b32 s29, s21, vcc_lo
	s_cselect_b32 s28, s58, s59
	s_add_i32 m0, s38, 0xc000
	ds_read_b128 v[96:99], v190
	ds_read_b128 v[100:103], v190 offset:1024
	ds_read_b128 v[108:111], v190 offset:2048
	ds_read_b128 v[112:115], v190 offset:3072
	ds_read_b128 v[160:163], v190 offset:4096
	ds_read_b128 v[164:167], v190 offset:5120
	ds_read_b128 v[198:201], v190 offset:6144
	ds_read_b128 v[202:205], v190 offset:7168
	global_load_lds_dwordx4 v178, s[44:45]
	s_add_i32 m0, s38, 0xe000
	s_nop 0
	global_load_lds_dwordx4 v176, s[44:45]
	s_waitcnt lgkmcnt(8)
	s_setprio 1
	s_barrier
	s_waitcnt lgkmcnt(7)
	v_mfma_f32_16x16x32_bf16 v[148:151], v[80:83], v[96:99], v[148:151]
	v_mfma_f32_16x16x32_bf16 v[144:147], v[88:91], v[96:99], v[144:147]
	s_waitcnt lgkmcnt(5)
	v_mfma_f32_16x16x32_bf16 v[136:139], v[80:83], v[108:111], v[136:139]
	v_mfma_f32_16x16x32_bf16 v[128:131], v[88:91], v[108:111], v[128:131]
	s_waitcnt lgkmcnt(3)
	v_mfma_f32_16x16x32_bf16 v[120:123], v[80:83], v[160:163], v[120:123]
	v_mfma_f32_16x16x32_bf16 v[104:107], v[88:91], v[160:163], v[104:107]
	s_waitcnt lgkmcnt(1)
	v_mfma_f32_16x16x32_bf16 v[76:79], v[80:83], v[198:201], v[76:79]
	v_mfma_f32_16x16x32_bf16 v[72:75], v[88:91], v[198:201], v[72:75]
	v_mfma_f32_16x16x32_bf16 v[148:151], v[84:87], v[100:103], v[148:151]
	v_mfma_f32_16x16x32_bf16 v[144:147], v[92:95], v[100:103], v[144:147]
	v_mfma_f32_16x16x32_bf16 v[136:139], v[84:87], v[112:115], v[136:139]
	v_mfma_f32_16x16x32_bf16 v[128:131], v[92:95], v[112:115], v[128:131]
	v_mfma_f32_16x16x32_bf16 v[120:123], v[84:87], v[164:167], v[120:123]
	v_mfma_f32_16x16x32_bf16 v[104:107], v[92:95], v[164:167], v[104:107]
	s_waitcnt lgkmcnt(0)
	v_mfma_f32_16x16x32_bf16 v[76:79], v[84:87], v[202:205], v[76:79]
	v_mfma_f32_16x16x32_bf16 v[72:75], v[92:95], v[202:205], v[72:75]
	s_barrier
	s_setprio 0
	s_add_i32 s68, s5, s37
	v_lshl_add_u64 v[184:185], s[28:29], 0, v[172:173]
	s_mov_b32 m0, s68
	ds_read_b128 v[206:209], v191
	ds_read_b128 v[210:213], v191 offset:1024
	ds_read_b128 v[214:217], v191 offset:2048
	ds_read_b128 v[218:221], v191 offset:3072
	global_load_lds_dwordx4 v[184:185], off
	v_lshl_add_u64 v[194:195], s[28:29], 0, v[168:169]
	s_add_i32 m0, s68, 0x2000
	s_nop 0
	global_load_lds_dwordx4 v[194:195], off
	s_setprio 1
	s_barrier
	s_waitcnt lgkmcnt(3)
	v_mfma_f32_16x16x32_bf16 v[156:159], v[206:209], v[96:99], v[156:159]
	s_waitcnt lgkmcnt(1)
	v_mfma_f32_16x16x32_bf16 v[96:99], v[214:217], v[96:99], v[152:155]
	v_mfma_f32_16x16x32_bf16 v[156:159], v[210:213], v[100:103], v[156:159]
	s_waitcnt lgkmcnt(0)
	v_mfma_f32_16x16x32_bf16 v[96:99], v[218:221], v[100:103], v[96:99]
	v_mfma_f32_16x16x32_bf16 v[100:103], v[206:209], v[108:111], v[140:143]
	v_mfma_f32_16x16x32_bf16 v[108:111], v[214:217], v[108:111], v[132:135]
	v_mfma_f32_16x16x32_bf16 v[116:119], v[214:217], v[160:163], v[116:119]
	v_mfma_f32_16x16x32_bf16 v[68:71], v[206:209], v[198:201], v[68:71]
	v_mfma_f32_16x16x32_bf16 v[64:67], v[214:217], v[198:201], v[64:67]
	s_mov_b32 m0, s38
	v_mfma_f32_16x16x32_bf16 v[100:103], v[210:213], v[112:115], v[100:103]
	v_lshl_add_u64 v[226:227], s[46:47], 0, v[174:175]
	v_mfma_f32_16x16x32_bf16 v[108:111], v[218:221], v[112:115], v[108:111]
	v_mfma_f32_16x16x32_bf16 v[112:115], v[206:209], v[160:163], v[124:127]
	v_mfma_f32_16x16x32_bf16 v[116:119], v[218:221], v[164:167], v[116:119]
	v_mfma_f32_16x16x32_bf16 v[68:71], v[210:213], v[202:205], v[68:71]
	v_mfma_f32_16x16x32_bf16 v[64:67], v[218:221], v[202:205], v[64:67]
	v_mfma_f32_16x16x32_bf16 v[112:115], v[210:213], v[164:167], v[112:115]
	s_barrier
	s_setprio 0
	ds_read_b128 v[124:127], v190 offset:16384
	ds_read_b128 v[132:135], v190 offset:17408
	ds_read_b128 v[140:143], v190 offset:18432
	ds_read_b128 v[152:155], v190 offset:19456
	ds_read_b128 v[160:163], v190 offset:20480
	ds_read_b128 v[164:167], v190 offset:21504
	ds_read_b128 v[198:201], v190 offset:22528
	ds_read_b128 v[202:205], v190 offset:23552
	global_load_lds_dwordx4 v[226:227], off
	v_lshl_add_u64 v[234:235], s[46:47], 0, v[170:171]
	s_mov_b32 m0, s39
	s_nop 0
	global_load_lds_dwordx4 v[234:235], off
	s_waitcnt vmcnt(10)
	s_setprio 1
	s_barrier
	s_waitcnt lgkmcnt(7)
	v_mfma_f32_16x16x32_bf16 v[60:63], v[80:83], v[124:127], v[60:63]
	v_mfma_f32_16x16x32_bf16 v[48:51], v[88:91], v[124:127], v[48:51]
	s_waitcnt lgkmcnt(5)
	v_mfma_f32_16x16x32_bf16 v[40:43], v[80:83], v[140:143], v[40:43]
	v_mfma_f32_16x16x32_bf16 v[32:35], v[88:91], v[140:143], v[32:35]
	s_waitcnt lgkmcnt(3)
	v_mfma_f32_16x16x32_bf16 v[24:27], v[80:83], v[160:163], v[24:27]
	v_mfma_f32_16x16x32_bf16 v[16:19], v[88:91], v[160:163], v[16:19]
	s_waitcnt lgkmcnt(1)
	v_mfma_f32_16x16x32_bf16 v[12:15], v[80:83], v[198:201], v[12:15]
	v_mfma_f32_16x16x32_bf16 v[8:11], v[88:91], v[198:201], v[8:11]
	v_mfma_f32_16x16x32_bf16 v[60:63], v[84:87], v[132:135], v[60:63]
	v_mfma_f32_16x16x32_bf16 v[48:51], v[92:95], v[132:135], v[48:51]
	v_mfma_f32_16x16x32_bf16 v[40:43], v[84:87], v[152:155], v[40:43]
	v_mfma_f32_16x16x32_bf16 v[32:35], v[92:95], v[152:155], v[32:35]
	v_mfma_f32_16x16x32_bf16 v[24:27], v[84:87], v[164:167], v[24:27]
	v_mfma_f32_16x16x32_bf16 v[16:19], v[92:95], v[164:167], v[16:19]
	s_waitcnt lgkmcnt(0)
	v_mfma_f32_16x16x32_bf16 v[12:15], v[84:87], v[202:205], v[12:15]
	v_mfma_f32_16x16x32_bf16 v[8:11], v[92:95], v[202:205], v[8:11]
	s_barrier
	s_setprio 0
	s_add_u32 s68, s28, 0x80000
	s_addc_u32 s69, s29, 0
	s_add_i32 s70, s2, s37
	s_mov_b32 m0, s70
	s_nop 0
	global_load_lds_dwordx4 v172, s[68:69]
	s_add_i32 m0, s70, 0x2000
	s_nop 0
	global_load_lds_dwordx4 v168, s[68:69]
	s_waitcnt vmcnt(6)
	s_setprio 1
	s_barrier
; #define PG8_STAGE(bufoff, gbase, voff) do { _Pragma("unroll") for (int _i = 0; _i < 2; ++_i) \
;         __builtin_amdgcn_global_load_lds((const unsigned*)((const char*)(gbase) + (voff)[_i]), (LAS unsigned*)(lds + (bufoff) + ldsw + _i * 8192), 16, 0, 0); } while (0)
; #define PG8_LDA(dst, b, h) do { _Pragma("unroll") for (int m = 0; m < 4; ++m) _Pragma("unroll") for (int k = 0; k < 2; ++k) dst[m][k] = *(const LAS bf16x8*)(lds + PG8_SA(b, h) + aoff + m * 2048 + k * 1024); } while (0)
; #define PG8_LDB(dst, b, h) do { _Pragma("unroll") for (int n = 0; n < 2; ++n) _Pragma("unroll") for (int k = 0; k < 2; ++k) dst[n][k] = *(const LAS bf16x8*)(lds + PG8_SB(b, h) + boff + n * 2048 + k * 1024); } while (0)
; #define PG8_WAIT_V(n) asm volatile("s_waitcnt vmcnt(" #n ")" ::: "memory")
; #define PG8_WAIT_L(n) asm volatile("s_waitcnt lgkmcnt(" #n ")" ::: "memory")
; #define PG8_BAR __builtin_amdgcn_s_barrier()
; #define PG8_SCHED __builtin_amdgcn_sched_barrier(0)
; template <class Map, class Epi>
; DI void gemm_phase(LAS unsigned char* lds, const Map& MP, const Epi& E, const int nM, const int nN, const int K, const int lda, const int ldb) {
;     ...
;             PG8_LDB(B0, 0, 0); PG8_SCHED; PG8_LDA(At, 0, 0); PG8_STAGE(PG8_SA(1, 1), a1 + hstepA, voffA);
;             PG8_WAIT_L(8); PG8_BAR; PG8_WAIT_L(0); PG8_MMA(0, 0, At, B0); PG8_BAR; PG8_SCHED;
;             PG8_LDB(B1, 0, 1); PG8_STAGE(PG8_SB(0, 0), b2, voffB);
;             PG8_BAR; PG8_WAIT_L(0); PG8_MMA(0, 1, At, B1); PG8_BAR;
;             PG8_LDA(At, 0, 1); PG8_STAGE(PG8_SA(0, 0), a2, voffA);
;             PG8_BAR; PG8_WAIT_L(0); PG8_MMA(1, 0, At, B0); PG8_BAR; PG8_SCHED;
;             PG8_STAGE(PG8_SB(0, 1), b2 + hstepB, voffB);
;             PG8_WAIT_V(6); PG8_BAR; PG8_MMA(1, 1, At, B1); PG8_BAR;
;             PG8_LDB(B0, 1, 0); PG8_SCHED; PG8_LDA(At, 1, 0); PG8_STAGE(PG8_SA(0, 1), a2 + hstepA, voffA);
;             PG8_WAIT_L(8); PG8_BAR; PG8_WAIT_L(0); PG8_MMA(0, 0, At, B0); PG8_BAR; PG8_SCHED;
;             PG8_LDB(B1, 1, 1); PG8_STAGE(PG8_SB(1, 0), b3, voffB);
;             PG8_BAR; PG8_WAIT_L(0); PG8_MMA(0, 1, At, B1); PG8_BAR;
;             PG8_LDA(At, 1, 1); PG8_STAGE(PG8_SA(1, 0), a3, voffA);
;             PG8_BAR; PG8_WAIT_L(0); PG8_MMA(1, 0, At, B0); PG8_BAR; PG8_SCHED;
;             PG8_STAGE(PG8_SB(1, 1), b3 + hstepB, voffB);
;             PG8_WAIT_V(6); PG8_BAR; PG8_MMA(1, 1, At, B1); PG8_BAR;
	v_mfma_f32_16x16x32_bf16 v[56:59], v[206:209], v[124:127], v[56:59]
	v_mfma_f32_16x16x32_bf16 v[52:55], v[214:217], v[124:127], v[52:55]
	s_add_i32 s68, 0, 0x18000
	v_add_u32_e32 v92, s68, v188
	ds_read_b128 v[80:83], v92
	v_mfma_f32_16x16x32_bf16 v[44:47], v[206:209], v[140:143], v[44:47]
	v_mfma_f32_16x16x32_bf16 v[36:39], v[214:217], v[140:143], v[36:39]
	ds_read_b128 v[84:87], v92 offset:1024
	v_mfma_f32_16x16x32_bf16 v[28:31], v[206:209], v[160:163], v[28:31]
	v_mfma_f32_16x16x32_bf16 v[20:23], v[214:217], v[160:163], v[20:23]
	ds_read_b128 v[88:91], v92 offset:2048
	v_mfma_f32_16x16x32_bf16 v[4:7], v[206:209], v[198:201], v[4:7]
	v_mfma_f32_16x16x32_bf16 v[0:3], v[214:217], v[198:201], v[0:3]
	ds_read_b128 v[92:95], v92 offset:3072
	v_mfma_f32_16x16x32_bf16 v[56:59], v[210:213], v[132:135], v[56:59]
	v_mfma_f32_16x16x32_bf16 v[52:55], v[218:221], v[132:135], v[52:55]
	v_mfma_f32_16x16x32_bf16 v[44:47], v[210:213], v[152:155], v[44:47]
	v_mfma_f32_16x16x32_bf16 v[36:39], v[218:221], v[152:155], v[36:39]
	v_mfma_f32_16x16x32_bf16 v[28:31], v[210:213], v[164:167], v[28:31]
	v_mfma_f32_16x16x32_bf16 v[20:23], v[218:221], v[164:167], v[20:23]
	v_mfma_f32_16x16x32_bf16 v[4:7], v[210:213], v[202:205], v[4:7]
	v_mfma_f32_16x16x32_bf16 v[0:3], v[218:221], v[202:205], v[0:3]
	s_barrier
	s_setprio 0
	s_add_u32 s46, s46, 0x80000
	s_addc_u32 s47, s47, 0
	s_mov_b32 m0, s56
	ds_read_b128 v[124:127], v190 offset:32768
	ds_read_b128 v[132:135], v190 offset:33792
	ds_read_b128 v[160:163], v190 offset:34816
	ds_read_b128 v[164:167], v190 offset:35840
	ds_read_b128 v[198:201], v190 offset:36864
	ds_read_b128 v[202:205], v190 offset:37888
	ds_read_b128 v[206:209], v190 offset:38912
	ds_read_b128 v[210:213], v190 offset:39936
	global_load_lds_dwordx4 v174, s[46:47]
	s_mov_b32 m0, s57
	s_nop 0
	global_load_lds_dwordx4 v170, s[46:47]
	s_waitcnt lgkmcnt(8)
	s_setprio 1
	s_barrier
	s_waitcnt lgkmcnt(7)
	v_mfma_f32_16x16x32_bf16 v[140:143], v[80:83], v[124:127], v[148:151]
	s_waitcnt lgkmcnt(6)
	v_mfma_f32_16x16x32_bf16 v[148:151], v[84:87], v[132:135], v[140:143]
	v_mfma_f32_16x16x32_bf16 v[140:143], v[88:91], v[124:127], v[144:147]
	s_waitcnt lgkmcnt(5)
	v_mfma_f32_16x16x32_bf16 v[136:139], v[80:83], v[160:163], v[136:139]
	v_mfma_f32_16x16x32_bf16 v[128:131], v[88:91], v[160:163], v[128:131]
	s_waitcnt lgkmcnt(3)
	v_mfma_f32_16x16x32_bf16 v[120:123], v[80:83], v[198:201], v[120:123]
	v_mfma_f32_16x16x32_bf16 v[104:107], v[88:91], v[198:201], v[104:107]
	s_waitcnt lgkmcnt(1)
	v_mfma_f32_16x16x32_bf16 v[76:79], v[80:83], v[206:209], v[76:79]
	v_mfma_f32_16x16x32_bf16 v[72:75], v[88:91], v[206:209], v[72:75]
	v_mfma_f32_16x16x32_bf16 v[144:147], v[92:95], v[132:135], v[140:143]
	v_mfma_f32_16x16x32_bf16 v[136:139], v[84:87], v[164:167], v[136:139]
	v_mfma_f32_16x16x32_bf16 v[128:131], v[92:95], v[164:167], v[128:131]
	v_mfma_f32_16x16x32_bf16 v[120:123], v[84:87], v[202:205], v[120:123]
	v_mfma_f32_16x16x32_bf16 v[104:107], v[92:95], v[202:205], v[104:107]
	s_waitcnt lgkmcnt(0)
	v_mfma_f32_16x16x32_bf16 v[76:79], v[84:87], v[210:213], v[76:79]
	v_mfma_f32_16x16x32_bf16 v[72:75], v[92:95], v[210:213], v[72:75]
	s_barrier
	s_setprio 0
	s_add_i32 s46, 0, 0x1c000
	v_add_u32_e32 v140, s46, v188
	s_add_i32 s47, s68, s37
	ds_read_b128 v[214:217], v140
	ds_read_b128 v[218:221], v140 offset:1024
	ds_read_b128 v[222:225], v140 offset:2048
	ds_read_b128 v[230:233], v140 offset:3072
	v_lshl_add_u64 v[140:141], v[184:185], 0, s[14:15]
	s_mov_b32 m0, s47
	s_nop 0
	global_load_lds_dwordx4 v[140:141], off
	v_lshl_add_u64 v[140:141], v[194:195], 0, s[14:15]
	s_add_i32 m0, s47, 0x2000
	s_nop 0
	global_load_lds_dwordx4 v[140:141], off
	s_setprio 1
	s_barrier
	s_waitcnt lgkmcnt(1)
	v_mfma_f32_16x16x32_bf16 v[96:99], v[222:225], v[124:127], v[96:99]
	v_mfma_f32_16x16x32_bf16 v[140:143], v[214:217], v[124:127], v[156:159]
	s_waitcnt lgkmcnt(0)
	v_mfma_f32_16x16x32_bf16 v[152:155], v[230:233], v[132:135], v[96:99]
	v_mfma_f32_16x16x32_bf16 v[96:99], v[214:217], v[160:163], v[100:103]
	v_mfma_f32_16x16x32_bf16 v[156:159], v[218:221], v[132:135], v[140:143]
	v_mfma_f32_16x16x32_bf16 v[140:143], v[218:221], v[164:167], v[96:99]
	v_mfma_f32_16x16x32_bf16 v[96:99], v[222:225], v[160:163], v[108:111]
	v_mfma_f32_16x16x32_bf16 v[132:135], v[230:233], v[164:167], v[96:99]
	v_mfma_f32_16x16x32_bf16 v[96:99], v[214:217], v[198:201], v[112:115]
	s_mov_b32 m0, s62
	v_mfma_f32_16x16x32_bf16 v[124:127], v[218:221], v[202:205], v[96:99]
	v_lshl_add_u64 v[184:185], v[226:227], 0, s[14:15]
	v_mfma_f32_16x16x32_bf16 v[96:99], v[222:225], v[198:201], v[116:119]
	v_mfma_f32_16x16x32_bf16 v[68:71], v[214:217], v[206:209], v[68:71]
	v_mfma_f32_16x16x32_bf16 v[64:67], v[222:225], v[206:209], v[64:67]
	v_mfma_f32_16x16x32_bf16 v[116:119], v[230:233], v[202:205], v[96:99]
	v_mfma_f32_16x16x32_bf16 v[68:71], v[218:221], v[210:213], v[68:71]
	v_mfma_f32_16x16x32_bf16 v[64:67], v[230:233], v[210:213], v[64:67]
	s_barrier
	s_setprio 0
	ds_read_b128 v[96:99], v190 offset:49152
	ds_read_b128 v[100:103], v190 offset:50176
	ds_read_b128 v[108:111], v190 offset:51200
	ds_read_b128 v[112:115], v190 offset:52224
	ds_read_b128 v[160:163], v190 offset:53248
	ds_read_b128 v[164:167], v190 offset:54272
	ds_read_b128 v[198:201], v190 offset:55296
	ds_read_b128 v[202:205], v190 offset:56320
	global_load_lds_dwordx4 v[184:185], off
	v_lshl_add_u64 v[184:185], v[234:235], 0, s[14:15]
	s_mov_b32 m0, s63
	s_nop 0
	global_load_lds_dwordx4 v[184:185], off
	s_waitcnt vmcnt(10)
	s_setprio 1
	s_barrier
; #define PG8_STAGE(bufoff, gbase, voff) do { _Pragma("unroll") for (int _i = 0; _i < 2; ++_i) \
;         __builtin_amdgcn_global_load_lds((const unsigned*)((const char*)(gbase) + (voff)[_i]), (LAS unsigned*)(lds + (bufoff) + ldsw + _i * 8192), 16, 0, 0); } while (0)
; #define PG8_LDA(dst, b, h) do { _Pragma("unroll") for (int m = 0; m < 4; ++m) _Pragma("unroll") for (int k = 0; k < 2; ++k) dst[m][k] = *(const LAS bf16x8*)(lds + PG8_SA(b, h) + aoff + m * 2048 + k * 1024); } while (0)
; #define PG8_LDB(dst, b, h) do { _Pragma("unroll") for (int n = 0; n < 2; ++n) _Pragma("unroll") for (int k = 0; k < 2; ++k) dst[n][k] = *(const LAS bf16x8*)(lds + PG8_SB(b, h) + boff + n * 2048 + k * 1024); } while (0)
; #define PG8_WAIT_V(n) asm volatile("s_waitcnt vmcnt(" #n ")" ::: "memory")
; #define PG8_WAIT_L(n) asm volatile("s_waitcnt lgkmcnt(" #n ")" ::: "memory")
; #define PG8_BAR __builtin_amdgcn_s_barrier()
; #define PG8_SCHED __builtin_amdgcn_sched_barrier(0)
; template <class Map, class Epi>
; DI void gemm_phase(LAS unsigned char* lds, const Map& MP, const Epi& E, const int nM, const int nN, const int K, const int lda, const int ldb) {
;     ...
;             PG8_LDB(B0, 0, 0); PG8_SCHED; PG8_LDA(At, 0, 0); PG8_STAGE(PG8_SA(1, 1), a1 + hstepA, voffA);
;             PG8_WAIT_L(8); PG8_BAR; PG8_WAIT_L(0); PG8_MMA(0, 0, At, B0); PG8_BAR; PG8_SCHED;
;             PG8_LDB(B1, 0, 1); PG8_STAGE(PG8_SB(0, 0), b2, voffB);
;             PG8_BAR; PG8_WAIT_L(0); PG8_MMA(0, 1, At, B1); PG8_BAR;
;             PG8_LDA(At, 0, 1); PG8_STAGE(PG8_SA(0, 0), a2, voffA);
;             PG8_BAR; PG8_WAIT_L(0); PG8_MMA(1, 0, At, B0); PG8_BAR; PG8_SCHED;
;             PG8_STAGE(PG8_SB(0, 1), b2 + hstepB, voffB);
;             PG8_WAIT_V(6); PG8_BAR; PG8_MMA(1, 1, At, B1); PG8_BAR;
;             PG8_LDB(B0, 1, 0); PG8_SCHED; PG8_LDA(At, 1, 0); PG8_STAGE(PG8_SA(0, 1), a2 + hstepA, voffA);
;             PG8_WAIT_L(8); PG8_BAR; PG8_WAIT_L(0); PG8_MMA(0, 0, At, B0); PG8_BAR; PG8_SCHED;
;             PG8_LDB(B1, 1, 1); PG8_STAGE(PG8_SB(1, 0), b3, voffB);
;             PG8_BAR; PG8_WAIT_L(0); PG8_MMA(0, 1, At, B1); PG8_BAR;
;             PG8_LDA(At, 1, 1); PG8_STAGE(PG8_SA(1, 0), a3, voffA);
;             PG8_BAR; PG8_WAIT_L(0); PG8_MMA(1, 0, At, B0); PG8_BAR; PG8_SCHED;
;             PG8_STAGE(PG8_SB(1, 1), b3 + hstepB, voffB);
;             PG8_WAIT_V(6); PG8_BAR; PG8_MMA(1, 1, At, B1); PG8_BAR;
	s_waitcnt lgkmcnt(7)
	v_mfma_f32_16x16x32_bf16 v[60:63], v[80:83], v[96:99], v[60:63]
	v_mfma_f32_16x16x32_bf16 v[48:51], v[88:91], v[96:99], v[48:51]
	s_waitcnt lgkmcnt(5)
	v_mfma_f32_16x16x32_bf16 v[40:43], v[80:83], v[108:111], v[40:43]
	v_mfma_f32_16x16x32_bf16 v[32:35], v[88:91], v[108:111], v[32:35]
	s_waitcnt lgkmcnt(3)
	v_mfma_f32_16x16x32_bf16 v[24:27], v[80:83], v[160:163], v[24:27]
	v_mfma_f32_16x16x32_bf16 v[16:19], v[88:91], v[160:163], v[16:19]
	s_waitcnt lgkmcnt(1)
	v_mfma_f32_16x16x32_bf16 v[12:15], v[80:83], v[198:201], v[12:15]
	v_mfma_f32_16x16x32_bf16 v[8:11], v[88:91], v[198:201], v[8:11]
	v_mfma_f32_16x16x32_bf16 v[60:63], v[84:87], v[100:103], v[60:63]
	v_mfma_f32_16x16x32_bf16 v[48:51], v[92:95], v[100:103], v[48:51]
	v_mfma_f32_16x16x32_bf16 v[40:43], v[84:87], v[112:115], v[40:43]
	v_mfma_f32_16x16x32_bf16 v[32:35], v[92:95], v[112:115], v[32:35]
	v_mfma_f32_16x16x32_bf16 v[24:27], v[84:87], v[164:167], v[24:27]
	v_mfma_f32_16x16x32_bf16 v[16:19], v[92:95], v[164:167], v[16:19]
	s_waitcnt lgkmcnt(0)
	v_mfma_f32_16x16x32_bf16 v[12:15], v[84:87], v[202:205], v[12:15]
	v_mfma_f32_16x16x32_bf16 v[8:11], v[92:95], v[202:205], v[8:11]
	s_barrier
	s_setprio 0
	s_add_u32 s28, s28, 0x80080
	s_addc_u32 s29, s29, 0
	s_add_i32 s46, s46, s37
	s_mov_b32 m0, s46
	s_nop 0
	global_load_lds_dwordx4 v172, s[28:29]
	s_add_i32 m0, s46, 0x2000
	s_nop 0
	global_load_lds_dwordx4 v168, s[28:29]
	s_waitcnt vmcnt(6)
	s_setprio 1
	s_barrier
	v_mfma_f32_16x16x32_bf16 v[56:59], v[214:217], v[96:99], v[56:59]
	v_mfma_f32_16x16x32_bf16 v[52:55], v[222:225], v[96:99], v[52:55]
	ds_read_b128 v[80:83], v189
	v_mfma_f32_16x16x32_bf16 v[44:47], v[214:217], v[108:111], v[44:47]
	v_mfma_f32_16x16x32_bf16 v[36:39], v[222:225], v[108:111], v[36:39]
	ds_read_b128 v[84:87], v189 offset:1024
	v_mfma_f32_16x16x32_bf16 v[28:31], v[214:217], v[160:163], v[28:31]
	v_mfma_f32_16x16x32_bf16 v[20:23], v[222:225], v[160:163], v[20:23]
	ds_read_b128 v[88:91], v189 offset:2048
	v_mfma_f32_16x16x32_bf16 v[4:7], v[214:217], v[198:201], v[4:7]
	v_mfma_f32_16x16x32_bf16 v[0:3], v[222:225], v[198:201], v[0:3]
	ds_read_b128 v[92:95], v189 offset:3072
	v_mfma_f32_16x16x32_bf16 v[56:59], v[218:221], v[100:103], v[56:59]
	s_add_i32 vcc_hi, vcc_hi, 2
	v_mfma_f32_16x16x32_bf16 v[52:55], v[230:233], v[100:103], v[52:55]
	s_add_u32 s59, s59, 0x100
	s_addc_u32 vcc_lo, vcc_lo, 0
	v_mfma_f32_16x16x32_bf16 v[44:47], v[218:221], v[112:115], v[44:47]
	s_add_u32 s44, s44, 0x100
	s_addc_u32 s45, s45, 0
	v_mfma_f32_16x16x32_bf16 v[36:39], v[230:233], v[112:115], v[36:39]
	s_cmp_gt_u32 vcc_hi, 29
	v_mfma_f32_16x16x32_bf16 v[28:31], v[218:221], v[164:167], v[28:31]
	v_mfma_f32_16x16x32_bf16 v[20:23], v[230:233], v[164:167], v[20:23]
	v_mfma_f32_16x16x32_bf16 v[4:7], v[218:221], v[202:205], v[4:7]
	v_mfma_f32_16x16x32_bf16 v[0:3], v[230:233], v[202:205], v[0:3]
	s_barrier
	s_setprio 0
	s_cbranch_scc0 .LBB1_380
; DI float silu_mul(float g, float v) { return g * v * __builtin_amdgcn_rcpf(1.0f + __builtin_amdgcn_exp2f(-LOG2E * g)); }
;     DI void operator()(const f32x4 (&acc)[2][2][4][2], const Unit& u, int wr, int wc, int fr, int fq) const {
;         const int row0 = u.pm * BM + wr * 64 + fr, ch0 = u.pn * 128 + wc * 32 + 8 * fq;
;         f32x4 w0[2], w1[2], w2[2], bb[2];
; #pragma unroll
;         for (int n = 0; n < 2; ++n) { w0[n] = *(const f32x4*)(cw + ch0 + 4 * n); w1[n] = *(const f32x4*)(cw + DFF + ch0 + 4 * n); w2[n] = *(const f32x4*)(cw + 2 * DFF + ch0 + 4 * n); bb[n] = *(const f32x4*)(cb + ch0 + 4 * n); }
; #pragma unroll
;         for (int ai = 0; ai < 2; ++ai)
; #pragma unroll
;             for (int m = 0; m < 4; ++m) {
;                 const bool efirst = (m == 0) && (fr == 0), elast = (m == 3) && (fr == 15);
;                 const int row = row0 + ai * HALF + m * 16;
;                 f32x4 gc[2];
; #pragma unroll
;                 for (int n = 0; n < 2; ++n) {
;                     const f32x4 g = acc[ai][0][m][n];
;                     const f32x4 gprev = acc[ai][0][m > 0 ? m - 1 : 0][n], gnext = acc[ai][0][m < 3 ? m + 1 : 3][n];
;                     f32x4 up, dn;
; #pragma unroll
;                     for (int e = 0; e < 4; ++e) {
;                         const float pu = (m > 0 && fr == 15) ? gprev[e] : g[e];
;                         const float pd = (m < 3 && fr == 0) ? gnext[e] : g[e];
;                         up[e] = dpp_ror1(pu); dn[e] = dpp_ror15(pd);
;                     }
;                     if (efirst) up = (f32x4){0.f, 0.f, 0.f, 0.f};
;                     if (elast) dn = (f32x4){0.f, 0.f, 0.f, 0.f};
;                     gc[n] = w0[n] * up + w1[n] * g + w2[n] * dn + bb[n];
;                 }
;                 if (efirst || elast) {
;                     const size_t eo = (size_t)((row >> 6) * 2 + (elast ? 1 : 0)) * DFF + ch0;
; #pragma unroll
;                     for (int n = 0; n < 2; ++n) { *(f32x4*)(EP + eo + 4 * n) = gc[n]; *(f32x4*)(ER + eo + 4 * n) = acc[ai][0][m][n]; *(f32x4*)(EV + eo + 4 * n) = acc[ai][1][m][n]; }
;                 } else {
;                     const f32x4 v0 = acc[ai][1][m][0], v1 = acc[ai][1][m][1];
;                     u32x4 o;
;                     o[0] = pack2(silu_mul(gc[0][0], v0[0]), silu_mul(gc[0][1], v0[1])); o[1] = pack2(silu_mul(gc[0][2], v0[2]), silu_mul(gc[0][3], v0[3]));
	s_waitcnt lgkmcnt(0)
	s_lshl_b32 s23, s43, 7
	v_mov_b32_e32 v194, v186
	v_mov_b32_e32 v80, v187
	s_or_b32 s23, s23, s67
	v_lshl_add_u32 v184, v80, 3, s23
	v_ashrrev_i32_e32 v185, 31, v184
	v_lshlrev_b64 v[80:81], 2, v[184:185]
	v_lshl_add_u64 v[84:85], s[52:53], 0, v[80:81]
	v_lshl_add_u64 v[88:89], s[16:17], 0, v[80:81]
	v_lshl_add_u64 v[92:93], s[18:19], 0, v[80:81]
	v_lshl_add_u64 v[112:113], s[54:55], 0, v[80:81]
	global_load_dwordx4 v[80:83], v[84:85], off offset:16
	global_load_dwordx4 v[96:99], v[84:85], off
	s_nop 0
	global_load_dwordx4 v[84:87], v[88:89], off offset:16
	global_load_dwordx4 v[100:103], v[88:89], off
	s_nop 0
	global_load_dwordx4 v[88:91], v[92:93], off offset:16
	global_load_dwordx4 v[108:111], v[92:93], off
	s_nop 0
	global_load_dwordx4 v[92:95], v[112:113], off offset:16
	s_nop 0
	global_load_dwordx4 v[112:115], v[112:113], off
	v_cmp_eq_u32_e32 vcc, 0, v194
	s_nop 0
	s_nop 0
	v_cndmask_b32_e32 v161, v148, v136, vcc
	v_cndmask_b32_e32 v162, v149, v137, vcc
	v_cndmask_b32_e32 v163, v150, v138, vcc
	v_mov_b32_dpp v160, v161 row_ror:15 row_mask:0xf bank_mask:0xf
	s_nop 0
	s_nop 0
	v_mov_b32_dpp v161, v162 row_ror:15 row_mask:0xf bank_mask:0xf
	v_mov_b32_dpp v164, v150 row_ror:1 row_mask:0xf bank_mask:0xf
	v_cndmask_b32_e32 v165, v151, v139, vcc
	v_mov_b32_dpp v162, v163 row_ror:15 row_mask:0xf bank_mask:0xf
	v_mov_b32_dpp v195, v151 row_ror:1 row_mask:0xf bank_mask:0xf
	v_mov_b32_dpp v166, v148 row_ror:1 row_mask:0xf bank_mask:0xf
	v_mov_b32_dpp v167, v149 row_ror:1 row_mask:0xf bank_mask:0xf
	v_mov_b32_dpp v163, v165 row_ror:15 row_mask:0xf bank_mask:0xf
	v_cndmask_b32_e64 v165, v195, 0, vcc
	v_cndmask_b32_e64 v164, v164, 0, vcc
	v_cndmask_b32_e64 v167, v167, 0, vcc
	v_cndmask_b32_e64 v166, v166, 0, vcc
	s_nop 0
	s_nop 0
	v_mov_b32_dpp v195, v144 row_ror:1 row_mask:0xf bank_mask:0xf
	v_mov_b32_dpp v196, v145 row_ror:1 row_mask:0xf bank_mask:0xf
	v_mov_b32_dpp v198, v146 row_ror:1 row_mask:0xf bank_mask:0xf
	v_cndmask_b32_e32 v199, v147, v131, vcc
	v_mov_b32_dpp v200, v147 row_ror:1 row_mask:0xf bank_mask:0xf
	v_cndmask_b32_e64 v198, v198, 0, vcc
	v_cndmask_b32_e64 v201, v196, 0, vcc
	s_lshl_b32 s21, s42, 8
	s_add_i32 s21, s21, s49
	v_add_u32_e32 v193, s21, v194
	v_cmp_ne_u32_e64 s[46:47], 0, v194
	s_waitcnt vmcnt(0)
	v_pk_mul_f32 v[164:165], v[98:99], v[164:165]
	v_pk_mul_f32 v[166:167], v[96:97], v[166:167]
	v_pk_fma_f32 v[164:165], v[150:151], v[102:103], v[164:165]
	v_pk_fma_f32 v[166:167], v[148:149], v[100:101], v[166:167]
	v_pk_fma_f32 v[162:163], v[110:111], v[162:163], v[164:165]
	v_cndmask_b32_e32 v165, v144, v128, vcc
	v_pk_fma_f32 v[160:161], v[108:109], v[160:161], v[166:167]
	v_cndmask_b32_e32 v166, v145, v129, vcc
	v_mov_b32_dpp v164, v165 row_ror:15 row_mask:0xf bank_mask:0xf
	v_cndmask_b32_e32 v167, v146, v130, vcc
	v_pk_add_f32 v[162:163], v[114:115], v[162:163]
	v_mov_b32_dpp v165, v166 row_ror:15 row_mask:0xf bank_mask:0xf
	v_pk_add_f32 v[160:161], v[112:113], v[160:161]
	s_nop 0
	v_mov_b32_dpp v166, v167 row_ror:15 row_mask:0xf bank_mask:0xf
	s_nop 1
	v_mov_b32_dpp v167, v199 row_ror:15 row_mask:0xf bank_mask:0xf
	v_cndmask_b32_e64 v199, v200, 0, vcc
	v_cndmask_b32_e64 v200, v195, 0, vcc
	v_pk_mul_f32 v[200:201], v[80:81], v[200:201]
	v_pk_mul_f32 v[198:199], v[82:83], v[198:199]
	v_pk_fma_f32 v[200:201], v[144:145], v[84:85], v[200:201]
	v_pk_fma_f32 v[198:199], v[146:147], v[86:87], v[198:199]
	v_pk_fma_f32 v[164:165], v[88:89], v[164:165], v[200:201]
	v_pk_fma_f32 v[166:167], v[90:91], v[166:167], v[198:199]
	v_pk_add_f32 v[164:165], v[92:93], v[164:165]
	v_pk_add_f32 v[166:167], v[94:95], v[166:167]
	s_and_saveexec_b64 s[28:29], s[46:47]
	s_xor_b64 s[28:29], exec, s[28:29]
	s_cbranch_execz .LBB1_383
	v_mul_f32_e32 v195, 0xbfb8aa3b, v160
	v_exp_f32_e32 v195, v195
	v_mul_f32_e32 v196, 0xbfb8aa3b, v161
	v_exp_f32_e32 v196, v196
	v_pk_mul_f32 v[160:161], v[156:157], v[160:161]
	v_add_f32_e32 v195, 1.0, v195
	v_rcp_f32_e32 v198, v195
	v_add_f32_e32 v196, 1.0, v196
	v_mul_f32_e32 v195, 0xbfb8aa3b, v162
	v_rcp_f32_e32 v199, v196
	v_exp_f32_e32 v195, v195
	v_mul_f32_e32 v196, 0xbfb8aa3b, v163
	v_exp_f32_e32 v196, v196
	v_pk_mul_f32 v[160:161], v[160:161], v[198:199]
	v_add_f32_e32 v195, 1.0, v195
	v_rcp_f32_e32 v200, v195
	v_add_f32_e32 v195, 1.0, v196
	v_rcp_f32_e32 v201, v195
	v_cvt_pk_bf16_f32 v160, v160, v161
	v_mul_f32_e32 v161, 0xbfb8aa3b, v164
	v_exp_f32_e32 v195, v161
	v_mul_f32_e32 v161, 0xbfb8aa3b, v165
	v_exp_f32_e32 v196, v161
	v_pk_mul_f32 v[162:163], v[158:159], v[162:163]
	v_pk_mul_f32 v[164:165], v[152:153], v[164:165]
	v_pk_mul_f32 v[162:163], v[162:163], v[200:201]
	s_nop 0
	v_cvt_pk_bf16_f32 v161, v162, v163
	v_add_f32_e32 v162, 1.0, v195
	v_mul_f32_e32 v195, 0xbfb8aa3b, v166
	v_add_f32_e32 v163, 1.0, v196
	v_exp_f32_e32 v195, v195
	v_mul_f32_e32 v196, 0xbfb8aa3b, v167
	v_exp_f32_e32 v196, v196
	v_rcp_f32_e32 v162, v162
	v_add_f32_e32 v195, 1.0, v195
	v_rcp_f32_e32 v198, v195
	v_add_f32_e32 v195, 1.0, v196
	v_rcp_f32_e32 v163, v163
	v_rcp_f32_e32 v199, v195
	v_pk_mul_f32 v[166:167], v[154:155], v[166:167]
	v_pk_mul_f32 v[162:163], v[164:165], v[162:163]
	v_pk_mul_f32 v[164:165], v[166:167], v[198:199]
	v_cvt_pk_bf16_f32 v162, v162, v163
	v_cvt_pk_bf16_f32 v163, v164, v165
	v_mov_b64_e32 v[164:165], s[6:7]
	v_mad_i64_i32 v[164:165], s[42:43], v193, s30, v[164:165]
	v_lshl_add_u64 v[164:165], v[184:185], 1, v[164:165]
	global_store_dwordx4 v[164:165], v[160:163], off

; DI unsigned pack2(float a, float b) { f32x2 v = {a, b}; hwbf16x2 r = __builtin_convertvector(v, hwbf16x2); return __builtin_bit_cast(unsigned, r); }
; DI float dpp_ror1(float v)  { return __builtin_bit_cast(float, __builtin_amdgcn_update_dpp(0, __builtin_bit_cast(int, v), 0x121, 0xf, 0xf, false)); }
;     DI void operator()(const f32x4 (&acc)[2][2][4][2], const Unit& u, int wr, int wc, int fr, int fq) const {
;     ...
;             for (int m = 0; m < 4; ++m) {
;                 const bool efirst = (m == 0) && (fr == 0), elast = (m == 3) && (fr == 15);
;                 const int row = row0 + ai * HALF + m * 16;
;                 f32x4 gc[2];
; #pragma unroll
;                 for (int n = 0; n < 2; ++n) {
;                     const f32x4 g = acc[ai][0][m][n];
;                     const f32x4 gprev = acc[ai][0][m > 0 ? m - 1 : 0][n], gnext = acc[ai][0][m < 3 ? m + 1 : 3][n];
;                     f32x4 up, dn;
; #pragma unroll
;                     for (int e = 0; e < 4; ++e) {
;                         const float pu = (m > 0 && fr == 15) ? gprev[e] : g[e];
;                         const float pd = (m < 3 && fr == 0) ? gnext[e] : g[e];
;                         up[e] = dpp_ror1(pu); dn[e] = dpp_ror15(pd);
;                     }
;                     if (efirst) up = (f32x4){0.f, 0.f, 0.f, 0.f};
;                     if (elast) dn = (f32x4){0.f, 0.f, 0.f, 0.f};
;                     gc[n] = w0[n] * up + w1[n] * g + w2[n] * dn + bb[n];
;                 }
;                 if (efirst || elast) {
;                     const size_t eo = (size_t)((row >> 6) * 2 + (elast ? 1 : 0)) * DFF + ch0;
; #pragma unroll
;                     for (int n = 0; n < 2; ++n) { *(f32x4*)(EP + eo + 4 * n) = gc[n]; *(f32x4*)(ER + eo + 4 * n) = acc[ai][0][m][n]; *(f32x4*)(EV + eo + 4 * n) = acc[ai][1][m][n]; }
;                 } else {
;                     const f32x4 v0 = acc[ai][1][m][0], v1 = acc[ai][1][m][1];
;                     u32x4 o;
;                     o[0] = pack2(silu_mul(gc[0][0], v0[0]), silu_mul(gc[0][1], v0[1])); o[1] = pack2(silu_mul(gc[0][2], v0[2]), silu_mul(gc[0][3], v0[3]));
;                     o[2] = pack2(silu_mul(gc[1][0], v1[0]), silu_mul(gc[1][1], v1[1])); o[3] = pack2(silu_mul(gc[1][2], v1[2]), silu_mul(gc[1][3], v1[3]));
;                     *(u32x4*)(ACT + (size_t)row * DFF + ch0) = o;
.LBB1_385:
	s_or_b64 exec, exec, s[28:29]
	v_cmp_eq_u32_e64 s[44:45], 15, v194
	v_cndmask_b32_e32 v153, v136, v120, vcc
	v_cndmask_b32_e32 v154, v137, v121, vcc
	v_cndmask_b32_e64 v152, v136, v148, s[44:45]
	v_cndmask_b32_e32 v155, v138, v122, vcc
	v_cndmask_b32_e32 v156, v139, v123, vcc
	v_mov_b32_dpp v148, v152 row_ror:1 row_mask:0xf bank_mask:0xf
	v_cndmask_b32_e32 v157, v128, v104, vcc
	v_cndmask_b32_e32 v158, v129, v105, vcc
	v_mov_b32_dpp v152, v153 row_ror:15 row_mask:0xf bank_mask:0xf
	v_cndmask_b32_e64 v153, v137, v149, s[44:45]
	v_cndmask_b32_e32 v159, v130, v106, vcc
	v_cndmask_b32_e32 v160, v131, v107, vcc
	v_mov_b32_dpp v149, v153 row_ror:1 row_mask:0xf bank_mask:0xf
	v_pk_mul_f32 v[148:149], v[96:97], v[148:149]
	v_cmp_ne_u32_e64 s[42:43], 15, v194
	v_mov_b32_dpp v153, v154 row_ror:15 row_mask:0xf bank_mask:0xf
	v_pk_fma_f32 v[148:149], v[136:137], v[100:101], v[148:149]
	v_cndmask_b32_e64 v154, v138, v150, s[44:45]
	v_pk_fma_f32 v[148:149], v[108:109], v[152:153], v[148:149]
	s_nop 0
	v_mov_b32_dpp v150, v154 row_ror:1 row_mask:0xf bank_mask:0xf
	v_pk_add_f32 v[148:149], v[112:113], v[148:149]
	s_nop 0
	v_mov_b32_dpp v154, v155 row_ror:15 row_mask:0xf bank_mask:0xf
	v_cndmask_b32_e64 v155, v139, v151, s[44:45]
	v_mul_f32_e32 v152, 0xbfb8aa3b, v148
	v_mul_f32_e32 v153, 0xbfb8aa3b, v149
	v_mov_b32_dpp v151, v155 row_ror:1 row_mask:0xf bank_mask:0xf
	v_exp_f32_e32 v152, v152
	v_exp_f32_e32 v153, v153
	v_pk_mul_f32 v[150:151], v[98:99], v[150:151]
	v_add_f32_e32 v152, 1.0, v152
	v_mov_b32_dpp v155, v156 row_ror:15 row_mask:0xf bank_mask:0xf
	v_cndmask_b32_e64 v156, v128, v144, s[44:45]
	v_pk_fma_f32 v[150:151], v[138:139], v[102:103], v[150:151]
	v_add_f32_e32 v153, 1.0, v153
	v_mov_b32_dpp v144, v156 row_ror:1 row_mask:0xf bank_mask:0xf
	v_pk_fma_f32 v[150:151], v[110:111], v[154:155], v[150:151]
	v_rcp_f32_e32 v152, v152
	v_mov_b32_dpp v156, v157 row_ror:15 row_mask:0xf bank_mask:0xf
	v_cndmask_b32_e64 v157, v129, v145, s[44:45]
	v_pk_add_f32 v[150:151], v[114:115], v[150:151]
	v_rcp_f32_e32 v153, v153
	v_mov_b32_dpp v145, v157 row_ror:1 row_mask:0xf bank_mask:0xf
	v_mul_f32_e32 v154, 0xbfb8aa3b, v150
	v_mul_f32_e32 v155, 0xbfb8aa3b, v151
	v_pk_mul_f32 v[144:145], v[80:81], v[144:145]
	v_exp_f32_e32 v154, v154
	v_exp_f32_e32 v155, v155
	v_mov_b32_dpp v157, v158 row_ror:15 row_mask:0xf bank_mask:0xf
	v_pk_fma_f32 v[144:145], v[128:129], v[84:85], v[144:145]
	v_cndmask_b32_e64 v158, v130, v146, s[44:45]
	v_pk_fma_f32 v[144:145], v[88:89], v[156:157], v[144:145]
	v_pk_mul_f32 v[140:141], v[140:141], v[148:149]
	v_mov_b32_dpp v146, v158 row_ror:1 row_mask:0xf bank_mask:0xf
	v_pk_add_f32 v[144:145], v[92:93], v[144:145]
	v_pk_mul_f32 v[140:141], v[140:141], v[152:153]
	v_mov_b32_dpp v158, v159 row_ror:15 row_mask:0xf bank_mask:0xf
	v_cndmask_b32_e64 v159, v131, v147, s[44:45]
	v_pk_mul_f32 v[142:143], v[142:143], v[150:151]
	v_add_f32_e32 v150, 1.0, v154
	v_add_f32_e32 v151, 1.0, v155
	v_cvt_pk_bf16_f32 v140, v140, v141
	v_mul_f32_e32 v141, 0xbfb8aa3b, v144
	v_mov_b32_dpp v147, v159 row_ror:1 row_mask:0xf bank_mask:0xf
	v_rcp_f32_e32 v150, v150
	v_rcp_f32_e32 v151, v151
	v_exp_f32_e32 v148, v141
	v_mul_f32_e32 v141, 0xbfb8aa3b, v145
	v_pk_mul_f32 v[146:147], v[82:83], v[146:147]
	v_exp_f32_e32 v149, v141
	v_mov_b32_dpp v159, v160 row_ror:15 row_mask:0xf bank_mask:0xf
	v_pk_fma_f32 v[146:147], v[130:131], v[86:87], v[146:147]
	v_pk_mul_f32 v[142:143], v[142:143], v[150:151]
	v_pk_fma_f32 v[146:147], v[90:91], v[158:159], v[146:147]
	v_cvt_pk_bf16_f32 v141, v142, v143
	v_pk_add_f32 v[146:147], v[94:95], v[146:147]
	v_add_f32_e32 v142, 1.0, v148
	v_add_f32_e32 v143, 1.0, v149
	v_mul_f32_e32 v148, 0xbfb8aa3b, v146
	v_mul_f32_e32 v149, 0xbfb8aa3b, v147
	v_exp_f32_e32 v148, v148
	v_exp_f32_e32 v149, v149
	v_rcp_f32_e32 v142, v142
	v_rcp_f32_e32 v143, v143
	v_pk_mul_f32 v[134:135], v[134:135], v[146:147]
	v_add_f32_e32 v146, 1.0, v148
	v_add_f32_e32 v147, 1.0, v149
	v_rcp_f32_e32 v146, v146
	v_rcp_f32_e32 v147, v147
	v_pk_mul_f32 v[132:133], v[132:133], v[144:145]
	v_add_u32_e32 v160, 16, v193
	v_pk_mul_f32 v[132:133], v[132:133], v[142:143]
	v_cndmask_b32_e32 v148, v107, v75, vcc
	v_cvt_pk_bf16_f32 v142, v132, v133
	v_pk_mul_f32 v[132:133], v[134:135], v[146:147]
	v_mov_b64_e32 v[134:135], s[6:7]
	v_cvt_pk_bf16_f32 v143, v132, v133
	v_mad_i64_i32 v[144:145], s[28:29], v160, s30, v[134:135]
	v_lshlrev_b64 v[132:133], 1, v[184:185]
	v_lshl_add_u64 v[144:145], v[144:145], 0, v[132:133]
	global_store_dwordx4 v[144:145], v[140:143], off
	v_cndmask_b32_e32 v144, v123, v79, vcc
	v_cndmask_b32_e32 v145, v104, v72, vcc
	v_cndmask_b32_e64 v140, v120, v136, s[44:45]
	v_cndmask_b32_e32 v141, v120, v76, vcc
	v_cndmask_b32_e32 v142, v121, v77, vcc
	v_mov_b32_dpp v136, v140 row_ror:1 row_mask:0xf bank_mask:0xf
	v_cndmask_b32_e32 v143, v122, v78, vcc
	v_cndmask_b32_e32 v146, v105, v73, vcc
	v_mov_b32_dpp v140, v141 row_ror:15 row_mask:0xf bank_mask:0xf
	v_cndmask_b32_e64 v141, v121, v137, s[44:45]
	v_cndmask_b32_e32 v147, v106, v74, vcc
	s_nop 0
	v_mov_b32_dpp v137, v141 row_ror:1 row_mask:0xf bank_mask:0xf
	v_pk_mul_f32 v[136:137], v[96:97], v[136:137]
	s_nop 0
	v_mov_b32_dpp v141, v142 row_ror:15 row_mask:0xf bank_mask:0xf
	v_pk_fma_f32 v[136:137], v[120:121], v[100:101], v[136:137]
	v_cndmask_b32_e64 v142, v122, v138, s[44:45]
	v_pk_fma_f32 v[136:137], v[108:109], v[140:141], v[136:137]
	s_nop 0
	v_mov_b32_dpp v138, v142 row_ror:1 row_mask:0xf bank_mask:0xf
	v_pk_add_f32 v[136:137], v[112:113], v[136:137]
	s_nop 0
	v_mov_b32_dpp v142, v143 row_ror:15 row_mask:0xf bank_mask:0xf
	v_cndmask_b32_e64 v143, v123, v139, s[44:45]
	v_mul_f32_e32 v140, 0xbfb8aa3b, v136
; DI unsigned pack2(float a, float b) { f32x2 v = {a, b}; hwbf16x2 r = __builtin_convertvector(v, hwbf16x2); return __builtin_bit_cast(unsigned, r); }
; DI float dpp_ror1(float v)  { return __builtin_bit_cast(float, __builtin_amdgcn_update_dpp(0, __builtin_bit_cast(int, v), 0x121, 0xf, 0xf, false)); }
;     DI void operator()(const f32x4 (&acc)[2][2][4][2], const Unit& u, int wr, int wc, int fr, int fq) const {
;     ...
;             for (int m = 0; m < 4; ++m) {
;                 const bool efirst = (m == 0) && (fr == 0), elast = (m == 3) && (fr == 15);
;                 const int row = row0 + ai * HALF + m * 16;
;                 f32x4 gc[2];
; #pragma unroll
;                 for (int n = 0; n < 2; ++n) {
;                     const f32x4 g = acc[ai][0][m][n];
;                     const f32x4 gprev = acc[ai][0][m > 0 ? m - 1 : 0][n], gnext = acc[ai][0][m < 3 ? m + 1 : 3][n];
;                     f32x4 up, dn;
; #pragma unroll
;                     for (int e = 0; e < 4; ++e) {
;                         const float pu = (m > 0 && fr == 15) ? gprev[e] : g[e];
;                         const float pd = (m < 3 && fr == 0) ? gnext[e] : g[e];
;                         up[e] = dpp_ror1(pu); dn[e] = dpp_ror15(pd);
;                     }
;                     if (efirst) up = (f32x4){0.f, 0.f, 0.f, 0.f};
;                     if (elast) dn = (f32x4){0.f, 0.f, 0.f, 0.f};
;                     gc[n] = w0[n] * up + w1[n] * g + w2[n] * dn + bb[n];
;                 }
;                 if (efirst || elast) {
;                     const size_t eo = (size_t)((row >> 6) * 2 + (elast ? 1 : 0)) * DFF + ch0;
; #pragma unroll
;                     for (int n = 0; n < 2; ++n) { *(f32x4*)(EP + eo + 4 * n) = gc[n]; *(f32x4*)(ER + eo + 4 * n) = acc[ai][0][m][n]; *(f32x4*)(EV + eo + 4 * n) = acc[ai][1][m][n]; }
;                 } else {
;                     const f32x4 v0 = acc[ai][1][m][0], v1 = acc[ai][1][m][1];
;                     u32x4 o;
;                     o[0] = pack2(silu_mul(gc[0][0], v0[0]), silu_mul(gc[0][1], v0[1])); o[1] = pack2(silu_mul(gc[0][2], v0[2]), silu_mul(gc[0][3], v0[3]));
;                     o[2] = pack2(silu_mul(gc[1][0], v1[0]), silu_mul(gc[1][1], v1[1])); o[3] = pack2(silu_mul(gc[1][2], v1[2]), silu_mul(gc[1][3], v1[3]));
;                     *(u32x4*)(ACT + (size_t)row * DFF + ch0) = o;
;                 }
	v_mul_f32_e32 v141, 0xbfb8aa3b, v137
	v_mov_b32_dpp v139, v143 row_ror:1 row_mask:0xf bank_mask:0xf
	v_exp_f32_e32 v140, v140
	v_exp_f32_e32 v141, v141
	v_pk_mul_f32 v[138:139], v[98:99], v[138:139]
	v_add_f32_e32 v140, 1.0, v140
	v_mov_b32_dpp v143, v144 row_ror:15 row_mask:0xf bank_mask:0xf
	v_cndmask_b32_e64 v144, v104, v128, s[44:45]
	v_pk_fma_f32 v[138:139], v[122:123], v[102:103], v[138:139]
	v_add_f32_e32 v141, 1.0, v141
	v_mov_b32_dpp v128, v144 row_ror:1 row_mask:0xf bank_mask:0xf
	v_pk_fma_f32 v[138:139], v[110:111], v[142:143], v[138:139]
	v_rcp_f32_e32 v140, v140
	v_mov_b32_dpp v144, v145 row_ror:15 row_mask:0xf bank_mask:0xf
	v_cndmask_b32_e64 v145, v105, v129, s[44:45]
	v_pk_add_f32 v[138:139], v[114:115], v[138:139]
	v_rcp_f32_e32 v141, v141
	v_mov_b32_dpp v129, v145 row_ror:1 row_mask:0xf bank_mask:0xf
	v_mul_f32_e32 v142, 0xbfb8aa3b, v138
	v_mul_f32_e32 v143, 0xbfb8aa3b, v139
	v_pk_mul_f32 v[128:129], v[80:81], v[128:129]
	v_exp_f32_e32 v142, v142
	v_exp_f32_e32 v143, v143
	v_mov_b32_dpp v145, v146 row_ror:15 row_mask:0xf bank_mask:0xf
	v_pk_fma_f32 v[128:129], v[104:105], v[84:85], v[128:129]
	v_cndmask_b32_e64 v146, v106, v130, s[44:45]
	v_pk_fma_f32 v[128:129], v[88:89], v[144:145], v[128:129]
	v_pk_mul_f32 v[124:125], v[124:125], v[136:137]
	v_mov_b32_dpp v130, v146 row_ror:1 row_mask:0xf bank_mask:0xf
	v_pk_add_f32 v[128:129], v[92:93], v[128:129]
	v_pk_mul_f32 v[124:125], v[124:125], v[140:141]
	v_mov_b32_dpp v146, v147 row_ror:15 row_mask:0xf bank_mask:0xf
	v_cndmask_b32_e64 v147, v107, v131, s[44:45]
	v_pk_mul_f32 v[126:127], v[126:127], v[138:139]
	v_add_f32_e32 v138, 1.0, v142
	v_add_f32_e32 v139, 1.0, v143
	v_cvt_pk_bf16_f32 v124, v124, v125
	v_mul_f32_e32 v125, 0xbfb8aa3b, v128
	v_mov_b32_dpp v131, v147 row_ror:1 row_mask:0xf bank_mask:0xf
	v_rcp_f32_e32 v138, v138
	v_rcp_f32_e32 v139, v139
	v_exp_f32_e32 v136, v125
	v_mul_f32_e32 v125, 0xbfb8aa3b, v129
	v_pk_mul_f32 v[130:131], v[82:83], v[130:131]
	v_exp_f32_e32 v137, v125
	v_mov_b32_dpp v147, v148 row_ror:15 row_mask:0xf bank_mask:0xf
	v_pk_fma_f32 v[130:131], v[106:107], v[86:87], v[130:131]
	v_pk_mul_f32 v[126:127], v[126:127], v[138:139]
	v_pk_fma_f32 v[130:131], v[90:91], v[146:147], v[130:131]
	v_cvt_pk_bf16_f32 v125, v126, v127
	v_pk_add_f32 v[130:131], v[94:95], v[130:131]
	v_add_f32_e32 v126, 1.0, v136
	v_add_f32_e32 v127, 1.0, v137
	v_mul_f32_e32 v136, 0xbfb8aa3b, v130
	v_mul_f32_e32 v137, 0xbfb8aa3b, v131
	v_exp_f32_e32 v136, v136
	v_exp_f32_e32 v137, v137
	v_rcp_f32_e32 v126, v126
	v_rcp_f32_e32 v127, v127
	v_pk_mul_f32 v[118:119], v[118:119], v[130:131]
	v_add_f32_e32 v130, 1.0, v136
	v_add_f32_e32 v131, 1.0, v137
	v_rcp_f32_e32 v130, v130
	v_rcp_f32_e32 v131, v131
	v_pk_mul_f32 v[116:117], v[116:117], v[128:129]
	v_add_u32_e32 v148, 32, v193
	v_pk_mul_f32 v[116:117], v[116:117], v[126:127]
	s_nop 0
	v_cvt_pk_bf16_f32 v126, v116, v117
	v_pk_mul_f32 v[116:117], v[118:119], v[130:131]
	v_cndmask_b32_e64 v118, v77, v121, s[44:45]
	v_cvt_pk_bf16_f32 v127, v116, v117
	v_mad_i64_i32 v[116:117], s[28:29], v148, s30, v[134:135]
	v_lshl_add_u64 v[116:117], v[116:117], 0, v[132:133]
	global_store_dwordx4 v[116:117], v[124:127], off
	v_cndmask_b32_e64 v117, v76, v120, s[44:45]
	v_cndmask_b32_e64 v119, v78, v122, s[44:45]
	v_cndmask_b32_e64 v121, v79, v123, s[44:45]
	v_mov_b32_dpp v116, v117 row_ror:1 row_mask:0xf bank_mask:0xf
	s_nop 0
	s_nop 0
	v_mov_b32_dpp v117, v118 row_ror:1 row_mask:0xf bank_mask:0xf
	v_mov_b32_dpp v120, v78 row_ror:15 row_mask:0xf bank_mask:0xf
	v_cndmask_b32_e64 v120, v120, 0, s[44:45]
	v_mov_b32_dpp v118, v119 row_ror:1 row_mask:0xf bank_mask:0xf
	s_nop 0
	v_mov_b32_dpp v124, v76 row_ror:15 row_mask:0xf bank_mask:0xf
	v_mov_b32_dpp v119, v121 row_ror:1 row_mask:0xf bank_mask:0xf
	v_pk_mul_f32 v[118:119], v[98:99], v[118:119]
	v_mov_b32_dpp v125, v77 row_ror:15 row_mask:0xf bank_mask:0xf
	v_mov_b32_dpp v121, v79 row_ror:15 row_mask:0xf bank_mask:0xf
	v_cndmask_b32_e64 v121, v121, 0, s[44:45]
	v_pk_fma_f32 v[118:119], v[78:79], v[102:103], v[118:119]
	v_pk_mul_f32 v[116:117], v[96:97], v[116:117]
	v_pk_fma_f32 v[118:119], v[110:111], v[120:121], v[118:119]
	v_cndmask_b32_e64 v120, v72, v104, s[44:45]
	v_cndmask_b32_e64 v123, v125, 0, s[44:45]
	v_cndmask_b32_e64 v122, v124, 0, s[44:45]
	v_mov_b32_dpp v104, v120 row_ror:1 row_mask:0xf bank_mask:0xf
	v_cndmask_b32_e64 v120, v73, v105, s[44:45]
	v_pk_fma_f32 v[116:117], v[76:77], v[100:101], v[116:117]
	v_cndmask_b32_e64 v121, v75, v107, s[44:45]
	v_mov_b32_dpp v105, v120 row_ror:1 row_mask:0xf bank_mask:0xf
	v_cndmask_b32_e64 v120, v74, v106, s[44:45]
	s_nop 0
	v_pk_fma_f32 v[116:117], v[108:109], v[122:123], v[116:117]
	v_mov_b32_dpp v106, v120 row_ror:1 row_mask:0xf bank_mask:0xf
	v_mov_b32_dpp v107, v121 row_ror:1 row_mask:0xf bank_mask:0xf
	v_mov_b32_dpp v122, v72 row_ror:15 row_mask:0xf bank_mask:0xf
	v_mov_b32_dpp v123, v73 row_ror:15 row_mask:0xf bank_mask:0xf
	v_mov_b32_dpp v120, v74 row_ror:15 row_mask:0xf bank_mask:0xf
	v_mov_b32_dpp v121, v75 row_ror:15 row_mask:0xf bank_mask:0xf
	v_pk_mul_f32 v[104:105], v[80:81], v[104:105]
	v_pk_mul_f32 v[106:107], v[82:83], v[106:107]
	v_cndmask_b32_e64 v121, v121, 0, s[44:45]
	v_cndmask_b32_e64 v120, v120, 0, s[44:45]
	v_cndmask_b32_e64 v123, v123, 0, s[44:45]
	v_cndmask_b32_e64 v122, v122, 0, s[44:45]
	v_pk_fma_f32 v[106:107], v[74:75], v[86:87], v[106:107]
	v_pk_fma_f32 v[104:105], v[72:73], v[84:85], v[104:105]
	v_pk_fma_f32 v[106:107], v[90:91], v[120:121], v[106:107]
	v_pk_fma_f32 v[104:105], v[88:89], v[122:123], v[104:105]
	v_pk_add_f32 v[118:119], v[114:115], v[118:119]
	v_pk_add_f32 v[116:117], v[112:113], v[116:117]
	v_pk_add_f32 v[106:107], v[94:95], v[106:107]
	v_pk_add_f32 v[104:105], v[92:93], v[104:105]
	v_add_u32_e32 v120, 48, v193
	s_and_saveexec_b64 s[28:29], s[42:43]
	s_xor_b64 s[28:29], exec, s[28:29]
	s_cbranch_execz .LBB1_387
; DI unsigned pack2(float a, float b) { f32x2 v = {a, b}; hwbf16x2 r = __builtin_convertvector(v, hwbf16x2); return __builtin_bit_cast(unsigned, r); }
; DI float silu_mul(float g, float v) { return g * v * __builtin_amdgcn_rcpf(1.0f + __builtin_amdgcn_exp2f(-LOG2E * g)); }
;     DI void operator()(const f32x4 (&acc)[2][2][4][2], const Unit& u, int wr, int wc, int fr, int fq) const {
;     ...
;                     const f32x4 v0 = acc[ai][1][m][0], v1 = acc[ai][1][m][1];
;                     u32x4 o;
;                     o[0] = pack2(silu_mul(gc[0][0], v0[0]), silu_mul(gc[0][1], v0[1])); o[1] = pack2(silu_mul(gc[0][2], v0[2]), silu_mul(gc[0][3], v0[3]));
;                     o[2] = pack2(silu_mul(gc[1][0], v1[0]), silu_mul(gc[1][1], v1[1])); o[3] = pack2(silu_mul(gc[1][2], v1[2]), silu_mul(gc[1][3], v1[3]));
;                     *(u32x4*)(ACT + (size_t)row * DFF + ch0) = o;
	v_mul_f32_e32 v121, 0xbfb8aa3b, v116
	v_exp_f32_e32 v121, v121
	v_mul_f32_e32 v122, 0xbfb8aa3b, v117
	v_exp_f32_e32 v122, v122
	v_mul_f32_e32 v124, 0xbfb8aa3b, v119
	v_add_f32_e32 v121, 1.0, v121
	v_exp_f32_e32 v125, v124
	v_add_f32_e32 v123, 1.0, v122
	v_rcp_f32_e32 v122, v121
	v_mul_f32_e32 v121, 0xbfb8aa3b, v118
	v_exp_f32_e32 v121, v121
	v_rcp_f32_e32 v123, v123
	v_pk_mul_f32 v[116:117], v[68:69], v[116:117]
	v_pk_mul_f32 v[118:119], v[70:71], v[118:119]
	v_add_f32_e32 v121, 1.0, v121
	v_rcp_f32_e32 v124, v121
	v_add_f32_e32 v121, 1.0, v125
	v_pk_mul_f32 v[116:117], v[116:117], v[122:123]
	v_rcp_f32_e32 v125, v121
	v_cvt_pk_bf16_f32 v116, v116, v117
	v_mul_f32_e32 v117, 0xbfb8aa3b, v104
	v_exp_f32_e32 v121, v117
	v_mul_f32_e32 v117, 0xbfb8aa3b, v105
	v_exp_f32_e32 v122, v117
	v_pk_mul_f32 v[118:119], v[118:119], v[124:125]
	v_pk_mul_f32 v[104:105], v[64:65], v[104:105]
	v_cvt_pk_bf16_f32 v117, v118, v119
	v_add_f32_e32 v118, 1.0, v121
	v_mul_f32_e32 v121, 0xbfb8aa3b, v106
	v_add_f32_e32 v119, 1.0, v122
	v_exp_f32_e32 v121, v121
	v_mul_f32_e32 v122, 0xbfb8aa3b, v107
	v_exp_f32_e32 v123, v122
	v_rcp_f32_e32 v118, v118
	v_add_f32_e32 v121, 1.0, v121
	v_rcp_f32_e32 v119, v119
	v_rcp_f32_e32 v122, v121
	v_add_f32_e32 v121, 1.0, v123
	v_rcp_f32_e32 v123, v121
	v_pk_mul_f32 v[106:107], v[66:67], v[106:107]
	v_pk_mul_f32 v[104:105], v[104:105], v[118:119]
	s_nop 0
	v_cvt_pk_bf16_f32 v118, v104, v105
	v_pk_mul_f32 v[104:105], v[106:107], v[122:123]
	s_nop 0
	v_cvt_pk_bf16_f32 v119, v104, v105
	v_mov_b64_e32 v[104:105], s[6:7]
	v_mad_i64_i32 v[104:105], s[58:59], v120, s30, v[104:105]
	v_lshl_add_u64 v[104:105], v[184:185], 1, v[104:105]
	global_store_dwordx4 v[104:105], v[116:119], off

; DI unsigned pack2(float a, float b) { f32x2 v = {a, b}; hwbf16x2 r = __builtin_convertvector(v, hwbf16x2); return __builtin_bit_cast(unsigned, r); }
; DI float dpp_ror1(float v)  { return __builtin_bit_cast(float, __builtin_amdgcn_update_dpp(0, __builtin_bit_cast(int, v), 0x121, 0xf, 0xf, false)); }
;     DI void operator()(const f32x4 (&acc)[2][2][4][2], const Unit& u, int wr, int wc, int fr, int fq) const {
;     ...
;             for (int m = 0; m < 4; ++m) {
;                 const bool efirst = (m == 0) && (fr == 0), elast = (m == 3) && (fr == 15);
;                 const int row = row0 + ai * HALF + m * 16;
;                 f32x4 gc[2];
; #pragma unroll
;                 for (int n = 0; n < 2; ++n) {
;                     const f32x4 g = acc[ai][0][m][n];
;                     const f32x4 gprev = acc[ai][0][m > 0 ? m - 1 : 0][n], gnext = acc[ai][0][m < 3 ? m + 1 : 3][n];
;                     f32x4 up, dn;
; #pragma unroll
;                     for (int e = 0; e < 4; ++e) {
;                         const float pu = (m > 0 && fr == 15) ? gprev[e] : g[e];
;                         const float pd = (m < 3 && fr == 0) ? gnext[e] : g[e];
;                         up[e] = dpp_ror1(pu); dn[e] = dpp_ror15(pd);
;                     }
;                     if (efirst) up = (f32x4){0.f, 0.f, 0.f, 0.f};
;                     if (elast) dn = (f32x4){0.f, 0.f, 0.f, 0.f};
;                     gc[n] = w0[n] * up + w1[n] * g + w2[n] * dn + bb[n];
;                 }
;                 if (efirst || elast) {
;                     const size_t eo = (size_t)((row >> 6) * 2 + (elast ? 1 : 0)) * DFF + ch0;
; #pragma unroll
;                     for (int n = 0; n < 2; ++n) { *(f32x4*)(EP + eo + 4 * n) = gc[n]; *(f32x4*)(ER + eo + 4 * n) = acc[ai][0][m][n]; *(f32x4*)(EV + eo + 4 * n) = acc[ai][1][m][n]; }
;                 } else {
;                     const f32x4 v0 = acc[ai][1][m][0], v1 = acc[ai][1][m][1];
;                     u32x4 o;
;                     o[0] = pack2(silu_mul(gc[0][0], v0[0]), silu_mul(gc[0][1], v0[1])); o[1] = pack2(silu_mul(gc[0][2], v0[2]), silu_mul(gc[0][3], v0[3]));
;                     o[2] = pack2(silu_mul(gc[1][0], v1[0]), silu_mul(gc[1][1], v1[1])); o[3] = pack2(silu_mul(gc[1][2], v1[2]), silu_mul(gc[1][3], v1[3]));
;                     *(u32x4*)(ACT + (size_t)row * DFF + ch0) = o;
;                 }
.LBB1_389:
	s_or_b64 exec, exec, s[28:29]
	s_nop 0
	v_cndmask_b32_e32 v65, v60, v40, vcc
	v_cndmask_b32_e32 v66, v61, v41, vcc
	v_cndmask_b32_e32 v67, v62, v42, vcc
	v_mov_b32_dpp v64, v65 row_ror:15 row_mask:0xf bank_mask:0xf
	s_nop 0
	s_nop 0
	v_mov_b32_dpp v65, v66 row_ror:15 row_mask:0xf bank_mask:0xf
	s_nop 0
	v_mov_b32_dpp v68, v62 row_ror:1 row_mask:0xf bank_mask:0xf
	v_mov_b32_dpp v66, v67 row_ror:15 row_mask:0xf bank_mask:0xf
	v_cndmask_b32_e32 v69, v63, v43, vcc
	v_mov_b32_dpp v73, v63 row_ror:1 row_mask:0xf bank_mask:0xf
	v_mov_b32_dpp v70, v60 row_ror:1 row_mask:0xf bank_mask:0xf
	v_mov_b32_dpp v71, v61 row_ror:1 row_mask:0xf bank_mask:0xf
	v_mov_b32_dpp v67, v69 row_ror:15 row_mask:0xf bank_mask:0xf
	v_cndmask_b32_e64 v69, v73, 0, vcc
	v_cndmask_b32_e64 v68, v68, 0, vcc
	v_cndmask_b32_e64 v71, v71, 0, vcc
	v_cndmask_b32_e64 v70, v70, 0, vcc
	v_pk_mul_f32 v[68:69], v[98:99], v[68:69]
	v_pk_mul_f32 v[70:71], v[96:97], v[70:71]
	v_pk_fma_f32 v[68:69], v[62:63], v[102:103], v[68:69]
	v_pk_fma_f32 v[70:71], v[60:61], v[100:101], v[70:71]
	v_pk_fma_f32 v[66:67], v[110:111], v[66:67], v[68:69]
	v_cndmask_b32_e32 v69, v48, v32, vcc
	v_pk_fma_f32 v[64:65], v[108:109], v[64:65], v[70:71]
	v_cndmask_b32_e32 v70, v49, v33, vcc
	v_mov_b32_dpp v68, v69 row_ror:15 row_mask:0xf bank_mask:0xf
	s_nop 0
	s_nop 0
	v_mov_b32_dpp v69, v70 row_ror:15 row_mask:0xf bank_mask:0xf
	v_cndmask_b32_e32 v71, v50, v34, vcc
	v_mov_b32_dpp v73, v48 row_ror:1 row_mask:0xf bank_mask:0xf
	v_mov_b32_dpp v76, v49 row_ror:1 row_mask:0xf bank_mask:0xf
	v_mov_b32_dpp v74, v50 row_ror:1 row_mask:0xf bank_mask:0xf
	v_mov_b32_dpp v70, v71 row_ror:15 row_mask:0xf bank_mask:0xf
	v_cndmask_b32_e32 v75, v51, v35, vcc
	v_mov_b32_dpp v77, v51 row_ror:1 row_mask:0xf bank_mask:0xf
	v_cndmask_b32_e64 v74, v74, 0, vcc
	v_add_u32_e32 v72, 0x80, v193
	v_mov_b32_dpp v71, v75 row_ror:15 row_mask:0xf bank_mask:0xf
	v_cndmask_b32_e64 v75, v77, 0, vcc
	v_cndmask_b32_e64 v77, v76, 0, vcc
	v_cndmask_b32_e64 v76, v73, 0, vcc
	v_pk_mul_f32 v[76:77], v[80:81], v[76:77]
	v_pk_mul_f32 v[74:75], v[82:83], v[74:75]
	v_pk_fma_f32 v[76:77], v[48:49], v[84:85], v[76:77]
	v_pk_fma_f32 v[74:75], v[50:51], v[86:87], v[74:75]
	v_pk_fma_f32 v[68:69], v[88:89], v[68:69], v[76:77]
	v_pk_fma_f32 v[70:71], v[90:91], v[70:71], v[74:75]
	v_pk_add_f32 v[66:67], v[114:115], v[66:67]
	v_pk_add_f32 v[64:65], v[112:113], v[64:65]
	v_pk_add_f32 v[70:71], v[94:95], v[70:71]
	v_pk_add_f32 v[68:69], v[92:93], v[68:69]
	s_and_saveexec_b64 s[28:29], s[46:47]
	s_xor_b64 s[28:29], exec, s[28:29]
	s_cbranch_execz .LBB1_391
	v_mul_f32_e32 v73, 0xbfb8aa3b, v64
	v_exp_f32_e32 v73, v73
	v_mul_f32_e32 v74, 0xbfb8aa3b, v65
	v_exp_f32_e32 v74, v74
	v_mul_f32_e32 v76, 0xbfb8aa3b, v67
	v_add_f32_e32 v73, 1.0, v73
	v_exp_f32_e32 v77, v76
	v_add_f32_e32 v75, 1.0, v74
	v_rcp_f32_e32 v74, v73
	v_mul_f32_e32 v73, 0xbfb8aa3b, v66
	v_exp_f32_e32 v73, v73
	v_rcp_f32_e32 v75, v75
	v_pk_mul_f32 v[64:65], v[56:57], v[64:65]
	v_pk_mul_f32 v[66:67], v[58:59], v[66:67]
	v_add_f32_e32 v73, 1.0, v73
	v_rcp_f32_e32 v76, v73
	v_add_f32_e32 v73, 1.0, v77
	v_pk_mul_f32 v[64:65], v[64:65], v[74:75]
	v_rcp_f32_e32 v77, v73
	v_cvt_pk_bf16_f32 v64, v64, v65
	v_mul_f32_e32 v65, 0xbfb8aa3b, v68
	v_exp_f32_e32 v73, v65
	v_mul_f32_e32 v65, 0xbfb8aa3b, v69
	v_exp_f32_e32 v74, v65
	v_pk_mul_f32 v[66:67], v[66:67], v[76:77]
	v_pk_mul_f32 v[68:69], v[52:53], v[68:69]
	v_cvt_pk_bf16_f32 v65, v66, v67
	v_add_f32_e32 v66, 1.0, v73
	v_mul_f32_e32 v73, 0xbfb8aa3b, v70
	v_add_f32_e32 v67, 1.0, v74
	v_exp_f32_e32 v73, v73
	v_mul_f32_e32 v74, 0xbfb8aa3b, v71
	v_exp_f32_e32 v75, v74
	v_rcp_f32_e32 v66, v66
	v_add_f32_e32 v73, 1.0, v73
	v_rcp_f32_e32 v74, v73
	v_add_f32_e32 v73, 1.0, v75
	v_rcp_f32_e32 v67, v67
	v_rcp_f32_e32 v75, v73
	v_pk_mul_f32 v[70:71], v[54:55], v[70:71]
	v_pk_mul_f32 v[66:67], v[68:69], v[66:67]
	v_pk_mul_f32 v[68:69], v[70:71], v[74:75]
	v_cvt_pk_bf16_f32 v66, v66, v67
	v_cvt_pk_bf16_f32 v67, v68, v69
	v_mov_b64_e32 v[68:69], s[6:7]
	v_mad_i64_i32 v[68:69], s[46:47], v72, s30, v[68:69]
	v_lshl_add_u64 v[68:69], v[184:185], 1, v[68:69]
	global_store_dwordx4 v[68:69], v[64:67], off

; DI unsigned pack2(float a, float b) { f32x2 v = {a, b}; hwbf16x2 r = __builtin_convertvector(v, hwbf16x2); return __builtin_bit_cast(unsigned, r); }
; DI float dpp_ror1(float v)  { return __builtin_bit_cast(float, __builtin_amdgcn_update_dpp(0, __builtin_bit_cast(int, v), 0x121, 0xf, 0xf, false)); }
;     DI void operator()(const f32x4 (&acc)[2][2][4][2], const Unit& u, int wr, int wc, int fr, int fq) const {
;     ...
;             for (int m = 0; m < 4; ++m) {
;                 const bool efirst = (m == 0) && (fr == 0), elast = (m == 3) && (fr == 15);
;                 const int row = row0 + ai * HALF + m * 16;
;                 f32x4 gc[2];
; #pragma unroll
;                 for (int n = 0; n < 2; ++n) {
;                     const f32x4 g = acc[ai][0][m][n];
;                     const f32x4 gprev = acc[ai][0][m > 0 ? m - 1 : 0][n], gnext = acc[ai][0][m < 3 ? m + 1 : 3][n];
;                     f32x4 up, dn;
; #pragma unroll
;                     for (int e = 0; e < 4; ++e) {
;                         const float pu = (m > 0 && fr == 15) ? gprev[e] : g[e];
;                         const float pd = (m < 3 && fr == 0) ? gnext[e] : g[e];
;                         up[e] = dpp_ror1(pu); dn[e] = dpp_ror15(pd);
;                     }
;                     if (efirst) up = (f32x4){0.f, 0.f, 0.f, 0.f};
;                     if (elast) dn = (f32x4){0.f, 0.f, 0.f, 0.f};
;                     gc[n] = w0[n] * up + w1[n] * g + w2[n] * dn + bb[n];
;                 }
;                 if (efirst || elast) {
;                     const size_t eo = (size_t)((row >> 6) * 2 + (elast ? 1 : 0)) * DFF + ch0;
; #pragma unroll
;                     for (int n = 0; n < 2; ++n) { *(f32x4*)(EP + eo + 4 * n) = gc[n]; *(f32x4*)(ER + eo + 4 * n) = acc[ai][0][m][n]; *(f32x4*)(EV + eo + 4 * n) = acc[ai][1][m][n]; }
;                 } else {
;                     const f32x4 v0 = acc[ai][1][m][0], v1 = acc[ai][1][m][1];
;                     u32x4 o;
;                     o[0] = pack2(silu_mul(gc[0][0], v0[0]), silu_mul(gc[0][1], v0[1])); o[1] = pack2(silu_mul(gc[0][2], v0[2]), silu_mul(gc[0][3], v0[3]));
;                     o[2] = pack2(silu_mul(gc[1][0], v1[0]), silu_mul(gc[1][1], v1[1])); o[3] = pack2(silu_mul(gc[1][2], v1[2]), silu_mul(gc[1][3], v1[3]));
;                     *(u32x4*)(ACT + (size_t)row * DFF + ch0) = o;
.LBB1_393:
	s_or_b64 exec, exec, s[28:29]
	s_nop 0
	v_cndmask_b32_e64 v53, v40, v60, s[44:45]
	v_cndmask_b32_e32 v55, v40, v24, vcc
	s_nop 0
	v_cndmask_b32_e32 v56, v41, v25, vcc
	v_mov_b32_dpp v52, v53 row_ror:1 row_mask:0xf bank_mask:0xf
	v_mov_b32_dpp v54, v55 row_ror:15 row_mask:0xf bank_mask:0xf
	v_cndmask_b32_e64 v55, v41, v61, s[44:45]
	v_cndmask_b32_e64 v57, v42, v62, s[44:45]
	v_cndmask_b32_e32 v59, v42, v26, vcc
	v_mov_b32_dpp v53, v55 row_ror:1 row_mask:0xf bank_mask:0xf
	s_nop 0
	v_pk_mul_f32 v[52:53], v[96:97], v[52:53]
	v_mov_b32_dpp v55, v56 row_ror:15 row_mask:0xf bank_mask:0xf
	v_mov_b32_dpp v58, v59 row_ror:15 row_mask:0xf bank_mask:0xf
	v_cndmask_b32_e64 v59, v43, v63, s[44:45]
	v_mov_b32_dpp v56, v57 row_ror:1 row_mask:0xf bank_mask:0xf
	v_pk_fma_f32 v[52:53], v[40:41], v[100:101], v[52:53]
	v_cndmask_b32_e32 v60, v43, v27, vcc
	v_mov_b32_dpp v57, v59 row_ror:1 row_mask:0xf bank_mask:0xf
	v_pk_fma_f32 v[52:53], v[108:109], v[54:55], v[52:53]
	v_pk_mul_f32 v[56:57], v[98:99], v[56:57]
	v_pk_add_f32 v[52:53], v[112:113], v[52:53]
	v_mov_b32_dpp v59, v60 row_ror:15 row_mask:0xf bank_mask:0xf
	v_pk_fma_f32 v[56:57], v[42:43], v[102:103], v[56:57]
	v_mul_f32_e32 v54, 0xbfb8aa3b, v52
	v_pk_fma_f32 v[56:57], v[110:111], v[58:59], v[56:57]
	v_exp_f32_e32 v58, v54
	v_mul_f32_e32 v54, 0xbfb8aa3b, v53
	v_exp_f32_e32 v59, v54
	v_cndmask_b32_e64 v60, v32, v48, s[44:45]
	v_cndmask_b32_e32 v61, v32, v16, vcc
	v_pk_add_f32 v[54:55], v[114:115], v[56:57]
	v_mov_b32_dpp v48, v60 row_ror:1 row_mask:0xf bank_mask:0xf
	v_add_f32_e32 v56, 1.0, v58
	v_add_f32_e32 v57, 1.0, v59
	v_mov_b32_dpp v60, v61 row_ror:15 row_mask:0xf bank_mask:0xf
	v_cndmask_b32_e64 v61, v33, v49, s[44:45]
	v_rcp_f32_e32 v56, v56
	v_rcp_f32_e32 v57, v57
	v_mov_b32_dpp v49, v61 row_ror:1 row_mask:0xf bank_mask:0xf
	v_mul_f32_e32 v58, 0xbfb8aa3b, v54
	v_mul_f32_e32 v59, 0xbfb8aa3b, v55
	v_cndmask_b32_e32 v62, v33, v17, vcc
	v_pk_mul_f32 v[48:49], v[80:81], v[48:49]
	v_exp_f32_e32 v58, v58
	v_exp_f32_e32 v59, v59
	v_mov_b32_dpp v61, v62 row_ror:15 row_mask:0xf bank_mask:0xf
	v_pk_fma_f32 v[48:49], v[32:33], v[84:85], v[48:49]
	v_cndmask_b32_e64 v62, v34, v50, s[44:45]
	v_pk_fma_f32 v[48:49], v[88:89], v[60:61], v[48:49]
	v_pk_mul_f32 v[44:45], v[44:45], v[52:53]
	v_cndmask_b32_e32 v63, v34, v18, vcc
	v_mov_b32_dpp v50, v62 row_ror:1 row_mask:0xf bank_mask:0xf
	v_pk_add_f32 v[48:49], v[92:93], v[48:49]
	v_pk_mul_f32 v[44:45], v[44:45], v[56:57]
	v_mov_b32_dpp v62, v63 row_ror:15 row_mask:0xf bank_mask:0xf
	v_cndmask_b32_e64 v63, v35, v51, s[44:45]
	v_pk_mul_f32 v[46:47], v[46:47], v[54:55]
	v_add_f32_e32 v54, 1.0, v58
	v_add_f32_e32 v55, 1.0, v59
	v_cvt_pk_bf16_f32 v44, v44, v45
	v_mul_f32_e32 v45, 0xbfb8aa3b, v48
	v_mov_b32_dpp v51, v63 row_ror:1 row_mask:0xf bank_mask:0xf
	v_rcp_f32_e32 v54, v54
	v_rcp_f32_e32 v55, v55
	v_exp_f32_e32 v52, v45
	v_mul_f32_e32 v45, 0xbfb8aa3b, v49
	v_cndmask_b32_e32 v64, v35, v19, vcc
	v_pk_mul_f32 v[50:51], v[82:83], v[50:51]
	v_exp_f32_e32 v53, v45
	v_mov_b32_dpp v63, v64 row_ror:15 row_mask:0xf bank_mask:0xf
	v_pk_fma_f32 v[50:51], v[34:35], v[86:87], v[50:51]
	v_pk_mul_f32 v[46:47], v[46:47], v[54:55]
	v_pk_fma_f32 v[50:51], v[90:91], v[62:63], v[50:51]
	v_cvt_pk_bf16_f32 v45, v46, v47
	v_pk_add_f32 v[50:51], v[94:95], v[50:51]
	v_add_f32_e32 v46, 1.0, v52
	v_add_f32_e32 v47, 1.0, v53
	v_mul_f32_e32 v52, 0xbfb8aa3b, v50
	v_mul_f32_e32 v53, 0xbfb8aa3b, v51
	v_exp_f32_e32 v52, v52
	v_exp_f32_e32 v53, v53
	v_rcp_f32_e32 v46, v46
	v_rcp_f32_e32 v47, v47
	v_pk_mul_f32 v[38:39], v[38:39], v[50:51]
	v_add_f32_e32 v50, 1.0, v52
	v_add_f32_e32 v51, 1.0, v53
	v_rcp_f32_e32 v50, v50
	v_rcp_f32_e32 v51, v51
	v_pk_mul_f32 v[36:37], v[36:37], v[48:49]
	v_add_u32_e32 v64, 0x90, v193
	v_pk_mul_f32 v[36:37], v[36:37], v[46:47]
	v_cndmask_b32_e64 v41, v25, v41, s[44:45]
	v_cvt_pk_bf16_f32 v46, v36, v37
	v_pk_mul_f32 v[36:37], v[38:39], v[50:51]
	v_cndmask_b32_e32 v48, v17, v9, vcc
	v_cvt_pk_bf16_f32 v47, v36, v37
	v_mov_b64_e32 v[36:37], s[6:7]
	v_mad_i64_i32 v[38:39], s[28:29], v64, s30, v[36:37]
	v_lshl_add_u64 v[38:39], v[38:39], 0, v[132:133]
	global_store_dwordx4 v[38:39], v[44:47], off
	v_cndmask_b32_e64 v39, v24, v40, s[44:45]
	s_nop 0
	v_cndmask_b32_e32 v44, v24, v12, vcc
	s_nop 0
	v_mov_b32_dpp v38, v39 row_ror:1 row_mask:0xf bank_mask:0xf
	s_nop 0
	v_mov_b32_dpp v40, v44 row_ror:15 row_mask:0xf bank_mask:0xf
	v_cndmask_b32_e32 v44, v25, v13, vcc
	v_mov_b32_dpp v39, v41 row_ror:1 row_mask:0xf bank_mask:0xf
	v_cndmask_b32_e32 v45, v26, v14, vcc
	v_pk_mul_f32 v[38:39], v[96:97], v[38:39]
	v_mov_b32_dpp v41, v44 row_ror:15 row_mask:0xf bank_mask:0xf
	v_cndmask_b32_e64 v44, v26, v42, s[44:45]
	v_pk_fma_f32 v[38:39], v[24:25], v[100:101], v[38:39]
	v_cndmask_b32_e32 v46, v27, v15, vcc
	v_mov_b32_dpp v42, v44 row_ror:1 row_mask:0xf bank_mask:0xf
	v_pk_fma_f32 v[38:39], v[108:109], v[40:41], v[38:39]
	v_cndmask_b32_e32 v47, v16, v8, vcc
	v_mov_b32_dpp v44, v45 row_ror:15 row_mask:0xf bank_mask:0xf
	v_cndmask_b32_e64 v45, v27, v43, s[44:45]
	v_pk_add_f32 v[38:39], v[112:113], v[38:39]
	v_cndmask_b32_e32 v49, v18, v10, vcc
	v_mov_b32_dpp v43, v45 row_ror:1 row_mask:0xf bank_mask:0xf
	v_pk_mul_f32 v[42:43], v[98:99], v[42:43]
	v_mul_f32_e32 v40, 0xbfb8aa3b, v38
	v_mov_b32_dpp v45, v46 row_ror:15 row_mask:0xf bank_mask:0xf
	v_pk_fma_f32 v[42:43], v[26:27], v[102:103], v[42:43]
	v_cndmask_b32_e64 v46, v16, v32, s[44:45]
	v_pk_fma_f32 v[42:43], v[110:111], v[44:45], v[42:43]
	v_exp_f32_e32 v44, v40
	v_mul_f32_e32 v40, 0xbfb8aa3b, v39
	v_exp_f32_e32 v45, v40
	v_pk_add_f32 v[40:41], v[114:115], v[42:43]
	v_add_f32_e32 v42, 1.0, v44
; DI unsigned pack2(float a, float b) { f32x2 v = {a, b}; hwbf16x2 r = __builtin_convertvector(v, hwbf16x2); return __builtin_bit_cast(unsigned, r); }
; DI float dpp_ror1(float v)  { return __builtin_bit_cast(float, __builtin_amdgcn_update_dpp(0, __builtin_bit_cast(int, v), 0x121, 0xf, 0xf, false)); }
;     DI void operator()(const f32x4 (&acc)[2][2][4][2], const Unit& u, int wr, int wc, int fr, int fq) const {
;     ...
;             for (int m = 0; m < 4; ++m) {
;                 const bool efirst = (m == 0) && (fr == 0), elast = (m == 3) && (fr == 15);
;                 const int row = row0 + ai * HALF + m * 16;
;                 f32x4 gc[2];
; #pragma unroll
;                 for (int n = 0; n < 2; ++n) {
;                     const f32x4 g = acc[ai][0][m][n];
;                     const f32x4 gprev = acc[ai][0][m > 0 ? m - 1 : 0][n], gnext = acc[ai][0][m < 3 ? m + 1 : 3][n];
;                     f32x4 up, dn;
; #pragma unroll
;                     for (int e = 0; e < 4; ++e) {
;                         const float pu = (m > 0 && fr == 15) ? gprev[e] : g[e];
;                         const float pd = (m < 3 && fr == 0) ? gnext[e] : g[e];
;                         up[e] = dpp_ror1(pu); dn[e] = dpp_ror15(pd);
;                     }
;                     if (efirst) up = (f32x4){0.f, 0.f, 0.f, 0.f};
;                     if (elast) dn = (f32x4){0.f, 0.f, 0.f, 0.f};
;                     gc[n] = w0[n] * up + w1[n] * g + w2[n] * dn + bb[n];
;                 }
;                 if (efirst || elast) {
;                     const size_t eo = (size_t)((row >> 6) * 2 + (elast ? 1 : 0)) * DFF + ch0;
; #pragma unroll
;                     for (int n = 0; n < 2; ++n) { *(f32x4*)(EP + eo + 4 * n) = gc[n]; *(f32x4*)(ER + eo + 4 * n) = acc[ai][0][m][n]; *(f32x4*)(EV + eo + 4 * n) = acc[ai][1][m][n]; }
;                 } else {
;                     const f32x4 v0 = acc[ai][1][m][0], v1 = acc[ai][1][m][1];
;                     u32x4 o;
;                     o[0] = pack2(silu_mul(gc[0][0], v0[0]), silu_mul(gc[0][1], v0[1])); o[1] = pack2(silu_mul(gc[0][2], v0[2]), silu_mul(gc[0][3], v0[3]));
;                     o[2] = pack2(silu_mul(gc[1][0], v1[0]), silu_mul(gc[1][1], v1[1])); o[3] = pack2(silu_mul(gc[1][2], v1[2]), silu_mul(gc[1][3], v1[3]));
;                     *(u32x4*)(ACT + (size_t)row * DFF + ch0) = o;
;                 }
	v_mov_b32_dpp v32, v46 row_ror:1 row_mask:0xf bank_mask:0xf
	v_add_f32_e32 v43, 1.0, v45
	v_rcp_f32_e32 v42, v42
	v_mov_b32_dpp v46, v47 row_ror:15 row_mask:0xf bank_mask:0xf
	v_cndmask_b32_e64 v47, v17, v33, s[44:45]
	v_rcp_f32_e32 v43, v43
	v_mul_f32_e32 v44, 0xbfb8aa3b, v40
	v_mov_b32_dpp v33, v47 row_ror:1 row_mask:0xf bank_mask:0xf
	v_mul_f32_e32 v45, 0xbfb8aa3b, v41
	v_pk_mul_f32 v[32:33], v[80:81], v[32:33]
	v_exp_f32_e32 v44, v44
	v_exp_f32_e32 v45, v45
	v_mov_b32_dpp v47, v48 row_ror:15 row_mask:0xf bank_mask:0xf
	v_pk_fma_f32 v[32:33], v[16:17], v[84:85], v[32:33]
	v_cndmask_b32_e64 v48, v18, v34, s[44:45]
	v_pk_fma_f32 v[32:33], v[88:89], v[46:47], v[32:33]
	v_pk_mul_f32 v[28:29], v[28:29], v[38:39]
	v_mov_b32_dpp v34, v48 row_ror:1 row_mask:0xf bank_mask:0xf
	v_pk_add_f32 v[32:33], v[92:93], v[32:33]
	v_pk_mul_f32 v[28:29], v[28:29], v[42:43]
	v_mov_b32_dpp v48, v49 row_ror:15 row_mask:0xf bank_mask:0xf
	v_cndmask_b32_e64 v49, v19, v35, s[44:45]
	v_pk_mul_f32 v[30:31], v[30:31], v[40:41]
	v_add_f32_e32 v40, 1.0, v44
	v_add_f32_e32 v41, 1.0, v45
	v_cvt_pk_bf16_f32 v28, v28, v29
	v_mul_f32_e32 v29, 0xbfb8aa3b, v32
	v_mov_b32_dpp v35, v49 row_ror:1 row_mask:0xf bank_mask:0xf
	v_rcp_f32_e32 v40, v40
	v_rcp_f32_e32 v41, v41
	v_exp_f32_e32 v38, v29
	v_mul_f32_e32 v29, 0xbfb8aa3b, v33
	v_cndmask_b32_e32 v50, v19, v11, vcc
	v_pk_mul_f32 v[34:35], v[82:83], v[34:35]
	v_exp_f32_e32 v39, v29
	v_mov_b32_dpp v49, v50 row_ror:15 row_mask:0xf bank_mask:0xf
	v_pk_fma_f32 v[34:35], v[18:19], v[86:87], v[34:35]
	v_pk_mul_f32 v[30:31], v[30:31], v[40:41]
	v_pk_fma_f32 v[34:35], v[90:91], v[48:49], v[34:35]
	v_cvt_pk_bf16_f32 v29, v30, v31
	v_pk_add_f32 v[34:35], v[94:95], v[34:35]
	v_add_f32_e32 v30, 1.0, v38
	v_add_f32_e32 v31, 1.0, v39
	v_mul_f32_e32 v38, 0xbfb8aa3b, v34
	v_mul_f32_e32 v39, 0xbfb8aa3b, v35
	v_exp_f32_e32 v38, v38
	v_exp_f32_e32 v39, v39
	v_rcp_f32_e32 v30, v30
	v_rcp_f32_e32 v31, v31
	v_pk_mul_f32 v[22:23], v[22:23], v[34:35]
	v_add_f32_e32 v34, 1.0, v38
	v_add_f32_e32 v35, 1.0, v39
	v_rcp_f32_e32 v34, v34
	v_rcp_f32_e32 v35, v35
	v_pk_mul_f32 v[20:21], v[20:21], v[32:33]
	v_add_u32_e32 v50, 0xa0, v193
	v_pk_mul_f32 v[20:21], v[20:21], v[30:31]
	s_nop 0
	v_cvt_pk_bf16_f32 v30, v20, v21
	v_pk_mul_f32 v[20:21], v[22:23], v[34:35]
	v_cndmask_b32_e64 v22, v13, v25, s[44:45]
	v_cvt_pk_bf16_f32 v31, v20, v21
	v_mad_i64_i32 v[20:21], s[28:29], v50, s30, v[36:37]
	v_lshl_add_u64 v[20:21], v[20:21], 0, v[132:133]
	global_store_dwordx4 v[20:21], v[28:31], off
	v_cndmask_b32_e64 v21, v12, v24, s[44:45]
	v_cndmask_b32_e64 v23, v14, v26, s[44:45]
	v_cndmask_b32_e64 v25, v15, v27, s[44:45]
	v_mov_b32_dpp v20, v21 row_ror:1 row_mask:0xf bank_mask:0xf
	s_nop 0
	s_nop 0
	v_mov_b32_dpp v21, v22 row_ror:1 row_mask:0xf bank_mask:0xf
	v_mov_b32_dpp v24, v14 row_ror:15 row_mask:0xf bank_mask:0xf
	v_cndmask_b32_e64 v24, v24, 0, s[44:45]
	v_mov_b32_dpp v22, v23 row_ror:1 row_mask:0xf bank_mask:0xf
	s_nop 0
	v_mov_b32_dpp v28, v12 row_ror:15 row_mask:0xf bank_mask:0xf
	v_mov_b32_dpp v23, v25 row_ror:1 row_mask:0xf bank_mask:0xf
	v_pk_mul_f32 v[22:23], v[98:99], v[22:23]
	v_mov_b32_dpp v29, v13 row_ror:15 row_mask:0xf bank_mask:0xf
	v_mov_b32_dpp v25, v15 row_ror:15 row_mask:0xf bank_mask:0xf
	v_cndmask_b32_e64 v25, v25, 0, s[44:45]
	v_pk_fma_f32 v[22:23], v[14:15], v[102:103], v[22:23]
	v_pk_mul_f32 v[20:21], v[96:97], v[20:21]
	v_pk_fma_f32 v[22:23], v[110:111], v[24:25], v[22:23]
	v_cndmask_b32_e64 v24, v8, v16, s[44:45]
	v_cndmask_b32_e64 v27, v29, 0, s[44:45]
	v_cndmask_b32_e64 v26, v28, 0, s[44:45]
	v_mov_b32_dpp v16, v24 row_ror:1 row_mask:0xf bank_mask:0xf
	v_cndmask_b32_e64 v24, v9, v17, s[44:45]
	v_pk_fma_f32 v[20:21], v[12:13], v[100:101], v[20:21]
	v_cndmask_b32_e64 v25, v11, v19, s[44:45]
	v_mov_b32_dpp v17, v24 row_ror:1 row_mask:0xf bank_mask:0xf
	v_cndmask_b32_e64 v24, v10, v18, s[44:45]
	s_nop 0
	v_pk_fma_f32 v[20:21], v[108:109], v[26:27], v[20:21]
	v_mov_b32_dpp v18, v24 row_ror:1 row_mask:0xf bank_mask:0xf
	v_mov_b32_dpp v19, v25 row_ror:1 row_mask:0xf bank_mask:0xf
	v_mov_b32_dpp v26, v8 row_ror:15 row_mask:0xf bank_mask:0xf
	v_mov_b32_dpp v27, v9 row_ror:15 row_mask:0xf bank_mask:0xf
	v_mov_b32_dpp v24, v10 row_ror:15 row_mask:0xf bank_mask:0xf
	v_mov_b32_dpp v25, v11 row_ror:15 row_mask:0xf bank_mask:0xf
	v_pk_mul_f32 v[16:17], v[80:81], v[16:17]
	v_pk_mul_f32 v[18:19], v[82:83], v[18:19]
	v_cndmask_b32_e64 v25, v25, 0, s[44:45]
	v_cndmask_b32_e64 v24, v24, 0, s[44:45]
	v_cndmask_b32_e64 v27, v27, 0, s[44:45]
	v_cndmask_b32_e64 v26, v26, 0, s[44:45]
	v_pk_fma_f32 v[18:19], v[10:11], v[86:87], v[18:19]
	v_pk_fma_f32 v[16:17], v[8:9], v[84:85], v[16:17]
	v_pk_fma_f32 v[18:19], v[90:91], v[24:25], v[18:19]
	v_pk_fma_f32 v[16:17], v[88:89], v[26:27], v[16:17]
	v_pk_add_f32 v[22:23], v[114:115], v[22:23]
	v_pk_add_f32 v[20:21], v[112:113], v[20:21]
	v_pk_add_f32 v[18:19], v[94:95], v[18:19]
	v_pk_add_f32 v[16:17], v[92:93], v[16:17]
	v_add_u32_e32 v24, 0xb0, v193
	s_and_saveexec_b64 s[28:29], s[42:43]
	s_xor_b64 s[28:29], exec, s[28:29]
	s_cbranch_execz .LBB1_395
	v_mul_f32_e32 v25, 0xbfb8aa3b, v20
	v_exp_f32_e32 v25, v25
	v_mul_f32_e32 v26, 0xbfb8aa3b, v21
	v_exp_f32_e32 v26, v26
	v_mul_f32_e32 v28, 0xbfb8aa3b, v23
	v_add_f32_e32 v25, 1.0, v25
	v_exp_f32_e32 v29, v28
	v_add_f32_e32 v27, 1.0, v26
	v_rcp_f32_e32 v26, v25
	v_mul_f32_e32 v25, 0xbfb8aa3b, v22
	v_exp_f32_e32 v25, v25
	v_rcp_f32_e32 v27, v27
	v_pk_mul_f32 v[20:21], v[4:5], v[20:21]
	v_pk_mul_f32 v[22:23], v[6:7], v[22:23]
	v_add_f32_e32 v25, 1.0, v25
	v_rcp_f32_e32 v28, v25
	v_add_f32_e32 v25, 1.0, v29
	v_pk_mul_f32 v[20:21], v[20:21], v[26:27]
	v_rcp_f32_e32 v29, v25
	v_cvt_pk_bf16_f32 v20, v20, v21
	v_mul_f32_e32 v21, 0xbfb8aa3b, v16
	v_exp_f32_e32 v25, v21
	v_mul_f32_e32 v21, 0xbfb8aa3b, v17
	v_exp_f32_e32 v26, v21
	v_pk_mul_f32 v[22:23], v[22:23], v[28:29]
	v_pk_mul_f32 v[16:17], v[0:1], v[16:17]
	v_cvt_pk_bf16_f32 v21, v22, v23
	v_add_f32_e32 v22, 1.0, v25
	v_mul_f32_e32 v25, 0xbfb8aa3b, v18
	v_add_f32_e32 v23, 1.0, v26
	v_exp_f32_e32 v25, v25
	v_mul_f32_e32 v26, 0xbfb8aa3b, v19
	v_exp_f32_e32 v27, v26
	v_rcp_f32_e32 v22, v22
	v_add_f32_e32 v25, 1.0, v25
	v_rcp_f32_e32 v23, v23
	v_rcp_f32_e32 v26, v25
	v_add_f32_e32 v25, 1.0, v27
	v_rcp_f32_e32 v27, v25
	v_pk_mul_f32 v[18:19], v[2:3], v[18:19]
	v_pk_mul_f32 v[16:17], v[16:17], v[22:23]
	s_nop 0
	v_cvt_pk_bf16_f32 v22, v16, v17
	v_pk_mul_f32 v[16:17], v[18:19], v[26:27]
	s_nop 0
	v_cvt_pk_bf16_f32 v23, v16, v17
	v_mov_b64_e32 v[16:17], s[6:7]
	v_mad_i64_i32 v[16:17], s[42:43], v24, s30, v[16:17]
	v_lshl_add_u64 v[16:17], v[184:185], 1, v[16:17]
	global_store_dwordx4 v[16:17], v[20:23], off

; #define PG8_STAGE(bufoff, gbase, voff) do { _Pragma("unroll") for (int _i = 0; _i < 2; ++_i) \
;         __builtin_amdgcn_global_load_lds((const unsigned*)((const char*)(gbase) + (voff)[_i]), (LAS unsigned*)(lds + (bufoff) + ldsw + _i * 8192), 16, 0, 0); } while (0)
; #define PG8_LDA(dst, b, h) do { _Pragma("unroll") for (int m = 0; m < 4; ++m) _Pragma("unroll") for (int k = 0; k < 2; ++k) dst[m][k] = *(const LAS bf16x8*)(lds + PG8_SA(b, h) + aoff + m * 2048 + k * 1024); } while (0)
; #define PG8_LDB(dst, b, h) do { _Pragma("unroll") for (int n = 0; n < 2; ++n) _Pragma("unroll") for (int k = 0; k < 2; ++k) dst[n][k] = *(const LAS bf16x8*)(lds + PG8_SB(b, h) + boff + n * 2048 + k * 1024); } while (0)
; #define PG8_MMA(ai, bj, At, Bt) do { __builtin_amdgcn_s_setprio(1); _Pragma("unroll") for (int m = 0; m < 4; ++m) _Pragma("unroll") for (int n = 0; n < 2; ++n) _Pragma("unroll") for (int k = 0; k < 2; ++k) \
;         acc[ai][bj][m][n] = __builtin_amdgcn_mfma_f32_16x16x32_bf16(Bt[n][k], At[m][k], acc[ai][bj][m][n], 0, 0, 0); __builtin_amdgcn_s_setprio(0); } while (0)
; #define PG8_WAIT_V(n) asm volatile("s_waitcnt vmcnt(" #n ")" ::: "memory")
; #define PG8_WAIT_L(n) asm volatile("s_waitcnt lgkmcnt(" #n ")" ::: "memory")
; #define PG8_BAR __builtin_amdgcn_s_barrier()
; #define PG8_SCHED __builtin_amdgcn_sched_barrier(0)
; template <class Map, class Epi>
; DI void gemm_phase(LAS unsigned char* lds, const Map& MP, const Epi& E, const int nM, const int nN, const int K, const int lda, const int ldb) {
;     ...
;             PG8_LDB(B0, 0, 0); PG8_SCHED; PG8_LDA(At, 0, 0); PG8_STAGE(PG8_SA(1, 1), a1 + hstepA, voffA);
;             PG8_WAIT_L(8); PG8_BAR; PG8_WAIT_L(0); PG8_MMA(0, 0, At, B0); PG8_BAR; PG8_SCHED;
;             PG8_LDB(B1, 0, 1); PG8_STAGE(PG8_SB(0, 0), b2, voffB);
;             PG8_BAR; PG8_WAIT_L(0); PG8_MMA(0, 1, At, B1); PG8_BAR;
;             PG8_LDA(At, 0, 1); PG8_STAGE(PG8_SA(0, 0), a2, voffA);
;             PG8_BAR; PG8_WAIT_L(0); PG8_MMA(1, 0, At, B0); PG8_BAR; PG8_SCHED;
;             PG8_STAGE(PG8_SB(0, 1), b2 + hstepB, voffB);
;             PG8_WAIT_V(6); PG8_BAR; PG8_MMA(1, 1, At, B1); PG8_BAR;
.LBB1_1069:
	s_add_u32 s24, s42, 0xfff80080
	s_addc_u32 s25, s43, -1
	s_cmp_eq_u32 s3, 28
	s_cselect_b32 s47, s23, s25
	s_cselect_b32 s46, s58, s24
	s_cselect_b32 s25, s21, vcc_hi
	s_cselect_b32 s24, s59, vcc_lo
	s_add_i32 m0, s38, 0xc000
	ds_read_b128 v[96:99], v190
	ds_read_b128 v[100:103], v190 offset:1024
	ds_read_b128 v[108:111], v190 offset:2048
	ds_read_b128 v[112:115], v190 offset:3072
	ds_read_b128 v[160:163], v190 offset:4096
	ds_read_b128 v[164:167], v190 offset:5120
	ds_read_b128 v[198:201], v190 offset:6144
	ds_read_b128 v[202:205], v190 offset:7168
	global_load_lds_dwordx4 v178, s[42:43]
	s_add_i32 m0, s38, 0xe000
	s_nop 0
	global_load_lds_dwordx4 v176, s[42:43]
	s_waitcnt lgkmcnt(8)
	s_setprio 1
	s_barrier
	s_waitcnt lgkmcnt(7)
	v_mfma_f32_16x16x32_bf16 v[148:151], v[80:83], v[96:99], v[148:151]
	v_mfma_f32_16x16x32_bf16 v[144:147], v[88:91], v[96:99], v[144:147]
	s_waitcnt lgkmcnt(5)
	v_mfma_f32_16x16x32_bf16 v[136:139], v[80:83], v[108:111], v[136:139]
	v_mfma_f32_16x16x32_bf16 v[128:131], v[88:91], v[108:111], v[128:131]
	s_waitcnt lgkmcnt(3)
	v_mfma_f32_16x16x32_bf16 v[120:123], v[80:83], v[160:163], v[120:123]
	v_mfma_f32_16x16x32_bf16 v[104:107], v[88:91], v[160:163], v[104:107]
	s_waitcnt lgkmcnt(1)
	v_mfma_f32_16x16x32_bf16 v[76:79], v[80:83], v[198:201], v[76:79]
	v_mfma_f32_16x16x32_bf16 v[72:75], v[88:91], v[198:201], v[72:75]
	v_mfma_f32_16x16x32_bf16 v[148:151], v[84:87], v[100:103], v[148:151]
	v_mfma_f32_16x16x32_bf16 v[144:147], v[92:95], v[100:103], v[144:147]
	v_mfma_f32_16x16x32_bf16 v[136:139], v[84:87], v[112:115], v[136:139]
	v_mfma_f32_16x16x32_bf16 v[128:131], v[92:95], v[112:115], v[128:131]
	v_mfma_f32_16x16x32_bf16 v[120:123], v[84:87], v[164:167], v[120:123]
	v_mfma_f32_16x16x32_bf16 v[104:107], v[92:95], v[164:167], v[104:107]
	s_waitcnt lgkmcnt(0)
	v_mfma_f32_16x16x32_bf16 v[76:79], v[84:87], v[202:205], v[76:79]
	v_mfma_f32_16x16x32_bf16 v[72:75], v[92:95], v[202:205], v[72:75]
	s_barrier
	s_setprio 0
	s_add_i32 s68, s31, s66
	v_lshl_add_u64 v[184:185], s[24:25], 0, v[172:173]
	s_mov_b32 m0, s68
	ds_read_b128 v[206:209], v191
	ds_read_b128 v[210:213], v191 offset:1024
	ds_read_b128 v[214:217], v191 offset:2048
	ds_read_b128 v[218:221], v191 offset:3072
	global_load_lds_dwordx4 v[184:185], off
	v_lshl_add_u64 v[194:195], s[24:25], 0, v[168:169]
	s_add_i32 m0, s68, 0x2000
	s_nop 0
	global_load_lds_dwordx4 v[194:195], off
	s_setprio 1
	s_barrier
	s_waitcnt lgkmcnt(3)
	v_mfma_f32_16x16x32_bf16 v[156:159], v[206:209], v[96:99], v[156:159]
	s_waitcnt lgkmcnt(1)
	v_mfma_f32_16x16x32_bf16 v[96:99], v[214:217], v[96:99], v[152:155]
	v_mfma_f32_16x16x32_bf16 v[156:159], v[210:213], v[100:103], v[156:159]
	s_waitcnt lgkmcnt(0)
	v_mfma_f32_16x16x32_bf16 v[96:99], v[218:221], v[100:103], v[96:99]
	v_mfma_f32_16x16x32_bf16 v[100:103], v[206:209], v[108:111], v[140:143]
	v_mfma_f32_16x16x32_bf16 v[108:111], v[214:217], v[108:111], v[132:135]
	v_mfma_f32_16x16x32_bf16 v[116:119], v[214:217], v[160:163], v[116:119]
	v_mfma_f32_16x16x32_bf16 v[68:71], v[206:209], v[198:201], v[68:71]
	v_mfma_f32_16x16x32_bf16 v[64:67], v[214:217], v[198:201], v[64:67]
	s_mov_b32 m0, s38
	v_mfma_f32_16x16x32_bf16 v[100:103], v[210:213], v[112:115], v[100:103]
	v_lshl_add_u64 v[226:227], s[46:47], 0, v[174:175]
	v_mfma_f32_16x16x32_bf16 v[108:111], v[218:221], v[112:115], v[108:111]
	v_mfma_f32_16x16x32_bf16 v[112:115], v[206:209], v[160:163], v[124:127]
	v_mfma_f32_16x16x32_bf16 v[116:119], v[218:221], v[164:167], v[116:119]
	v_mfma_f32_16x16x32_bf16 v[68:71], v[210:213], v[202:205], v[68:71]
	v_mfma_f32_16x16x32_bf16 v[64:67], v[218:221], v[202:205], v[64:67]
	v_mfma_f32_16x16x32_bf16 v[112:115], v[210:213], v[164:167], v[112:115]
	s_barrier
	s_setprio 0
	ds_read_b128 v[124:127], v190 offset:16384
	ds_read_b128 v[132:135], v190 offset:17408
	ds_read_b128 v[140:143], v190 offset:18432
	ds_read_b128 v[152:155], v190 offset:19456
	ds_read_b128 v[160:163], v190 offset:20480
	ds_read_b128 v[164:167], v190 offset:21504
	ds_read_b128 v[198:201], v190 offset:22528
	ds_read_b128 v[202:205], v190 offset:23552
	global_load_lds_dwordx4 v[226:227], off
	v_lshl_add_u64 v[234:235], s[46:47], 0, v[170:171]
	s_mov_b32 m0, s39
	s_nop 0
	global_load_lds_dwordx4 v[234:235], off
	s_waitcnt vmcnt(10)
	s_setprio 1
	s_barrier
	s_waitcnt lgkmcnt(7)
	v_mfma_f32_16x16x32_bf16 v[60:63], v[80:83], v[124:127], v[60:63]
	v_mfma_f32_16x16x32_bf16 v[48:51], v[88:91], v[124:127], v[48:51]
	s_waitcnt lgkmcnt(5)
	v_mfma_f32_16x16x32_bf16 v[40:43], v[80:83], v[140:143], v[40:43]
	v_mfma_f32_16x16x32_bf16 v[32:35], v[88:91], v[140:143], v[32:35]
	s_waitcnt lgkmcnt(3)
	v_mfma_f32_16x16x32_bf16 v[24:27], v[80:83], v[160:163], v[24:27]
	v_mfma_f32_16x16x32_bf16 v[16:19], v[88:91], v[160:163], v[16:19]
	s_waitcnt lgkmcnt(1)
	v_mfma_f32_16x16x32_bf16 v[12:15], v[80:83], v[198:201], v[12:15]
	v_mfma_f32_16x16x32_bf16 v[8:11], v[88:91], v[198:201], v[8:11]
	v_mfma_f32_16x16x32_bf16 v[60:63], v[84:87], v[132:135], v[60:63]
	v_mfma_f32_16x16x32_bf16 v[48:51], v[92:95], v[132:135], v[48:51]
	v_mfma_f32_16x16x32_bf16 v[40:43], v[84:87], v[152:155], v[40:43]
	v_mfma_f32_16x16x32_bf16 v[32:35], v[92:95], v[152:155], v[32:35]
	v_mfma_f32_16x16x32_bf16 v[24:27], v[84:87], v[164:167], v[24:27]
	v_mfma_f32_16x16x32_bf16 v[16:19], v[92:95], v[164:167], v[16:19]
	s_waitcnt lgkmcnt(0)
	v_mfma_f32_16x16x32_bf16 v[12:15], v[84:87], v[202:205], v[12:15]
	v_mfma_f32_16x16x32_bf16 v[8:11], v[92:95], v[202:205], v[8:11]
	s_barrier
	s_setprio 0
	s_add_u32 s68, s24, 0x80000
	s_addc_u32 s69, s25, 0
	s_add_i32 s70, s2, s66
	s_mov_b32 m0, s70
	s_nop 0
	global_load_lds_dwordx4 v172, s[68:69]
	s_add_i32 m0, s70, 0x2000
	s_nop 0
	global_load_lds_dwordx4 v168, s[68:69]
	s_waitcnt vmcnt(6)
	s_setprio 1
	s_barrier
; #define PG8_STAGE(bufoff, gbase, voff) do { _Pragma("unroll") for (int _i = 0; _i < 2; ++_i) \
;         __builtin_amdgcn_global_load_lds((const unsigned*)((const char*)(gbase) + (voff)[_i]), (LAS unsigned*)(lds + (bufoff) + ldsw + _i * 8192), 16, 0, 0); } while (0)
; #define PG8_LDA(dst, b, h) do { _Pragma("unroll") for (int m = 0; m < 4; ++m) _Pragma("unroll") for (int k = 0; k < 2; ++k) dst[m][k] = *(const LAS bf16x8*)(lds + PG8_SA(b, h) + aoff + m * 2048 + k * 1024); } while (0)
; #define PG8_LDB(dst, b, h) do { _Pragma("unroll") for (int n = 0; n < 2; ++n) _Pragma("unroll") for (int k = 0; k < 2; ++k) dst[n][k] = *(const LAS bf16x8*)(lds + PG8_SB(b, h) + boff + n * 2048 + k * 1024); } while (0)
; #define PG8_MMA(ai, bj, At, Bt) do { __builtin_amdgcn_s_setprio(1); _Pragma("unroll") for (int m = 0; m < 4; ++m) _Pragma("unroll") for (int n = 0; n < 2; ++n) _Pragma("unroll") for (int k = 0; k < 2; ++k) \
;         acc[ai][bj][m][n] = __builtin_amdgcn_mfma_f32_16x16x32_bf16(Bt[n][k], At[m][k], acc[ai][bj][m][n], 0, 0, 0); __builtin_amdgcn_s_setprio(0); } while (0)
; #define PG8_WAIT_V(n) asm volatile("s_waitcnt vmcnt(" #n ")" ::: "memory")
; #define PG8_WAIT_L(n) asm volatile("s_waitcnt lgkmcnt(" #n ")" ::: "memory")
; #define PG8_BAR __builtin_amdgcn_s_barrier()
; #define PG8_SCHED __builtin_amdgcn_sched_barrier(0)
; template <class Map, class Epi>
; DI void gemm_phase(LAS unsigned char* lds, const Map& MP, const Epi& E, const int nM, const int nN, const int K, const int lda, const int ldb) {
;     ...
;             PG8_WAIT_V(6); PG8_BAR; PG8_MMA(1, 1, At, B1); PG8_BAR;
;             PG8_LDB(B0, 1, 0); PG8_SCHED; PG8_LDA(At, 1, 0); PG8_STAGE(PG8_SA(0, 1), a2 + hstepA, voffA);
;             PG8_WAIT_L(8); PG8_BAR; PG8_WAIT_L(0); PG8_MMA(0, 0, At, B0); PG8_BAR; PG8_SCHED;
;             PG8_LDB(B1, 1, 1); PG8_STAGE(PG8_SB(1, 0), b3, voffB);
;             PG8_BAR; PG8_WAIT_L(0); PG8_MMA(0, 1, At, B1); PG8_BAR;
;             PG8_LDA(At, 1, 1); PG8_STAGE(PG8_SA(1, 0), a3, voffA);
;             PG8_BAR; PG8_WAIT_L(0); PG8_MMA(1, 0, At, B0); PG8_BAR; PG8_SCHED;
	v_mfma_f32_16x16x32_bf16 v[56:59], v[206:209], v[124:127], v[56:59]
	v_mfma_f32_16x16x32_bf16 v[52:55], v[214:217], v[124:127], v[52:55]
	s_add_i32 s68, 0, 0x18000
	v_add_u32_e32 v92, s68, v188
	ds_read_b128 v[80:83], v92
	v_mfma_f32_16x16x32_bf16 v[44:47], v[206:209], v[140:143], v[44:47]
	v_mfma_f32_16x16x32_bf16 v[36:39], v[214:217], v[140:143], v[36:39]
	ds_read_b128 v[84:87], v92 offset:1024
	v_mfma_f32_16x16x32_bf16 v[28:31], v[206:209], v[160:163], v[28:31]
	v_mfma_f32_16x16x32_bf16 v[20:23], v[214:217], v[160:163], v[20:23]
	ds_read_b128 v[88:91], v92 offset:2048
	v_mfma_f32_16x16x32_bf16 v[4:7], v[206:209], v[198:201], v[4:7]
	v_mfma_f32_16x16x32_bf16 v[0:3], v[214:217], v[198:201], v[0:3]
	ds_read_b128 v[92:95], v92 offset:3072
	v_mfma_f32_16x16x32_bf16 v[56:59], v[210:213], v[132:135], v[56:59]
	v_mfma_f32_16x16x32_bf16 v[52:55], v[218:221], v[132:135], v[52:55]
	v_mfma_f32_16x16x32_bf16 v[44:47], v[210:213], v[152:155], v[44:47]
	v_mfma_f32_16x16x32_bf16 v[36:39], v[218:221], v[152:155], v[36:39]
	v_mfma_f32_16x16x32_bf16 v[28:31], v[210:213], v[164:167], v[28:31]
	v_mfma_f32_16x16x32_bf16 v[20:23], v[218:221], v[164:167], v[20:23]
	v_mfma_f32_16x16x32_bf16 v[4:7], v[210:213], v[202:205], v[4:7]
	v_mfma_f32_16x16x32_bf16 v[0:3], v[218:221], v[202:205], v[0:3]
	s_barrier
	s_setprio 0
	s_add_u32 s46, s46, 0x80000
	s_addc_u32 s47, s47, 0
	s_mov_b32 m0, s56
	ds_read_b128 v[124:127], v190 offset:32768
	ds_read_b128 v[132:135], v190 offset:33792
	ds_read_b128 v[160:163], v190 offset:34816
	ds_read_b128 v[164:167], v190 offset:35840
	ds_read_b128 v[198:201], v190 offset:36864
	ds_read_b128 v[202:205], v190 offset:37888
	ds_read_b128 v[206:209], v190 offset:38912
	ds_read_b128 v[210:213], v190 offset:39936
	global_load_lds_dwordx4 v174, s[46:47]
	s_mov_b32 m0, s57
	s_nop 0
	global_load_lds_dwordx4 v170, s[46:47]
	s_waitcnt lgkmcnt(8)
	s_setprio 1
	s_barrier
	s_waitcnt lgkmcnt(7)
	v_mfma_f32_16x16x32_bf16 v[140:143], v[80:83], v[124:127], v[148:151]
	s_waitcnt lgkmcnt(6)
	v_mfma_f32_16x16x32_bf16 v[148:151], v[84:87], v[132:135], v[140:143]
	v_mfma_f32_16x16x32_bf16 v[140:143], v[88:91], v[124:127], v[144:147]
	s_waitcnt lgkmcnt(5)
	v_mfma_f32_16x16x32_bf16 v[136:139], v[80:83], v[160:163], v[136:139]
	v_mfma_f32_16x16x32_bf16 v[128:131], v[88:91], v[160:163], v[128:131]
	s_waitcnt lgkmcnt(3)
	v_mfma_f32_16x16x32_bf16 v[120:123], v[80:83], v[198:201], v[120:123]
	v_mfma_f32_16x16x32_bf16 v[104:107], v[88:91], v[198:201], v[104:107]
	s_waitcnt lgkmcnt(1)
	v_mfma_f32_16x16x32_bf16 v[76:79], v[80:83], v[206:209], v[76:79]
	v_mfma_f32_16x16x32_bf16 v[72:75], v[88:91], v[206:209], v[72:75]
	v_mfma_f32_16x16x32_bf16 v[144:147], v[92:95], v[132:135], v[140:143]
	v_mfma_f32_16x16x32_bf16 v[136:139], v[84:87], v[164:167], v[136:139]
	v_mfma_f32_16x16x32_bf16 v[128:131], v[92:95], v[164:167], v[128:131]
	v_mfma_f32_16x16x32_bf16 v[120:123], v[84:87], v[202:205], v[120:123]
	v_mfma_f32_16x16x32_bf16 v[104:107], v[92:95], v[202:205], v[104:107]
	s_waitcnt lgkmcnt(0)
	v_mfma_f32_16x16x32_bf16 v[76:79], v[84:87], v[210:213], v[76:79]
	v_mfma_f32_16x16x32_bf16 v[72:75], v[92:95], v[210:213], v[72:75]
	s_barrier
	s_setprio 0
	s_add_i32 s46, 0, 0x1c000
	v_add_u32_e32 v140, s46, v188
	s_add_i32 s47, s68, s66
	ds_read_b128 v[214:217], v140
	ds_read_b128 v[218:221], v140 offset:1024
	ds_read_b128 v[222:225], v140 offset:2048
	ds_read_b128 v[230:233], v140 offset:3072
	v_lshl_add_u64 v[140:141], v[184:185], 0, s[14:15]
	s_mov_b32 m0, s47
	s_nop 0
	global_load_lds_dwordx4 v[140:141], off
	v_lshl_add_u64 v[140:141], v[194:195], 0, s[14:15]
	s_add_i32 m0, s47, 0x2000
	s_nop 0
	global_load_lds_dwordx4 v[140:141], off
	s_setprio 1
	s_barrier
	s_waitcnt lgkmcnt(1)
	v_mfma_f32_16x16x32_bf16 v[96:99], v[222:225], v[124:127], v[96:99]
	v_mfma_f32_16x16x32_bf16 v[140:143], v[214:217], v[124:127], v[156:159]
	s_waitcnt lgkmcnt(0)
	v_mfma_f32_16x16x32_bf16 v[152:155], v[230:233], v[132:135], v[96:99]
	v_mfma_f32_16x16x32_bf16 v[96:99], v[214:217], v[160:163], v[100:103]
	v_mfma_f32_16x16x32_bf16 v[156:159], v[218:221], v[132:135], v[140:143]
	v_mfma_f32_16x16x32_bf16 v[140:143], v[218:221], v[164:167], v[96:99]
	v_mfma_f32_16x16x32_bf16 v[96:99], v[222:225], v[160:163], v[108:111]
	v_mfma_f32_16x16x32_bf16 v[132:135], v[230:233], v[164:167], v[96:99]
	v_mfma_f32_16x16x32_bf16 v[96:99], v[214:217], v[198:201], v[112:115]
	s_mov_b32 m0, s63
	v_mfma_f32_16x16x32_bf16 v[124:127], v[218:221], v[202:205], v[96:99]
	v_lshl_add_u64 v[184:185], v[226:227], 0, s[14:15]
	v_mfma_f32_16x16x32_bf16 v[96:99], v[222:225], v[198:201], v[116:119]
	v_mfma_f32_16x16x32_bf16 v[68:71], v[214:217], v[206:209], v[68:71]
	v_mfma_f32_16x16x32_bf16 v[64:67], v[222:225], v[206:209], v[64:67]
	v_mfma_f32_16x16x32_bf16 v[116:119], v[230:233], v[202:205], v[96:99]
	v_mfma_f32_16x16x32_bf16 v[68:71], v[218:221], v[210:213], v[68:71]
	v_mfma_f32_16x16x32_bf16 v[64:67], v[230:233], v[210:213], v[64:67]
	s_barrier
	s_setprio 0
	ds_read_b128 v[96:99], v190 offset:49152
	ds_read_b128 v[100:103], v190 offset:50176
	ds_read_b128 v[108:111], v190 offset:51200
	ds_read_b128 v[112:115], v190 offset:52224
	ds_read_b128 v[160:163], v190 offset:53248
	ds_read_b128 v[164:167], v190 offset:54272
	ds_read_b128 v[198:201], v190 offset:55296
	ds_read_b128 v[202:205], v190 offset:56320
	global_load_lds_dwordx4 v[184:185], off
	v_lshl_add_u64 v[184:185], v[234:235], 0, s[14:15]
	s_mov_b32 m0, s4
	s_nop 0
	global_load_lds_dwordx4 v[184:185], off
	s_waitcnt vmcnt(10)
	s_setprio 1
	s_barrier
; #define PG8_STAGE(bufoff, gbase, voff) do { _Pragma("unroll") for (int _i = 0; _i < 2; ++_i) \
;         __builtin_amdgcn_global_load_lds((const unsigned*)((const char*)(gbase) + (voff)[_i]), (LAS unsigned*)(lds + (bufoff) + ldsw + _i * 8192), 16, 0, 0); } while (0)
; #define PG8_LDA(dst, b, h) do { _Pragma("unroll") for (int m = 0; m < 4; ++m) _Pragma("unroll") for (int k = 0; k < 2; ++k) dst[m][k] = *(const LAS bf16x8*)(lds + PG8_SA(b, h) + aoff + m * 2048 + k * 1024); } while (0)
; #define PG8_LDB(dst, b, h) do { _Pragma("unroll") for (int n = 0; n < 2; ++n) _Pragma("unroll") for (int k = 0; k < 2; ++k) dst[n][k] = *(const LAS bf16x8*)(lds + PG8_SB(b, h) + boff + n * 2048 + k * 1024); } while (0)
; #define PG8_WAIT_V(n) asm volatile("s_waitcnt vmcnt(" #n ")" ::: "memory")
; #define PG8_WAIT_L(n) asm volatile("s_waitcnt lgkmcnt(" #n ")" ::: "memory")
; #define PG8_BAR __builtin_amdgcn_s_barrier()
; #define PG8_SCHED __builtin_amdgcn_sched_barrier(0)
; template <class Map, class Epi>
; DI void gemm_phase(LAS unsigned char* lds, const Map& MP, const Epi& E, const int nM, const int nN, const int K, const int lda, const int ldb) {
;     ...
;             PG8_LDB(B0, 0, 0); PG8_SCHED; PG8_LDA(At, 0, 0); PG8_STAGE(PG8_SA(1, 1), a1 + hstepA, voffA);
;             PG8_WAIT_L(8); PG8_BAR; PG8_WAIT_L(0); PG8_MMA(0, 0, At, B0); PG8_BAR; PG8_SCHED;
;             PG8_LDB(B1, 0, 1); PG8_STAGE(PG8_SB(0, 0), b2, voffB);
;             PG8_BAR; PG8_WAIT_L(0); PG8_MMA(0, 1, At, B1); PG8_BAR;
;             PG8_LDA(At, 0, 1); PG8_STAGE(PG8_SA(0, 0), a2, voffA);
;             PG8_BAR; PG8_WAIT_L(0); PG8_MMA(1, 0, At, B0); PG8_BAR; PG8_SCHED;
;             PG8_STAGE(PG8_SB(0, 1), b2 + hstepB, voffB);
;             PG8_WAIT_V(6); PG8_BAR; PG8_MMA(1, 1, At, B1); PG8_BAR;
;             PG8_LDB(B0, 1, 0); PG8_SCHED; PG8_LDA(At, 1, 0); PG8_STAGE(PG8_SA(0, 1), a2 + hstepA, voffA);
;             PG8_WAIT_L(8); PG8_BAR; PG8_WAIT_L(0); PG8_MMA(0, 0, At, B0); PG8_BAR; PG8_SCHED;
;             PG8_LDB(B1, 1, 1); PG8_STAGE(PG8_SB(1, 0), b3, voffB);
;             PG8_BAR; PG8_WAIT_L(0); PG8_MMA(0, 1, At, B1); PG8_BAR;
;             PG8_LDA(At, 1, 1); PG8_STAGE(PG8_SA(1, 0), a3, voffA);
;             PG8_BAR; PG8_WAIT_L(0); PG8_MMA(1, 0, At, B0); PG8_BAR; PG8_SCHED;
;             PG8_STAGE(PG8_SB(1, 1), b3 + hstepB, voffB);
;             PG8_WAIT_V(6); PG8_BAR; PG8_MMA(1, 1, At, B1); PG8_BAR;
	s_waitcnt lgkmcnt(7)
	v_mfma_f32_16x16x32_bf16 v[60:63], v[80:83], v[96:99], v[60:63]
	v_mfma_f32_16x16x32_bf16 v[48:51], v[88:91], v[96:99], v[48:51]
	s_waitcnt lgkmcnt(5)
	v_mfma_f32_16x16x32_bf16 v[40:43], v[80:83], v[108:111], v[40:43]
	v_mfma_f32_16x16x32_bf16 v[32:35], v[88:91], v[108:111], v[32:35]
	s_waitcnt lgkmcnt(3)
	v_mfma_f32_16x16x32_bf16 v[24:27], v[80:83], v[160:163], v[24:27]
	v_mfma_f32_16x16x32_bf16 v[16:19], v[88:91], v[160:163], v[16:19]
	s_waitcnt lgkmcnt(1)
	v_mfma_f32_16x16x32_bf16 v[12:15], v[80:83], v[198:201], v[12:15]
	v_mfma_f32_16x16x32_bf16 v[8:11], v[88:91], v[198:201], v[8:11]
	v_mfma_f32_16x16x32_bf16 v[60:63], v[84:87], v[100:103], v[60:63]
	v_mfma_f32_16x16x32_bf16 v[48:51], v[92:95], v[100:103], v[48:51]
	v_mfma_f32_16x16x32_bf16 v[40:43], v[84:87], v[112:115], v[40:43]
	v_mfma_f32_16x16x32_bf16 v[32:35], v[92:95], v[112:115], v[32:35]
	v_mfma_f32_16x16x32_bf16 v[24:27], v[84:87], v[164:167], v[24:27]
	v_mfma_f32_16x16x32_bf16 v[16:19], v[92:95], v[164:167], v[16:19]
	s_waitcnt lgkmcnt(0)
	v_mfma_f32_16x16x32_bf16 v[12:15], v[84:87], v[202:205], v[12:15]
	v_mfma_f32_16x16x32_bf16 v[8:11], v[92:95], v[202:205], v[8:11]
	s_barrier
	s_setprio 0
	s_add_u32 s24, s24, 0x80080
	s_addc_u32 s25, s25, 0
	s_add_i32 s46, s46, s66
	s_mov_b32 m0, s46
	s_nop 0
	global_load_lds_dwordx4 v172, s[24:25]
	s_add_i32 m0, s46, 0x2000
	s_nop 0
	global_load_lds_dwordx4 v168, s[24:25]
	s_waitcnt vmcnt(6)
	s_setprio 1
	s_barrier
	v_mfma_f32_16x16x32_bf16 v[56:59], v[214:217], v[96:99], v[56:59]
	v_mfma_f32_16x16x32_bf16 v[52:55], v[222:225], v[96:99], v[52:55]
	ds_read_b128 v[80:83], v189
	v_mfma_f32_16x16x32_bf16 v[44:47], v[214:217], v[108:111], v[44:47]
	v_mfma_f32_16x16x32_bf16 v[36:39], v[222:225], v[108:111], v[36:39]
	ds_read_b128 v[84:87], v189 offset:1024
	v_mfma_f32_16x16x32_bf16 v[28:31], v[214:217], v[160:163], v[28:31]
	v_mfma_f32_16x16x32_bf16 v[20:23], v[222:225], v[160:163], v[20:23]
	ds_read_b128 v[88:91], v189 offset:2048
	v_mfma_f32_16x16x32_bf16 v[4:7], v[214:217], v[198:201], v[4:7]
	v_mfma_f32_16x16x32_bf16 v[0:3], v[222:225], v[198:201], v[0:3]
	ds_read_b128 v[92:95], v189 offset:3072
	v_mfma_f32_16x16x32_bf16 v[56:59], v[218:221], v[100:103], v[56:59]
	s_add_i32 s3, s3, 2
	v_mfma_f32_16x16x32_bf16 v[52:55], v[230:233], v[100:103], v[52:55]
	s_add_u32 vcc_lo, vcc_lo, 0x100
	s_addc_u32 vcc_hi, vcc_hi, 0
	v_mfma_f32_16x16x32_bf16 v[44:47], v[218:221], v[112:115], v[44:47]
	s_add_u32 s42, s42, 0x100
	s_addc_u32 s43, s43, 0
	v_mfma_f32_16x16x32_bf16 v[36:39], v[230:233], v[112:115], v[36:39]
	s_cmp_gt_u32 s3, 29
	v_mfma_f32_16x16x32_bf16 v[28:31], v[218:221], v[164:167], v[28:31]
	v_mfma_f32_16x16x32_bf16 v[20:23], v[230:233], v[164:167], v[20:23]
	v_mfma_f32_16x16x32_bf16 v[4:7], v[218:221], v[202:205], v[4:7]
	v_mfma_f32_16x16x32_bf16 v[0:3], v[230:233], v[202:205], v[0:3]
	s_barrier
	s_setprio 0
	s_cbranch_scc0 .LBB1_1069
; DI float silu_mul(float g, float v) { return g * v * __builtin_amdgcn_rcpf(1.0f + __builtin_amdgcn_exp2f(-LOG2E * g)); }
;     DI void operator()(const f32x4 (&acc)[2][2][4][2], const Unit& u, int wr, int wc, int fr, int fq) const {
;         const int row0 = u.pm * BM + wr * 64 + fr, ch0 = u.pn * 128 + wc * 32 + 8 * fq;
;         f32x4 w0[2], w1[2], w2[2], bb[2];
; #pragma unroll
;         for (int n = 0; n < 2; ++n) { w0[n] = *(const f32x4*)(cw + ch0 + 4 * n); w1[n] = *(const f32x4*)(cw + DFF + ch0 + 4 * n); w2[n] = *(const f32x4*)(cw + 2 * DFF + ch0 + 4 * n); bb[n] = *(const f32x4*)(cb + ch0 + 4 * n); }
; #pragma unroll
;         for (int ai = 0; ai < 2; ++ai)
; #pragma unroll
;             for (int m = 0; m < 4; ++m) {
;                 const bool efirst = (m == 0) && (fr == 0), elast = (m == 3) && (fr == 15);
;                 const int row = row0 + ai * HALF + m * 16;
;                 f32x4 gc[2];
; #pragma unroll
;                 for (int n = 0; n < 2; ++n) {
;                     const f32x4 g = acc[ai][0][m][n];
;                     const f32x4 gprev = acc[ai][0][m > 0 ? m - 1 : 0][n], gnext = acc[ai][0][m < 3 ? m + 1 : 3][n];
;                     f32x4 up, dn;
; #pragma unroll
;                     for (int e = 0; e < 4; ++e) {
;                         const float pu = (m > 0 && fr == 15) ? gprev[e] : g[e];
;                         const float pd = (m < 3 && fr == 0) ? gnext[e] : g[e];
;                         up[e] = dpp_ror1(pu); dn[e] = dpp_ror15(pd);
;                     }
;                     if (efirst) up = (f32x4){0.f, 0.f, 0.f, 0.f};
;                     if (elast) dn = (f32x4){0.f, 0.f, 0.f, 0.f};
;                     gc[n] = w0[n] * up + w1[n] * g + w2[n] * dn + bb[n];
;                 }
;                 if (efirst || elast) {
;                     const size_t eo = (size_t)((row >> 6) * 2 + (elast ? 1 : 0)) * DFF + ch0;
; #pragma unroll
;                     for (int n = 0; n < 2; ++n) { *(f32x4*)(EP + eo + 4 * n) = gc[n]; *(f32x4*)(ER + eo + 4 * n) = acc[ai][0][m][n]; *(f32x4*)(EV + eo + 4 * n) = acc[ai][1][m][n]; }
;                 } else {
;                     const f32x4 v0 = acc[ai][1][m][0], v1 = acc[ai][1][m][1];
;                     u32x4 o;
;                     o[0] = pack2(silu_mul(gc[0][0], v0[0]), silu_mul(gc[0][1], v0[1])); o[1] = pack2(silu_mul(gc[0][2], v0[2]), silu_mul(gc[0][3], v0[3]));
	s_waitcnt lgkmcnt(0)
	s_lshl_b32 s21, s45, 7
	v_mov_b32_e32 v194, v186
	v_mov_b32_e32 v80, v187
	s_or_b32 s21, s21, s62
	v_lshl_add_u32 v184, v80, 3, s21
	v_ashrrev_i32_e32 v185, 31, v184
	v_lshlrev_b64 v[80:81], 2, v[184:185]
	v_lshl_add_u64 v[84:85], s[6:7], 0, v[80:81]
	v_lshl_add_u64 v[88:89], s[16:17], 0, v[80:81]
	v_lshl_add_u64 v[92:93], s[18:19], 0, v[80:81]
	v_lshl_add_u64 v[112:113], s[52:53], 0, v[80:81]
	global_load_dwordx4 v[80:83], v[84:85], off offset:16
	global_load_dwordx4 v[96:99], v[84:85], off
	s_nop 0
	global_load_dwordx4 v[84:87], v[88:89], off offset:16
	global_load_dwordx4 v[100:103], v[88:89], off
	s_nop 0
	global_load_dwordx4 v[88:91], v[92:93], off offset:16
	global_load_dwordx4 v[108:111], v[92:93], off
	s_nop 0
	global_load_dwordx4 v[92:95], v[112:113], off offset:16
	s_nop 0
	global_load_dwordx4 v[112:115], v[112:113], off
	v_cmp_eq_u32_e32 vcc, 0, v194
	s_nop 0
	s_nop 0
	v_cndmask_b32_e32 v161, v148, v136, vcc
	v_cndmask_b32_e32 v162, v149, v137, vcc
	v_cndmask_b32_e32 v163, v150, v138, vcc
	v_mov_b32_dpp v160, v161 row_ror:15 row_mask:0xf bank_mask:0xf
	s_nop 0
	s_nop 0
	v_mov_b32_dpp v161, v162 row_ror:15 row_mask:0xf bank_mask:0xf
	v_mov_b32_dpp v164, v150 row_ror:1 row_mask:0xf bank_mask:0xf
	v_cndmask_b32_e32 v165, v151, v139, vcc
	v_mov_b32_dpp v162, v163 row_ror:15 row_mask:0xf bank_mask:0xf
	v_mov_b32_dpp v195, v151 row_ror:1 row_mask:0xf bank_mask:0xf
	v_mov_b32_dpp v166, v148 row_ror:1 row_mask:0xf bank_mask:0xf
	v_mov_b32_dpp v167, v149 row_ror:1 row_mask:0xf bank_mask:0xf
	v_mov_b32_dpp v163, v165 row_ror:15 row_mask:0xf bank_mask:0xf
	v_cndmask_b32_e64 v165, v195, 0, vcc
	v_cndmask_b32_e64 v164, v164, 0, vcc
	v_cndmask_b32_e64 v167, v167, 0, vcc
	v_cndmask_b32_e64 v166, v166, 0, vcc
	s_nop 0
	s_nop 0
	v_mov_b32_dpp v195, v144 row_ror:1 row_mask:0xf bank_mask:0xf
	v_mov_b32_dpp v196, v145 row_ror:1 row_mask:0xf bank_mask:0xf
	v_mov_b32_dpp v198, v146 row_ror:1 row_mask:0xf bank_mask:0xf
	v_cndmask_b32_e32 v199, v147, v131, vcc
	v_mov_b32_dpp v200, v147 row_ror:1 row_mask:0xf bank_mask:0xf
	v_cndmask_b32_e64 v198, v198, 0, vcc
	v_cndmask_b32_e64 v201, v196, 0, vcc
	s_lshl_b32 s3, s44, 8
	s_add_i32 s3, s3, s49
	v_add_u32_e32 v193, s3, v194
	v_cmp_ne_u32_e64 s[46:47], 0, v194
	s_waitcnt vmcnt(0)
	v_pk_mul_f32 v[164:165], v[98:99], v[164:165]
	v_pk_mul_f32 v[166:167], v[96:97], v[166:167]
	v_pk_fma_f32 v[164:165], v[150:151], v[102:103], v[164:165]
	v_pk_fma_f32 v[166:167], v[148:149], v[100:101], v[166:167]
	v_pk_fma_f32 v[162:163], v[110:111], v[162:163], v[164:165]
	v_cndmask_b32_e32 v165, v144, v128, vcc
	v_pk_fma_f32 v[160:161], v[108:109], v[160:161], v[166:167]
	v_cndmask_b32_e32 v166, v145, v129, vcc
	v_mov_b32_dpp v164, v165 row_ror:15 row_mask:0xf bank_mask:0xf
	v_cndmask_b32_e32 v167, v146, v130, vcc
	v_pk_add_f32 v[162:163], v[114:115], v[162:163]
	v_mov_b32_dpp v165, v166 row_ror:15 row_mask:0xf bank_mask:0xf
	v_pk_add_f32 v[160:161], v[112:113], v[160:161]
	s_nop 0
	v_mov_b32_dpp v166, v167 row_ror:15 row_mask:0xf bank_mask:0xf
	s_nop 1
	v_mov_b32_dpp v167, v199 row_ror:15 row_mask:0xf bank_mask:0xf
	v_cndmask_b32_e64 v199, v200, 0, vcc
	v_cndmask_b32_e64 v200, v195, 0, vcc
	v_pk_mul_f32 v[200:201], v[80:81], v[200:201]
	v_pk_mul_f32 v[198:199], v[82:83], v[198:199]
	v_pk_fma_f32 v[200:201], v[144:145], v[84:85], v[200:201]
	v_pk_fma_f32 v[198:199], v[146:147], v[86:87], v[198:199]
	v_pk_fma_f32 v[164:165], v[88:89], v[164:165], v[200:201]
	v_pk_fma_f32 v[166:167], v[90:91], v[166:167], v[198:199]
	v_pk_add_f32 v[164:165], v[92:93], v[164:165]
	v_pk_add_f32 v[166:167], v[94:95], v[166:167]
	s_and_saveexec_b64 s[24:25], s[46:47]
	s_xor_b64 s[24:25], exec, s[24:25]
	s_cbranch_execz .LBB1_1072
	v_mul_f32_e32 v195, 0xbfb8aa3b, v160
	v_exp_f32_e32 v195, v195
	v_mul_f32_e32 v196, 0xbfb8aa3b, v161
	v_exp_f32_e32 v196, v196
	v_pk_mul_f32 v[160:161], v[156:157], v[160:161]
	v_add_f32_e32 v195, 1.0, v195
	v_rcp_f32_e32 v198, v195
	v_add_f32_e32 v196, 1.0, v196
	v_mul_f32_e32 v195, 0xbfb8aa3b, v162
	v_rcp_f32_e32 v199, v196
	v_exp_f32_e32 v195, v195
	v_mul_f32_e32 v196, 0xbfb8aa3b, v163
	v_exp_f32_e32 v196, v196
	v_pk_mul_f32 v[160:161], v[160:161], v[198:199]
	v_add_f32_e32 v195, 1.0, v195
	v_rcp_f32_e32 v200, v195
	v_add_f32_e32 v195, 1.0, v196
	v_rcp_f32_e32 v201, v195
	v_cvt_pk_bf16_f32 v160, v160, v161
	v_mul_f32_e32 v161, 0xbfb8aa3b, v164
	v_exp_f32_e32 v195, v161
	v_mul_f32_e32 v161, 0xbfb8aa3b, v165
	v_exp_f32_e32 v196, v161
	v_pk_mul_f32 v[162:163], v[158:159], v[162:163]
	v_pk_mul_f32 v[164:165], v[152:153], v[164:165]
	v_pk_mul_f32 v[162:163], v[162:163], v[200:201]
	s_nop 0
	v_cvt_pk_bf16_f32 v161, v162, v163
	v_add_f32_e32 v162, 1.0, v195
	v_mul_f32_e32 v195, 0xbfb8aa3b, v166
	v_add_f32_e32 v163, 1.0, v196
	v_exp_f32_e32 v195, v195
	v_mul_f32_e32 v196, 0xbfb8aa3b, v167
	v_exp_f32_e32 v196, v196
	v_rcp_f32_e32 v162, v162
	v_add_f32_e32 v195, 1.0, v195
	v_rcp_f32_e32 v198, v195
	v_add_f32_e32 v195, 1.0, v196
	v_rcp_f32_e32 v163, v163
	v_rcp_f32_e32 v199, v195
	v_pk_mul_f32 v[166:167], v[154:155], v[166:167]
	v_pk_mul_f32 v[162:163], v[164:165], v[162:163]
	v_pk_mul_f32 v[164:165], v[166:167], v[198:199]
	v_cvt_pk_bf16_f32 v162, v162, v163
	v_cvt_pk_bf16_f32 v163, v164, v165
	v_mov_b64_e32 v[164:165], s[54:55]
	v_mad_i64_i32 v[164:165], s[42:43], v193, s60, v[164:165]
	v_lshl_add_u64 v[164:165], v[184:185], 1, v[164:165]
	global_store_dwordx4 v[164:165], v[160:163], off

; DI unsigned pack2(float a, float b) { f32x2 v = {a, b}; hwbf16x2 r = __builtin_convertvector(v, hwbf16x2); return __builtin_bit_cast(unsigned, r); }
; DI float dpp_ror1(float v)  { return __builtin_bit_cast(float, __builtin_amdgcn_update_dpp(0, __builtin_bit_cast(int, v), 0x121, 0xf, 0xf, false)); }
;     DI void operator()(const f32x4 (&acc)[2][2][4][2], const Unit& u, int wr, int wc, int fr, int fq) const {
;     ...
;             for (int m = 0; m < 4; ++m) {
;                 const bool efirst = (m == 0) && (fr == 0), elast = (m == 3) && (fr == 15);
;                 const int row = row0 + ai * HALF + m * 16;
;                 f32x4 gc[2];
; #pragma unroll
;                 for (int n = 0; n < 2; ++n) {
;                     const f32x4 g = acc[ai][0][m][n];
;                     const f32x4 gprev = acc[ai][0][m > 0 ? m - 1 : 0][n], gnext = acc[ai][0][m < 3 ? m + 1 : 3][n];
;                     f32x4 up, dn;
; #pragma unroll
;                     for (int e = 0; e < 4; ++e) {
;                         const float pu = (m > 0 && fr == 15) ? gprev[e] : g[e];
;                         const float pd = (m < 3 && fr == 0) ? gnext[e] : g[e];
;                         up[e] = dpp_ror1(pu); dn[e] = dpp_ror15(pd);
;                     }
;                     if (efirst) up = (f32x4){0.f, 0.f, 0.f, 0.f};
;                     if (elast) dn = (f32x4){0.f, 0.f, 0.f, 0.f};
;                     gc[n] = w0[n] * up + w1[n] * g + w2[n] * dn + bb[n];
;                 }
;                 if (efirst || elast) {
;                     const size_t eo = (size_t)((row >> 6) * 2 + (elast ? 1 : 0)) * DFF + ch0;
; #pragma unroll
;                     for (int n = 0; n < 2; ++n) { *(f32x4*)(EP + eo + 4 * n) = gc[n]; *(f32x4*)(ER + eo + 4 * n) = acc[ai][0][m][n]; *(f32x4*)(EV + eo + 4 * n) = acc[ai][1][m][n]; }
;                 } else {
;                     const f32x4 v0 = acc[ai][1][m][0], v1 = acc[ai][1][m][1];
;                     u32x4 o;
;                     o[0] = pack2(silu_mul(gc[0][0], v0[0]), silu_mul(gc[0][1], v0[1])); o[1] = pack2(silu_mul(gc[0][2], v0[2]), silu_mul(gc[0][3], v0[3]));
;                     o[2] = pack2(silu_mul(gc[1][0], v1[0]), silu_mul(gc[1][1], v1[1])); o[3] = pack2(silu_mul(gc[1][2], v1[2]), silu_mul(gc[1][3], v1[3]));
;                     *(u32x4*)(ACT + (size_t)row * DFF + ch0) = o;
.LBB1_1074:
	s_or_b64 exec, exec, s[24:25]
	v_cmp_eq_u32_e64 s[44:45], 15, v194
	v_cndmask_b32_e32 v153, v136, v120, vcc
	v_cndmask_b32_e32 v154, v137, v121, vcc
	v_cndmask_b32_e64 v152, v136, v148, s[44:45]
	v_cndmask_b32_e32 v155, v138, v122, vcc
	v_cndmask_b32_e32 v156, v139, v123, vcc
	v_mov_b32_dpp v148, v152 row_ror:1 row_mask:0xf bank_mask:0xf
	v_cndmask_b32_e32 v157, v128, v104, vcc
	v_cndmask_b32_e32 v158, v129, v105, vcc
	v_mov_b32_dpp v152, v153 row_ror:15 row_mask:0xf bank_mask:0xf
	v_cndmask_b32_e64 v153, v137, v149, s[44:45]
	v_cndmask_b32_e32 v159, v130, v106, vcc
	v_cndmask_b32_e32 v160, v131, v107, vcc
	v_mov_b32_dpp v149, v153 row_ror:1 row_mask:0xf bank_mask:0xf
	v_pk_mul_f32 v[148:149], v[96:97], v[148:149]
	v_cmp_ne_u32_e64 s[42:43], 15, v194
	v_mov_b32_dpp v153, v154 row_ror:15 row_mask:0xf bank_mask:0xf
	v_pk_fma_f32 v[148:149], v[136:137], v[100:101], v[148:149]
	v_cndmask_b32_e64 v154, v138, v150, s[44:45]
	v_pk_fma_f32 v[148:149], v[108:109], v[152:153], v[148:149]
	s_nop 0
	v_mov_b32_dpp v150, v154 row_ror:1 row_mask:0xf bank_mask:0xf
	v_pk_add_f32 v[148:149], v[112:113], v[148:149]
	s_nop 0
	v_mov_b32_dpp v154, v155 row_ror:15 row_mask:0xf bank_mask:0xf
	v_cndmask_b32_e64 v155, v139, v151, s[44:45]
	v_mul_f32_e32 v152, 0xbfb8aa3b, v148
	v_mul_f32_e32 v153, 0xbfb8aa3b, v149
	v_mov_b32_dpp v151, v155 row_ror:1 row_mask:0xf bank_mask:0xf
	v_exp_f32_e32 v152, v152
	v_exp_f32_e32 v153, v153
	v_pk_mul_f32 v[150:151], v[98:99], v[150:151]
	v_add_f32_e32 v152, 1.0, v152
	v_mov_b32_dpp v155, v156 row_ror:15 row_mask:0xf bank_mask:0xf
	v_cndmask_b32_e64 v156, v128, v144, s[44:45]
	v_pk_fma_f32 v[150:151], v[138:139], v[102:103], v[150:151]
	v_add_f32_e32 v153, 1.0, v153
	v_mov_b32_dpp v144, v156 row_ror:1 row_mask:0xf bank_mask:0xf
	v_pk_fma_f32 v[150:151], v[110:111], v[154:155], v[150:151]
	v_rcp_f32_e32 v152, v152
	v_mov_b32_dpp v156, v157 row_ror:15 row_mask:0xf bank_mask:0xf
	v_cndmask_b32_e64 v157, v129, v145, s[44:45]
	v_pk_add_f32 v[150:151], v[114:115], v[150:151]
	v_rcp_f32_e32 v153, v153
	v_mov_b32_dpp v145, v157 row_ror:1 row_mask:0xf bank_mask:0xf
	v_mul_f32_e32 v154, 0xbfb8aa3b, v150
	v_mul_f32_e32 v155, 0xbfb8aa3b, v151
	v_pk_mul_f32 v[144:145], v[80:81], v[144:145]
	v_exp_f32_e32 v154, v154
	v_exp_f32_e32 v155, v155
	v_mov_b32_dpp v157, v158 row_ror:15 row_mask:0xf bank_mask:0xf
	v_pk_fma_f32 v[144:145], v[128:129], v[84:85], v[144:145]
	v_cndmask_b32_e64 v158, v130, v146, s[44:45]
	v_pk_fma_f32 v[144:145], v[88:89], v[156:157], v[144:145]
	v_pk_mul_f32 v[140:141], v[140:141], v[148:149]
	v_mov_b32_dpp v146, v158 row_ror:1 row_mask:0xf bank_mask:0xf
	v_pk_add_f32 v[144:145], v[92:93], v[144:145]
	v_pk_mul_f32 v[140:141], v[140:141], v[152:153]
	v_mov_b32_dpp v158, v159 row_ror:15 row_mask:0xf bank_mask:0xf
	v_cndmask_b32_e64 v159, v131, v147, s[44:45]
	v_pk_mul_f32 v[142:143], v[142:143], v[150:151]
	v_add_f32_e32 v150, 1.0, v154
	v_add_f32_e32 v151, 1.0, v155
	v_cvt_pk_bf16_f32 v140, v140, v141
	v_mul_f32_e32 v141, 0xbfb8aa3b, v144
	v_mov_b32_dpp v147, v159 row_ror:1 row_mask:0xf bank_mask:0xf
	v_rcp_f32_e32 v150, v150
	v_rcp_f32_e32 v151, v151
	v_exp_f32_e32 v148, v141
	v_mul_f32_e32 v141, 0xbfb8aa3b, v145
	v_pk_mul_f32 v[146:147], v[82:83], v[146:147]
	v_exp_f32_e32 v149, v141
	v_mov_b32_dpp v159, v160 row_ror:15 row_mask:0xf bank_mask:0xf
	v_pk_fma_f32 v[146:147], v[130:131], v[86:87], v[146:147]
	v_pk_mul_f32 v[142:143], v[142:143], v[150:151]
	v_pk_fma_f32 v[146:147], v[90:91], v[158:159], v[146:147]
	v_cvt_pk_bf16_f32 v141, v142, v143
	v_pk_add_f32 v[146:147], v[94:95], v[146:147]
	v_add_f32_e32 v142, 1.0, v148
	v_add_f32_e32 v143, 1.0, v149
	v_mul_f32_e32 v148, 0xbfb8aa3b, v146
	v_mul_f32_e32 v149, 0xbfb8aa3b, v147
	v_exp_f32_e32 v148, v148
	v_exp_f32_e32 v149, v149
	v_rcp_f32_e32 v142, v142
	v_rcp_f32_e32 v143, v143
	v_pk_mul_f32 v[134:135], v[134:135], v[146:147]
	v_add_f32_e32 v146, 1.0, v148
	v_add_f32_e32 v147, 1.0, v149
	v_rcp_f32_e32 v146, v146
	v_rcp_f32_e32 v147, v147
	v_pk_mul_f32 v[132:133], v[132:133], v[144:145]
	v_add_u32_e32 v160, 16, v193
	v_pk_mul_f32 v[132:133], v[132:133], v[142:143]
	v_cndmask_b32_e32 v148, v107, v75, vcc
	v_cvt_pk_bf16_f32 v142, v132, v133
	v_pk_mul_f32 v[132:133], v[134:135], v[146:147]
	v_mov_b64_e32 v[134:135], s[54:55]
	v_cvt_pk_bf16_f32 v143, v132, v133
	v_mad_i64_i32 v[144:145], s[24:25], v160, s60, v[134:135]
	v_lshlrev_b64 v[132:133], 1, v[184:185]
	v_lshl_add_u64 v[144:145], v[144:145], 0, v[132:133]
	global_store_dwordx4 v[144:145], v[140:143], off
	v_cndmask_b32_e32 v144, v123, v79, vcc
	v_cndmask_b32_e32 v145, v104, v72, vcc
	v_cndmask_b32_e64 v140, v120, v136, s[44:45]
	v_cndmask_b32_e32 v141, v120, v76, vcc
	v_cndmask_b32_e32 v142, v121, v77, vcc
	v_mov_b32_dpp v136, v140 row_ror:1 row_mask:0xf bank_mask:0xf
	v_cndmask_b32_e32 v143, v122, v78, vcc
	v_cndmask_b32_e32 v146, v105, v73, vcc
	v_mov_b32_dpp v140, v141 row_ror:15 row_mask:0xf bank_mask:0xf
	v_cndmask_b32_e64 v141, v121, v137, s[44:45]
	v_cndmask_b32_e32 v147, v106, v74, vcc
	s_nop 0
	v_mov_b32_dpp v137, v141 row_ror:1 row_mask:0xf bank_mask:0xf
	v_pk_mul_f32 v[136:137], v[96:97], v[136:137]
	s_nop 0
	v_mov_b32_dpp v141, v142 row_ror:15 row_mask:0xf bank_mask:0xf
	v_pk_fma_f32 v[136:137], v[120:121], v[100:101], v[136:137]
	v_cndmask_b32_e64 v142, v122, v138, s[44:45]
	v_pk_fma_f32 v[136:137], v[108:109], v[140:141], v[136:137]
	s_nop 0
	v_mov_b32_dpp v138, v142 row_ror:1 row_mask:0xf bank_mask:0xf
	v_pk_add_f32 v[136:137], v[112:113], v[136:137]
	s_nop 0
	v_mov_b32_dpp v142, v143 row_ror:15 row_mask:0xf bank_mask:0xf
	v_cndmask_b32_e64 v143, v123, v139, s[44:45]
	v_mul_f32_e32 v140, 0xbfb8aa3b, v136
; DI unsigned pack2(float a, float b) { f32x2 v = {a, b}; hwbf16x2 r = __builtin_convertvector(v, hwbf16x2); return __builtin_bit_cast(unsigned, r); }
; DI float dpp_ror1(float v)  { return __builtin_bit_cast(float, __builtin_amdgcn_update_dpp(0, __builtin_bit_cast(int, v), 0x121, 0xf, 0xf, false)); }
;     DI void operator()(const f32x4 (&acc)[2][2][4][2], const Unit& u, int wr, int wc, int fr, int fq) const {
;     ...
;             for (int m = 0; m < 4; ++m) {
;                 const bool efirst = (m == 0) && (fr == 0), elast = (m == 3) && (fr == 15);
;                 const int row = row0 + ai * HALF + m * 16;
;                 f32x4 gc[2];
; #pragma unroll
;                 for (int n = 0; n < 2; ++n) {
;                     const f32x4 g = acc[ai][0][m][n];
;                     const f32x4 gprev = acc[ai][0][m > 0 ? m - 1 : 0][n], gnext = acc[ai][0][m < 3 ? m + 1 : 3][n];
;                     f32x4 up, dn;
; #pragma unroll
;                     for (int e = 0; e < 4; ++e) {
;                         const float pu = (m > 0 && fr == 15) ? gprev[e] : g[e];
;                         const float pd = (m < 3 && fr == 0) ? gnext[e] : g[e];
;                         up[e] = dpp_ror1(pu); dn[e] = dpp_ror15(pd);
;                     }
;                     if (efirst) up = (f32x4){0.f, 0.f, 0.f, 0.f};
;                     if (elast) dn = (f32x4){0.f, 0.f, 0.f, 0.f};
;                     gc[n] = w0[n] * up + w1[n] * g + w2[n] * dn + bb[n];
;                 }
;                 if (efirst || elast) {
;                     const size_t eo = (size_t)((row >> 6) * 2 + (elast ? 1 : 0)) * DFF + ch0;
; #pragma unroll
;                     for (int n = 0; n < 2; ++n) { *(f32x4*)(EP + eo + 4 * n) = gc[n]; *(f32x4*)(ER + eo + 4 * n) = acc[ai][0][m][n]; *(f32x4*)(EV + eo + 4 * n) = acc[ai][1][m][n]; }
;                 } else {
;                     const f32x4 v0 = acc[ai][1][m][0], v1 = acc[ai][1][m][1];
;                     u32x4 o;
;                     o[0] = pack2(silu_mul(gc[0][0], v0[0]), silu_mul(gc[0][1], v0[1])); o[1] = pack2(silu_mul(gc[0][2], v0[2]), silu_mul(gc[0][3], v0[3]));
;                     o[2] = pack2(silu_mul(gc[1][0], v1[0]), silu_mul(gc[1][1], v1[1])); o[3] = pack2(silu_mul(gc[1][2], v1[2]), silu_mul(gc[1][3], v1[3]));
;                     *(u32x4*)(ACT + (size_t)row * DFF + ch0) = o;
;                 }
	v_mul_f32_e32 v141, 0xbfb8aa3b, v137
	v_mov_b32_dpp v139, v143 row_ror:1 row_mask:0xf bank_mask:0xf
	v_exp_f32_e32 v140, v140
	v_exp_f32_e32 v141, v141
	v_pk_mul_f32 v[138:139], v[98:99], v[138:139]
	v_add_f32_e32 v140, 1.0, v140
	v_mov_b32_dpp v143, v144 row_ror:15 row_mask:0xf bank_mask:0xf
	v_cndmask_b32_e64 v144, v104, v128, s[44:45]
	v_pk_fma_f32 v[138:139], v[122:123], v[102:103], v[138:139]
	v_add_f32_e32 v141, 1.0, v141
	v_mov_b32_dpp v128, v144 row_ror:1 row_mask:0xf bank_mask:0xf
	v_pk_fma_f32 v[138:139], v[110:111], v[142:143], v[138:139]
	v_rcp_f32_e32 v140, v140
	v_mov_b32_dpp v144, v145 row_ror:15 row_mask:0xf bank_mask:0xf
	v_cndmask_b32_e64 v145, v105, v129, s[44:45]
	v_pk_add_f32 v[138:139], v[114:115], v[138:139]
	v_rcp_f32_e32 v141, v141
	v_mov_b32_dpp v129, v145 row_ror:1 row_mask:0xf bank_mask:0xf
	v_mul_f32_e32 v142, 0xbfb8aa3b, v138
	v_mul_f32_e32 v143, 0xbfb8aa3b, v139
	v_pk_mul_f32 v[128:129], v[80:81], v[128:129]
	v_exp_f32_e32 v142, v142
	v_exp_f32_e32 v143, v143
	v_mov_b32_dpp v145, v146 row_ror:15 row_mask:0xf bank_mask:0xf
	v_pk_fma_f32 v[128:129], v[104:105], v[84:85], v[128:129]
	v_cndmask_b32_e64 v146, v106, v130, s[44:45]
	v_pk_fma_f32 v[128:129], v[88:89], v[144:145], v[128:129]
	v_pk_mul_f32 v[124:125], v[124:125], v[136:137]
	v_mov_b32_dpp v130, v146 row_ror:1 row_mask:0xf bank_mask:0xf
	v_pk_add_f32 v[128:129], v[92:93], v[128:129]
	v_pk_mul_f32 v[124:125], v[124:125], v[140:141]
	v_mov_b32_dpp v146, v147 row_ror:15 row_mask:0xf bank_mask:0xf
	v_cndmask_b32_e64 v147, v107, v131, s[44:45]
	v_pk_mul_f32 v[126:127], v[126:127], v[138:139]
	v_add_f32_e32 v138, 1.0, v142
	v_add_f32_e32 v139, 1.0, v143
	v_cvt_pk_bf16_f32 v124, v124, v125
	v_mul_f32_e32 v125, 0xbfb8aa3b, v128
	v_mov_b32_dpp v131, v147 row_ror:1 row_mask:0xf bank_mask:0xf
	v_rcp_f32_e32 v138, v138
	v_rcp_f32_e32 v139, v139
	v_exp_f32_e32 v136, v125
	v_mul_f32_e32 v125, 0xbfb8aa3b, v129
	v_pk_mul_f32 v[130:131], v[82:83], v[130:131]
	v_exp_f32_e32 v137, v125
	v_mov_b32_dpp v147, v148 row_ror:15 row_mask:0xf bank_mask:0xf
	v_pk_fma_f32 v[130:131], v[106:107], v[86:87], v[130:131]
	v_pk_mul_f32 v[126:127], v[126:127], v[138:139]
	v_pk_fma_f32 v[130:131], v[90:91], v[146:147], v[130:131]
	v_cvt_pk_bf16_f32 v125, v126, v127
	v_pk_add_f32 v[130:131], v[94:95], v[130:131]
	v_add_f32_e32 v126, 1.0, v136
	v_add_f32_e32 v127, 1.0, v137
	v_mul_f32_e32 v136, 0xbfb8aa3b, v130
	v_mul_f32_e32 v137, 0xbfb8aa3b, v131
	v_exp_f32_e32 v136, v136
	v_exp_f32_e32 v137, v137
	v_rcp_f32_e32 v126, v126
	v_rcp_f32_e32 v127, v127
	v_pk_mul_f32 v[118:119], v[118:119], v[130:131]
	v_add_f32_e32 v130, 1.0, v136
	v_add_f32_e32 v131, 1.0, v137
	v_rcp_f32_e32 v130, v130
	v_rcp_f32_e32 v131, v131
	v_pk_mul_f32 v[116:117], v[116:117], v[128:129]
	v_add_u32_e32 v148, 32, v193
	v_pk_mul_f32 v[116:117], v[116:117], v[126:127]
	s_nop 0
	v_cvt_pk_bf16_f32 v126, v116, v117
	v_pk_mul_f32 v[116:117], v[118:119], v[130:131]
	v_cndmask_b32_e64 v118, v77, v121, s[44:45]
	v_cvt_pk_bf16_f32 v127, v116, v117
	v_mad_i64_i32 v[116:117], s[24:25], v148, s60, v[134:135]
	v_lshl_add_u64 v[116:117], v[116:117], 0, v[132:133]
	global_store_dwordx4 v[116:117], v[124:127], off
	v_cndmask_b32_e64 v117, v76, v120, s[44:45]
	v_cndmask_b32_e64 v119, v78, v122, s[44:45]
	v_cndmask_b32_e64 v121, v79, v123, s[44:45]
	v_mov_b32_dpp v116, v117 row_ror:1 row_mask:0xf bank_mask:0xf
	s_nop 0
	s_nop 0
	v_mov_b32_dpp v117, v118 row_ror:1 row_mask:0xf bank_mask:0xf
	v_mov_b32_dpp v120, v78 row_ror:15 row_mask:0xf bank_mask:0xf
	v_cndmask_b32_e64 v120, v120, 0, s[44:45]
	v_mov_b32_dpp v118, v119 row_ror:1 row_mask:0xf bank_mask:0xf
	s_nop 0
	v_mov_b32_dpp v124, v76 row_ror:15 row_mask:0xf bank_mask:0xf
	v_mov_b32_dpp v119, v121 row_ror:1 row_mask:0xf bank_mask:0xf
	v_pk_mul_f32 v[118:119], v[98:99], v[118:119]
	v_mov_b32_dpp v125, v77 row_ror:15 row_mask:0xf bank_mask:0xf
	v_mov_b32_dpp v121, v79 row_ror:15 row_mask:0xf bank_mask:0xf
	v_cndmask_b32_e64 v121, v121, 0, s[44:45]
	v_pk_fma_f32 v[118:119], v[78:79], v[102:103], v[118:119]
	v_pk_mul_f32 v[116:117], v[96:97], v[116:117]
	v_pk_fma_f32 v[118:119], v[110:111], v[120:121], v[118:119]
	v_cndmask_b32_e64 v120, v72, v104, s[44:45]
	v_cndmask_b32_e64 v123, v125, 0, s[44:45]
	v_cndmask_b32_e64 v122, v124, 0, s[44:45]
	v_mov_b32_dpp v104, v120 row_ror:1 row_mask:0xf bank_mask:0xf
	v_cndmask_b32_e64 v120, v73, v105, s[44:45]
	v_pk_fma_f32 v[116:117], v[76:77], v[100:101], v[116:117]
	v_cndmask_b32_e64 v121, v75, v107, s[44:45]
	v_mov_b32_dpp v105, v120 row_ror:1 row_mask:0xf bank_mask:0xf
	v_cndmask_b32_e64 v120, v74, v106, s[44:45]
	s_nop 0
	v_pk_fma_f32 v[116:117], v[108:109], v[122:123], v[116:117]
	v_mov_b32_dpp v106, v120 row_ror:1 row_mask:0xf bank_mask:0xf
	v_mov_b32_dpp v107, v121 row_ror:1 row_mask:0xf bank_mask:0xf
	v_mov_b32_dpp v122, v72 row_ror:15 row_mask:0xf bank_mask:0xf
	v_mov_b32_dpp v123, v73 row_ror:15 row_mask:0xf bank_mask:0xf
	v_mov_b32_dpp v120, v74 row_ror:15 row_mask:0xf bank_mask:0xf
	v_mov_b32_dpp v121, v75 row_ror:15 row_mask:0xf bank_mask:0xf
	v_pk_mul_f32 v[104:105], v[80:81], v[104:105]
	v_pk_mul_f32 v[106:107], v[82:83], v[106:107]
	v_cndmask_b32_e64 v121, v121, 0, s[44:45]
	v_cndmask_b32_e64 v120, v120, 0, s[44:45]
	v_cndmask_b32_e64 v123, v123, 0, s[44:45]
	v_cndmask_b32_e64 v122, v122, 0, s[44:45]
	v_pk_fma_f32 v[106:107], v[74:75], v[86:87], v[106:107]
	v_pk_fma_f32 v[104:105], v[72:73], v[84:85], v[104:105]
	v_pk_fma_f32 v[106:107], v[90:91], v[120:121], v[106:107]
	v_pk_fma_f32 v[104:105], v[88:89], v[122:123], v[104:105]
	v_pk_add_f32 v[118:119], v[114:115], v[118:119]
	v_pk_add_f32 v[116:117], v[112:113], v[116:117]
	v_pk_add_f32 v[106:107], v[94:95], v[106:107]
	v_pk_add_f32 v[104:105], v[92:93], v[104:105]
	v_add_u32_e32 v120, 48, v193
	s_and_saveexec_b64 s[24:25], s[42:43]
	s_xor_b64 s[24:25], exec, s[24:25]
	s_cbranch_execz .LBB1_1076
; DI unsigned pack2(float a, float b) { f32x2 v = {a, b}; hwbf16x2 r = __builtin_convertvector(v, hwbf16x2); return __builtin_bit_cast(unsigned, r); }
; DI float silu_mul(float g, float v) { return g * v * __builtin_amdgcn_rcpf(1.0f + __builtin_amdgcn_exp2f(-LOG2E * g)); }
;     DI void operator()(const f32x4 (&acc)[2][2][4][2], const Unit& u, int wr, int wc, int fr, int fq) const {
;     ...
;                     const f32x4 v0 = acc[ai][1][m][0], v1 = acc[ai][1][m][1];
;                     u32x4 o;
;                     o[0] = pack2(silu_mul(gc[0][0], v0[0]), silu_mul(gc[0][1], v0[1])); o[1] = pack2(silu_mul(gc[0][2], v0[2]), silu_mul(gc[0][3], v0[3]));
;                     o[2] = pack2(silu_mul(gc[1][0], v1[0]), silu_mul(gc[1][1], v1[1])); o[3] = pack2(silu_mul(gc[1][2], v1[2]), silu_mul(gc[1][3], v1[3]));
;                     *(u32x4*)(ACT + (size_t)row * DFF + ch0) = o;
	v_mul_f32_e32 v121, 0xbfb8aa3b, v116
	v_exp_f32_e32 v121, v121
	v_mul_f32_e32 v122, 0xbfb8aa3b, v117
	v_exp_f32_e32 v122, v122
	v_mul_f32_e32 v124, 0xbfb8aa3b, v119
	v_add_f32_e32 v121, 1.0, v121
	v_exp_f32_e32 v125, v124
	v_add_f32_e32 v123, 1.0, v122
	v_rcp_f32_e32 v122, v121
	v_mul_f32_e32 v121, 0xbfb8aa3b, v118
	v_exp_f32_e32 v121, v121
	v_rcp_f32_e32 v123, v123
	v_pk_mul_f32 v[116:117], v[68:69], v[116:117]
	v_pk_mul_f32 v[118:119], v[70:71], v[118:119]
	v_add_f32_e32 v121, 1.0, v121
	v_rcp_f32_e32 v124, v121
	v_add_f32_e32 v121, 1.0, v125
	v_pk_mul_f32 v[116:117], v[116:117], v[122:123]
	v_rcp_f32_e32 v125, v121
	v_cvt_pk_bf16_f32 v116, v116, v117
	v_mul_f32_e32 v117, 0xbfb8aa3b, v104
	v_exp_f32_e32 v121, v117
	v_mul_f32_e32 v117, 0xbfb8aa3b, v105
	v_exp_f32_e32 v122, v117
	v_pk_mul_f32 v[118:119], v[118:119], v[124:125]
	v_pk_mul_f32 v[104:105], v[64:65], v[104:105]
	v_cvt_pk_bf16_f32 v117, v118, v119
	v_add_f32_e32 v118, 1.0, v121
	v_mul_f32_e32 v121, 0xbfb8aa3b, v106
	v_add_f32_e32 v119, 1.0, v122
	v_exp_f32_e32 v121, v121
	v_mul_f32_e32 v122, 0xbfb8aa3b, v107
	v_exp_f32_e32 v123, v122
	v_rcp_f32_e32 v118, v118
	v_add_f32_e32 v121, 1.0, v121
	v_rcp_f32_e32 v119, v119
	v_rcp_f32_e32 v122, v121
	v_add_f32_e32 v121, 1.0, v123
	v_rcp_f32_e32 v123, v121
	v_pk_mul_f32 v[106:107], v[66:67], v[106:107]
	v_pk_mul_f32 v[104:105], v[104:105], v[118:119]
	s_nop 0
	v_cvt_pk_bf16_f32 v118, v104, v105
	v_pk_mul_f32 v[104:105], v[106:107], v[122:123]
	s_nop 0
	v_cvt_pk_bf16_f32 v119, v104, v105
	v_mov_b64_e32 v[104:105], s[54:55]
	v_mad_i64_i32 v[104:105], s[58:59], v120, s60, v[104:105]
	v_lshl_add_u64 v[104:105], v[184:185], 1, v[104:105]
	global_store_dwordx4 v[104:105], v[116:119], off

; DI unsigned pack2(float a, float b) { f32x2 v = {a, b}; hwbf16x2 r = __builtin_convertvector(v, hwbf16x2); return __builtin_bit_cast(unsigned, r); }
; DI float dpp_ror1(float v)  { return __builtin_bit_cast(float, __builtin_amdgcn_update_dpp(0, __builtin_bit_cast(int, v), 0x121, 0xf, 0xf, false)); }
;     DI void operator()(const f32x4 (&acc)[2][2][4][2], const Unit& u, int wr, int wc, int fr, int fq) const {
;     ...
;             for (int m = 0; m < 4; ++m) {
;                 const bool efirst = (m == 0) && (fr == 0), elast = (m == 3) && (fr == 15);
;                 const int row = row0 + ai * HALF + m * 16;
;                 f32x4 gc[2];
; #pragma unroll
;                 for (int n = 0; n < 2; ++n) {
;                     const f32x4 g = acc[ai][0][m][n];
;                     const f32x4 gprev = acc[ai][0][m > 0 ? m - 1 : 0][n], gnext = acc[ai][0][m < 3 ? m + 1 : 3][n];
;                     f32x4 up, dn;
; #pragma unroll
;                     for (int e = 0; e < 4; ++e) {
;                         const float pu = (m > 0 && fr == 15) ? gprev[e] : g[e];
;                         const float pd = (m < 3 && fr == 0) ? gnext[e] : g[e];
;                         up[e] = dpp_ror1(pu); dn[e] = dpp_ror15(pd);
;                     }
;                     if (efirst) up = (f32x4){0.f, 0.f, 0.f, 0.f};
;                     if (elast) dn = (f32x4){0.f, 0.f, 0.f, 0.f};
;                     gc[n] = w0[n] * up + w1[n] * g + w2[n] * dn + bb[n];
;                 }
;                 if (efirst || elast) {
;                     const size_t eo = (size_t)((row >> 6) * 2 + (elast ? 1 : 0)) * DFF + ch0;
; #pragma unroll
;                     for (int n = 0; n < 2; ++n) { *(f32x4*)(EP + eo + 4 * n) = gc[n]; *(f32x4*)(ER + eo + 4 * n) = acc[ai][0][m][n]; *(f32x4*)(EV + eo + 4 * n) = acc[ai][1][m][n]; }
;                 } else {
;                     const f32x4 v0 = acc[ai][1][m][0], v1 = acc[ai][1][m][1];
;                     u32x4 o;
;                     o[0] = pack2(silu_mul(gc[0][0], v0[0]), silu_mul(gc[0][1], v0[1])); o[1] = pack2(silu_mul(gc[0][2], v0[2]), silu_mul(gc[0][3], v0[3]));
;                     o[2] = pack2(silu_mul(gc[1][0], v1[0]), silu_mul(gc[1][1], v1[1])); o[3] = pack2(silu_mul(gc[1][2], v1[2]), silu_mul(gc[1][3], v1[3]));
;                     *(u32x4*)(ACT + (size_t)row * DFF + ch0) = o;
;                 }
.LBB1_1078:
	s_or_b64 exec, exec, s[24:25]
	s_nop 0
	v_cndmask_b32_e32 v65, v60, v40, vcc
	v_cndmask_b32_e32 v66, v61, v41, vcc
	v_cndmask_b32_e32 v67, v62, v42, vcc
	v_mov_b32_dpp v64, v65 row_ror:15 row_mask:0xf bank_mask:0xf
	s_nop 0
	s_nop 0
	v_mov_b32_dpp v65, v66 row_ror:15 row_mask:0xf bank_mask:0xf
	s_nop 0
	v_mov_b32_dpp v68, v62 row_ror:1 row_mask:0xf bank_mask:0xf
	v_mov_b32_dpp v66, v67 row_ror:15 row_mask:0xf bank_mask:0xf
	v_cndmask_b32_e32 v69, v63, v43, vcc
	v_mov_b32_dpp v73, v63 row_ror:1 row_mask:0xf bank_mask:0xf
	v_mov_b32_dpp v70, v60 row_ror:1 row_mask:0xf bank_mask:0xf
	v_mov_b32_dpp v71, v61 row_ror:1 row_mask:0xf bank_mask:0xf
	v_mov_b32_dpp v67, v69 row_ror:15 row_mask:0xf bank_mask:0xf
	v_cndmask_b32_e64 v69, v73, 0, vcc
	v_cndmask_b32_e64 v68, v68, 0, vcc
	v_cndmask_b32_e64 v71, v71, 0, vcc
	v_cndmask_b32_e64 v70, v70, 0, vcc
	v_pk_mul_f32 v[68:69], v[98:99], v[68:69]
	v_pk_mul_f32 v[70:71], v[96:97], v[70:71]
	v_pk_fma_f32 v[68:69], v[62:63], v[102:103], v[68:69]
	v_pk_fma_f32 v[70:71], v[60:61], v[100:101], v[70:71]
	v_pk_fma_f32 v[66:67], v[110:111], v[66:67], v[68:69]
	v_cndmask_b32_e32 v69, v48, v32, vcc
	v_pk_fma_f32 v[64:65], v[108:109], v[64:65], v[70:71]
	v_cndmask_b32_e32 v70, v49, v33, vcc
	v_mov_b32_dpp v68, v69 row_ror:15 row_mask:0xf bank_mask:0xf
	s_nop 0
	s_nop 0
	v_mov_b32_dpp v69, v70 row_ror:15 row_mask:0xf bank_mask:0xf
	v_cndmask_b32_e32 v71, v50, v34, vcc
	v_mov_b32_dpp v73, v48 row_ror:1 row_mask:0xf bank_mask:0xf
	v_mov_b32_dpp v76, v49 row_ror:1 row_mask:0xf bank_mask:0xf
	v_mov_b32_dpp v74, v50 row_ror:1 row_mask:0xf bank_mask:0xf
	v_mov_b32_dpp v70, v71 row_ror:15 row_mask:0xf bank_mask:0xf
	v_cndmask_b32_e32 v75, v51, v35, vcc
	v_mov_b32_dpp v77, v51 row_ror:1 row_mask:0xf bank_mask:0xf
	v_cndmask_b32_e64 v74, v74, 0, vcc
	v_add_u32_e32 v72, 0x80, v193
	v_mov_b32_dpp v71, v75 row_ror:15 row_mask:0xf bank_mask:0xf
	v_cndmask_b32_e64 v75, v77, 0, vcc
	v_cndmask_b32_e64 v77, v76, 0, vcc
	v_cndmask_b32_e64 v76, v73, 0, vcc
	v_pk_mul_f32 v[76:77], v[80:81], v[76:77]
	v_pk_mul_f32 v[74:75], v[82:83], v[74:75]
	v_pk_fma_f32 v[76:77], v[48:49], v[84:85], v[76:77]
	v_pk_fma_f32 v[74:75], v[50:51], v[86:87], v[74:75]
	v_pk_fma_f32 v[68:69], v[88:89], v[68:69], v[76:77]
	v_pk_fma_f32 v[70:71], v[90:91], v[70:71], v[74:75]
	v_pk_add_f32 v[66:67], v[114:115], v[66:67]
	v_pk_add_f32 v[64:65], v[112:113], v[64:65]
	v_pk_add_f32 v[70:71], v[94:95], v[70:71]
	v_pk_add_f32 v[68:69], v[92:93], v[68:69]
	s_and_saveexec_b64 s[24:25], s[46:47]
	s_xor_b64 s[24:25], exec, s[24:25]
	s_cbranch_execz .LBB1_1080
	v_mul_f32_e32 v73, 0xbfb8aa3b, v64
	v_exp_f32_e32 v73, v73
	v_mul_f32_e32 v74, 0xbfb8aa3b, v65
	v_exp_f32_e32 v74, v74
	v_mul_f32_e32 v76, 0xbfb8aa3b, v67
	v_add_f32_e32 v73, 1.0, v73
	v_exp_f32_e32 v77, v76
	v_add_f32_e32 v75, 1.0, v74
	v_rcp_f32_e32 v74, v73
	v_mul_f32_e32 v73, 0xbfb8aa3b, v66
	v_exp_f32_e32 v73, v73
	v_rcp_f32_e32 v75, v75
	v_pk_mul_f32 v[64:65], v[56:57], v[64:65]
	v_pk_mul_f32 v[66:67], v[58:59], v[66:67]
	v_add_f32_e32 v73, 1.0, v73
	v_rcp_f32_e32 v76, v73
	v_add_f32_e32 v73, 1.0, v77
	v_pk_mul_f32 v[64:65], v[64:65], v[74:75]
	v_rcp_f32_e32 v77, v73
	v_cvt_pk_bf16_f32 v64, v64, v65
	v_mul_f32_e32 v65, 0xbfb8aa3b, v68
	v_exp_f32_e32 v73, v65
	v_mul_f32_e32 v65, 0xbfb8aa3b, v69
	v_exp_f32_e32 v74, v65
	v_pk_mul_f32 v[66:67], v[66:67], v[76:77]
	v_pk_mul_f32 v[68:69], v[52:53], v[68:69]
	v_cvt_pk_bf16_f32 v65, v66, v67
	v_add_f32_e32 v66, 1.0, v73
	v_mul_f32_e32 v73, 0xbfb8aa3b, v70
	v_add_f32_e32 v67, 1.0, v74
	v_exp_f32_e32 v73, v73
	v_mul_f32_e32 v74, 0xbfb8aa3b, v71
	v_exp_f32_e32 v75, v74
	v_rcp_f32_e32 v66, v66
	v_add_f32_e32 v73, 1.0, v73
	v_rcp_f32_e32 v74, v73
	v_add_f32_e32 v73, 1.0, v75
	v_rcp_f32_e32 v67, v67
	v_rcp_f32_e32 v75, v73
	v_pk_mul_f32 v[70:71], v[54:55], v[70:71]
	v_pk_mul_f32 v[66:67], v[68:69], v[66:67]
	v_pk_mul_f32 v[68:69], v[70:71], v[74:75]
	v_cvt_pk_bf16_f32 v66, v66, v67
	v_cvt_pk_bf16_f32 v67, v68, v69
	v_mov_b64_e32 v[68:69], s[54:55]
	v_mad_i64_i32 v[68:69], s[46:47], v72, s60, v[68:69]
	v_lshl_add_u64 v[68:69], v[184:185], 1, v[68:69]
	global_store_dwordx4 v[68:69], v[64:67], off

; DI unsigned pack2(float a, float b) { f32x2 v = {a, b}; hwbf16x2 r = __builtin_convertvector(v, hwbf16x2); return __builtin_bit_cast(unsigned, r); }
; DI float dpp_ror1(float v)  { return __builtin_bit_cast(float, __builtin_amdgcn_update_dpp(0, __builtin_bit_cast(int, v), 0x121, 0xf, 0xf, false)); }
;     DI void operator()(const f32x4 (&acc)[2][2][4][2], const Unit& u, int wr, int wc, int fr, int fq) const {
;     ...
;             for (int m = 0; m < 4; ++m) {
;                 const bool efirst = (m == 0) && (fr == 0), elast = (m == 3) && (fr == 15);
;                 const int row = row0 + ai * HALF + m * 16;
;                 f32x4 gc[2];
; #pragma unroll
;                 for (int n = 0; n < 2; ++n) {
;                     const f32x4 g = acc[ai][0][m][n];
;                     const f32x4 gprev = acc[ai][0][m > 0 ? m - 1 : 0][n], gnext = acc[ai][0][m < 3 ? m + 1 : 3][n];
;                     f32x4 up, dn;
; #pragma unroll
;                     for (int e = 0; e < 4; ++e) {
;                         const float pu = (m > 0 && fr == 15) ? gprev[e] : g[e];
;                         const float pd = (m < 3 && fr == 0) ? gnext[e] : g[e];
;                         up[e] = dpp_ror1(pu); dn[e] = dpp_ror15(pd);
;                     }
;                     if (efirst) up = (f32x4){0.f, 0.f, 0.f, 0.f};
;                     if (elast) dn = (f32x4){0.f, 0.f, 0.f, 0.f};
;                     gc[n] = w0[n] * up + w1[n] * g + w2[n] * dn + bb[n];
;                 }
;                 if (efirst || elast) {
;                     const size_t eo = (size_t)((row >> 6) * 2 + (elast ? 1 : 0)) * DFF + ch0;
; #pragma unroll
;                     for (int n = 0; n < 2; ++n) { *(f32x4*)(EP + eo + 4 * n) = gc[n]; *(f32x4*)(ER + eo + 4 * n) = acc[ai][0][m][n]; *(f32x4*)(EV + eo + 4 * n) = acc[ai][1][m][n]; }
;                 } else {
;                     const f32x4 v0 = acc[ai][1][m][0], v1 = acc[ai][1][m][1];
;                     u32x4 o;
;                     o[0] = pack2(silu_mul(gc[0][0], v0[0]), silu_mul(gc[0][1], v0[1])); o[1] = pack2(silu_mul(gc[0][2], v0[2]), silu_mul(gc[0][3], v0[3]));
;                     o[2] = pack2(silu_mul(gc[1][0], v1[0]), silu_mul(gc[1][1], v1[1])); o[3] = pack2(silu_mul(gc[1][2], v1[2]), silu_mul(gc[1][3], v1[3]));
;                     *(u32x4*)(ACT + (size_t)row * DFF + ch0) = o;
.LBB1_1082:
	s_or_b64 exec, exec, s[24:25]
	s_nop 0
	v_cndmask_b32_e64 v53, v40, v60, s[44:45]
	v_cndmask_b32_e32 v55, v40, v24, vcc
	s_nop 0
	v_cndmask_b32_e32 v56, v41, v25, vcc
	v_mov_b32_dpp v52, v53 row_ror:1 row_mask:0xf bank_mask:0xf
	v_mov_b32_dpp v54, v55 row_ror:15 row_mask:0xf bank_mask:0xf
	v_cndmask_b32_e64 v55, v41, v61, s[44:45]
	v_cndmask_b32_e64 v57, v42, v62, s[44:45]
	v_cndmask_b32_e32 v59, v42, v26, vcc
	v_mov_b32_dpp v53, v55 row_ror:1 row_mask:0xf bank_mask:0xf
	s_nop 0
	v_pk_mul_f32 v[52:53], v[96:97], v[52:53]
	v_mov_b32_dpp v55, v56 row_ror:15 row_mask:0xf bank_mask:0xf
	v_mov_b32_dpp v58, v59 row_ror:15 row_mask:0xf bank_mask:0xf
	v_cndmask_b32_e64 v59, v43, v63, s[44:45]
	v_mov_b32_dpp v56, v57 row_ror:1 row_mask:0xf bank_mask:0xf
	v_pk_fma_f32 v[52:53], v[40:41], v[100:101], v[52:53]
	v_cndmask_b32_e32 v60, v43, v27, vcc
	v_mov_b32_dpp v57, v59 row_ror:1 row_mask:0xf bank_mask:0xf
	v_pk_fma_f32 v[52:53], v[108:109], v[54:55], v[52:53]
	v_pk_mul_f32 v[56:57], v[98:99], v[56:57]
	v_pk_add_f32 v[52:53], v[112:113], v[52:53]
	v_mov_b32_dpp v59, v60 row_ror:15 row_mask:0xf bank_mask:0xf
	v_pk_fma_f32 v[56:57], v[42:43], v[102:103], v[56:57]
	v_mul_f32_e32 v54, 0xbfb8aa3b, v52
	v_pk_fma_f32 v[56:57], v[110:111], v[58:59], v[56:57]
	v_exp_f32_e32 v58, v54
	v_mul_f32_e32 v54, 0xbfb8aa3b, v53
	v_exp_f32_e32 v59, v54
	v_cndmask_b32_e64 v60, v32, v48, s[44:45]
	v_cndmask_b32_e32 v61, v32, v16, vcc
	v_pk_add_f32 v[54:55], v[114:115], v[56:57]
	v_mov_b32_dpp v48, v60 row_ror:1 row_mask:0xf bank_mask:0xf
	v_add_f32_e32 v56, 1.0, v58
	v_add_f32_e32 v57, 1.0, v59
	v_mov_b32_dpp v60, v61 row_ror:15 row_mask:0xf bank_mask:0xf
	v_cndmask_b32_e64 v61, v33, v49, s[44:45]
	v_rcp_f32_e32 v56, v56
	v_rcp_f32_e32 v57, v57
	v_mov_b32_dpp v49, v61 row_ror:1 row_mask:0xf bank_mask:0xf
	v_mul_f32_e32 v58, 0xbfb8aa3b, v54
	v_mul_f32_e32 v59, 0xbfb8aa3b, v55
	v_cndmask_b32_e32 v62, v33, v17, vcc
	v_pk_mul_f32 v[48:49], v[80:81], v[48:49]
	v_exp_f32_e32 v58, v58
	v_exp_f32_e32 v59, v59
	v_mov_b32_dpp v61, v62 row_ror:15 row_mask:0xf bank_mask:0xf
	v_pk_fma_f32 v[48:49], v[32:33], v[84:85], v[48:49]
	v_cndmask_b32_e64 v62, v34, v50, s[44:45]
	v_pk_fma_f32 v[48:49], v[88:89], v[60:61], v[48:49]
	v_pk_mul_f32 v[44:45], v[44:45], v[52:53]
	v_cndmask_b32_e32 v63, v34, v18, vcc
	v_mov_b32_dpp v50, v62 row_ror:1 row_mask:0xf bank_mask:0xf
	v_pk_add_f32 v[48:49], v[92:93], v[48:49]
	v_pk_mul_f32 v[44:45], v[44:45], v[56:57]
	v_mov_b32_dpp v62, v63 row_ror:15 row_mask:0xf bank_mask:0xf
	v_cndmask_b32_e64 v63, v35, v51, s[44:45]
	v_pk_mul_f32 v[46:47], v[46:47], v[54:55]
	v_add_f32_e32 v54, 1.0, v58
	v_add_f32_e32 v55, 1.0, v59
	v_cvt_pk_bf16_f32 v44, v44, v45
	v_mul_f32_e32 v45, 0xbfb8aa3b, v48
	v_mov_b32_dpp v51, v63 row_ror:1 row_mask:0xf bank_mask:0xf
	v_rcp_f32_e32 v54, v54
	v_rcp_f32_e32 v55, v55
	v_exp_f32_e32 v52, v45
	v_mul_f32_e32 v45, 0xbfb8aa3b, v49
	v_cndmask_b32_e32 v64, v35, v19, vcc
	v_pk_mul_f32 v[50:51], v[82:83], v[50:51]
	v_exp_f32_e32 v53, v45
	v_mov_b32_dpp v63, v64 row_ror:15 row_mask:0xf bank_mask:0xf
	v_pk_fma_f32 v[50:51], v[34:35], v[86:87], v[50:51]
	v_pk_mul_f32 v[46:47], v[46:47], v[54:55]
	v_pk_fma_f32 v[50:51], v[90:91], v[62:63], v[50:51]
	v_cvt_pk_bf16_f32 v45, v46, v47
	v_pk_add_f32 v[50:51], v[94:95], v[50:51]
	v_add_f32_e32 v46, 1.0, v52
	v_add_f32_e32 v47, 1.0, v53
	v_mul_f32_e32 v52, 0xbfb8aa3b, v50
	v_mul_f32_e32 v53, 0xbfb8aa3b, v51
	v_exp_f32_e32 v52, v52
	v_exp_f32_e32 v53, v53
	v_rcp_f32_e32 v46, v46
	v_rcp_f32_e32 v47, v47
	v_pk_mul_f32 v[38:39], v[38:39], v[50:51]
	v_add_f32_e32 v50, 1.0, v52
	v_add_f32_e32 v51, 1.0, v53
	v_rcp_f32_e32 v50, v50
	v_rcp_f32_e32 v51, v51
	v_pk_mul_f32 v[36:37], v[36:37], v[48:49]
	v_add_u32_e32 v64, 0x90, v193
	v_pk_mul_f32 v[36:37], v[36:37], v[46:47]
	v_cndmask_b32_e64 v41, v25, v41, s[44:45]
	v_cvt_pk_bf16_f32 v46, v36, v37
	v_pk_mul_f32 v[36:37], v[38:39], v[50:51]
	v_cndmask_b32_e32 v48, v17, v9, vcc
	v_cvt_pk_bf16_f32 v47, v36, v37
	v_mov_b64_e32 v[36:37], s[54:55]
	v_mad_i64_i32 v[38:39], s[24:25], v64, s60, v[36:37]
	v_lshl_add_u64 v[38:39], v[38:39], 0, v[132:133]
	global_store_dwordx4 v[38:39], v[44:47], off
	v_cndmask_b32_e64 v39, v24, v40, s[44:45]
	s_nop 0
	v_cndmask_b32_e32 v44, v24, v12, vcc
	s_nop 0
	v_mov_b32_dpp v38, v39 row_ror:1 row_mask:0xf bank_mask:0xf
	s_nop 0
	v_mov_b32_dpp v40, v44 row_ror:15 row_mask:0xf bank_mask:0xf
	v_cndmask_b32_e32 v44, v25, v13, vcc
	v_mov_b32_dpp v39, v41 row_ror:1 row_mask:0xf bank_mask:0xf
	v_cndmask_b32_e32 v45, v26, v14, vcc
	v_pk_mul_f32 v[38:39], v[96:97], v[38:39]
	v_mov_b32_dpp v41, v44 row_ror:15 row_mask:0xf bank_mask:0xf
	v_cndmask_b32_e64 v44, v26, v42, s[44:45]
	v_pk_fma_f32 v[38:39], v[24:25], v[100:101], v[38:39]
	v_cndmask_b32_e32 v46, v27, v15, vcc
	v_mov_b32_dpp v42, v44 row_ror:1 row_mask:0xf bank_mask:0xf
	v_pk_fma_f32 v[38:39], v[108:109], v[40:41], v[38:39]
	v_cndmask_b32_e32 v47, v16, v8, vcc
	v_mov_b32_dpp v44, v45 row_ror:15 row_mask:0xf bank_mask:0xf
	v_cndmask_b32_e64 v45, v27, v43, s[44:45]
	v_pk_add_f32 v[38:39], v[112:113], v[38:39]
	v_cndmask_b32_e32 v49, v18, v10, vcc
	v_mov_b32_dpp v43, v45 row_ror:1 row_mask:0xf bank_mask:0xf
	v_pk_mul_f32 v[42:43], v[98:99], v[42:43]
	v_mul_f32_e32 v40, 0xbfb8aa3b, v38
	v_mov_b32_dpp v45, v46 row_ror:15 row_mask:0xf bank_mask:0xf
	v_pk_fma_f32 v[42:43], v[26:27], v[102:103], v[42:43]
	v_cndmask_b32_e64 v46, v16, v32, s[44:45]
	v_pk_fma_f32 v[42:43], v[110:111], v[44:45], v[42:43]
	v_exp_f32_e32 v44, v40
	v_mul_f32_e32 v40, 0xbfb8aa3b, v39
	v_exp_f32_e32 v45, v40
	v_pk_add_f32 v[40:41], v[114:115], v[42:43]
	v_add_f32_e32 v42, 1.0, v44
; DI unsigned pack2(float a, float b) { f32x2 v = {a, b}; hwbf16x2 r = __builtin_convertvector(v, hwbf16x2); return __builtin_bit_cast(unsigned, r); }
; DI float dpp_ror1(float v)  { return __builtin_bit_cast(float, __builtin_amdgcn_update_dpp(0, __builtin_bit_cast(int, v), 0x121, 0xf, 0xf, false)); }
;     DI void operator()(const f32x4 (&acc)[2][2][4][2], const Unit& u, int wr, int wc, int fr, int fq) const {
;     ...
;             for (int m = 0; m < 4; ++m) {
;                 const bool efirst = (m == 0) && (fr == 0), elast = (m == 3) && (fr == 15);
;                 const int row = row0 + ai * HALF + m * 16;
;                 f32x4 gc[2];
; #pragma unroll
;                 for (int n = 0; n < 2; ++n) {
;                     const f32x4 g = acc[ai][0][m][n];
;                     const f32x4 gprev = acc[ai][0][m > 0 ? m - 1 : 0][n], gnext = acc[ai][0][m < 3 ? m + 1 : 3][n];
;                     f32x4 up, dn;
; #pragma unroll
;                     for (int e = 0; e < 4; ++e) {
;                         const float pu = (m > 0 && fr == 15) ? gprev[e] : g[e];
;                         const float pd = (m < 3 && fr == 0) ? gnext[e] : g[e];
;                         up[e] = dpp_ror1(pu); dn[e] = dpp_ror15(pd);
;                     }
;                     if (efirst) up = (f32x4){0.f, 0.f, 0.f, 0.f};
;                     if (elast) dn = (f32x4){0.f, 0.f, 0.f, 0.f};
;                     gc[n] = w0[n] * up + w1[n] * g + w2[n] * dn + bb[n];
;                 }
;                 if (efirst || elast) {
;                     const size_t eo = (size_t)((row >> 6) * 2 + (elast ? 1 : 0)) * DFF + ch0;
; #pragma unroll
;                     for (int n = 0; n < 2; ++n) { *(f32x4*)(EP + eo + 4 * n) = gc[n]; *(f32x4*)(ER + eo + 4 * n) = acc[ai][0][m][n]; *(f32x4*)(EV + eo + 4 * n) = acc[ai][1][m][n]; }
;                 } else {
;                     const f32x4 v0 = acc[ai][1][m][0], v1 = acc[ai][1][m][1];
;                     u32x4 o;
;                     o[0] = pack2(silu_mul(gc[0][0], v0[0]), silu_mul(gc[0][1], v0[1])); o[1] = pack2(silu_mul(gc[0][2], v0[2]), silu_mul(gc[0][3], v0[3]));
;                     o[2] = pack2(silu_mul(gc[1][0], v1[0]), silu_mul(gc[1][1], v1[1])); o[3] = pack2(silu_mul(gc[1][2], v1[2]), silu_mul(gc[1][3], v1[3]));
;                     *(u32x4*)(ACT + (size_t)row * DFF + ch0) = o;
;                 }
	v_mov_b32_dpp v32, v46 row_ror:1 row_mask:0xf bank_mask:0xf
	v_add_f32_e32 v43, 1.0, v45
	v_rcp_f32_e32 v42, v42
	v_mov_b32_dpp v46, v47 row_ror:15 row_mask:0xf bank_mask:0xf
	v_cndmask_b32_e64 v47, v17, v33, s[44:45]
	v_rcp_f32_e32 v43, v43
	v_mul_f32_e32 v44, 0xbfb8aa3b, v40
	v_mov_b32_dpp v33, v47 row_ror:1 row_mask:0xf bank_mask:0xf
	v_mul_f32_e32 v45, 0xbfb8aa3b, v41
	v_pk_mul_f32 v[32:33], v[80:81], v[32:33]
	v_exp_f32_e32 v44, v44
	v_exp_f32_e32 v45, v45
	v_mov_b32_dpp v47, v48 row_ror:15 row_mask:0xf bank_mask:0xf
	v_pk_fma_f32 v[32:33], v[16:17], v[84:85], v[32:33]
	v_cndmask_b32_e64 v48, v18, v34, s[44:45]
	v_pk_fma_f32 v[32:33], v[88:89], v[46:47], v[32:33]
	v_pk_mul_f32 v[28:29], v[28:29], v[38:39]
	v_mov_b32_dpp v34, v48 row_ror:1 row_mask:0xf bank_mask:0xf
	v_pk_add_f32 v[32:33], v[92:93], v[32:33]
	v_pk_mul_f32 v[28:29], v[28:29], v[42:43]
	v_mov_b32_dpp v48, v49 row_ror:15 row_mask:0xf bank_mask:0xf
	v_cndmask_b32_e64 v49, v19, v35, s[44:45]
	v_pk_mul_f32 v[30:31], v[30:31], v[40:41]
	v_add_f32_e32 v40, 1.0, v44
	v_add_f32_e32 v41, 1.0, v45
	v_cvt_pk_bf16_f32 v28, v28, v29
	v_mul_f32_e32 v29, 0xbfb8aa3b, v32
	v_mov_b32_dpp v35, v49 row_ror:1 row_mask:0xf bank_mask:0xf
	v_rcp_f32_e32 v40, v40
	v_rcp_f32_e32 v41, v41
	v_exp_f32_e32 v38, v29
	v_mul_f32_e32 v29, 0xbfb8aa3b, v33
	v_cndmask_b32_e32 v50, v19, v11, vcc
	v_pk_mul_f32 v[34:35], v[82:83], v[34:35]
	v_exp_f32_e32 v39, v29
	v_mov_b32_dpp v49, v50 row_ror:15 row_mask:0xf bank_mask:0xf
	v_pk_fma_f32 v[34:35], v[18:19], v[86:87], v[34:35]
	v_pk_mul_f32 v[30:31], v[30:31], v[40:41]
	v_pk_fma_f32 v[34:35], v[90:91], v[48:49], v[34:35]
	v_cvt_pk_bf16_f32 v29, v30, v31
	v_pk_add_f32 v[34:35], v[94:95], v[34:35]
	v_add_f32_e32 v30, 1.0, v38
	v_add_f32_e32 v31, 1.0, v39
	v_mul_f32_e32 v38, 0xbfb8aa3b, v34
	v_mul_f32_e32 v39, 0xbfb8aa3b, v35
	v_exp_f32_e32 v38, v38
	v_exp_f32_e32 v39, v39
	v_rcp_f32_e32 v30, v30
	v_rcp_f32_e32 v31, v31
	v_pk_mul_f32 v[22:23], v[22:23], v[34:35]
	v_add_f32_e32 v34, 1.0, v38
	v_add_f32_e32 v35, 1.0, v39
	v_rcp_f32_e32 v34, v34
	v_rcp_f32_e32 v35, v35
	v_pk_mul_f32 v[20:21], v[20:21], v[32:33]
	v_add_u32_e32 v50, 0xa0, v193
	v_pk_mul_f32 v[20:21], v[20:21], v[30:31]
	s_nop 0
	v_cvt_pk_bf16_f32 v30, v20, v21
	v_pk_mul_f32 v[20:21], v[22:23], v[34:35]
	v_cndmask_b32_e64 v22, v13, v25, s[44:45]
	v_cvt_pk_bf16_f32 v31, v20, v21
	v_mad_i64_i32 v[20:21], s[24:25], v50, s60, v[36:37]
	v_lshl_add_u64 v[20:21], v[20:21], 0, v[132:133]
	global_store_dwordx4 v[20:21], v[28:31], off
	v_cndmask_b32_e64 v21, v12, v24, s[44:45]
	v_cndmask_b32_e64 v23, v14, v26, s[44:45]
	v_cndmask_b32_e64 v25, v15, v27, s[44:45]
	v_mov_b32_dpp v20, v21 row_ror:1 row_mask:0xf bank_mask:0xf
	s_nop 0
	s_nop 0
	v_mov_b32_dpp v21, v22 row_ror:1 row_mask:0xf bank_mask:0xf
	v_mov_b32_dpp v24, v14 row_ror:15 row_mask:0xf bank_mask:0xf
	v_cndmask_b32_e64 v24, v24, 0, s[44:45]
	v_mov_b32_dpp v22, v23 row_ror:1 row_mask:0xf bank_mask:0xf
	s_nop 0
	v_mov_b32_dpp v28, v12 row_ror:15 row_mask:0xf bank_mask:0xf
	v_mov_b32_dpp v23, v25 row_ror:1 row_mask:0xf bank_mask:0xf
	v_pk_mul_f32 v[22:23], v[98:99], v[22:23]
	v_mov_b32_dpp v29, v13 row_ror:15 row_mask:0xf bank_mask:0xf
	v_mov_b32_dpp v25, v15 row_ror:15 row_mask:0xf bank_mask:0xf
	v_cndmask_b32_e64 v25, v25, 0, s[44:45]
	v_pk_fma_f32 v[22:23], v[14:15], v[102:103], v[22:23]
	v_pk_mul_f32 v[20:21], v[96:97], v[20:21]
	v_pk_fma_f32 v[22:23], v[110:111], v[24:25], v[22:23]
	v_cndmask_b32_e64 v24, v8, v16, s[44:45]
	v_cndmask_b32_e64 v27, v29, 0, s[44:45]
	v_cndmask_b32_e64 v26, v28, 0, s[44:45]
	v_mov_b32_dpp v16, v24 row_ror:1 row_mask:0xf bank_mask:0xf
	v_cndmask_b32_e64 v24, v9, v17, s[44:45]
	v_pk_fma_f32 v[20:21], v[12:13], v[100:101], v[20:21]
	v_cndmask_b32_e64 v25, v11, v19, s[44:45]
	v_mov_b32_dpp v17, v24 row_ror:1 row_mask:0xf bank_mask:0xf
	v_cndmask_b32_e64 v24, v10, v18, s[44:45]
	s_nop 0
	v_pk_fma_f32 v[20:21], v[108:109], v[26:27], v[20:21]
	v_mov_b32_dpp v18, v24 row_ror:1 row_mask:0xf bank_mask:0xf
	v_mov_b32_dpp v19, v25 row_ror:1 row_mask:0xf bank_mask:0xf
	v_mov_b32_dpp v26, v8 row_ror:15 row_mask:0xf bank_mask:0xf
	v_mov_b32_dpp v27, v9 row_ror:15 row_mask:0xf bank_mask:0xf
	v_mov_b32_dpp v24, v10 row_ror:15 row_mask:0xf bank_mask:0xf
	v_mov_b32_dpp v25, v11 row_ror:15 row_mask:0xf bank_mask:0xf
	v_pk_mul_f32 v[16:17], v[80:81], v[16:17]
	v_pk_mul_f32 v[18:19], v[82:83], v[18:19]
	v_cndmask_b32_e64 v25, v25, 0, s[44:45]
	v_cndmask_b32_e64 v24, v24, 0, s[44:45]
	v_cndmask_b32_e64 v27, v27, 0, s[44:45]
	v_cndmask_b32_e64 v26, v26, 0, s[44:45]
	v_pk_fma_f32 v[18:19], v[10:11], v[86:87], v[18:19]
	v_pk_fma_f32 v[16:17], v[8:9], v[84:85], v[16:17]
	v_pk_fma_f32 v[18:19], v[90:91], v[24:25], v[18:19]
	v_pk_fma_f32 v[16:17], v[88:89], v[26:27], v[16:17]
	v_pk_add_f32 v[22:23], v[114:115], v[22:23]
	v_pk_add_f32 v[20:21], v[112:113], v[20:21]
	v_pk_add_f32 v[18:19], v[94:95], v[18:19]
	v_pk_add_f32 v[16:17], v[92:93], v[16:17]
	v_add_u32_e32 v24, 0xb0, v193
	s_and_saveexec_b64 s[24:25], s[42:43]
	s_xor_b64 s[24:25], exec, s[24:25]
	s_cbranch_execz .LBB1_1084
	v_mul_f32_e32 v25, 0xbfb8aa3b, v20
	v_exp_f32_e32 v25, v25
	v_mul_f32_e32 v26, 0xbfb8aa3b, v21
	v_exp_f32_e32 v26, v26
	v_mul_f32_e32 v28, 0xbfb8aa3b, v23
	v_add_f32_e32 v25, 1.0, v25
	v_exp_f32_e32 v29, v28
	v_add_f32_e32 v27, 1.0, v26
	v_rcp_f32_e32 v26, v25
	v_mul_f32_e32 v25, 0xbfb8aa3b, v22
	v_exp_f32_e32 v25, v25
	v_rcp_f32_e32 v27, v27
	v_pk_mul_f32 v[20:21], v[4:5], v[20:21]
	v_pk_mul_f32 v[22:23], v[6:7], v[22:23]
	v_add_f32_e32 v25, 1.0, v25
	v_rcp_f32_e32 v28, v25
	v_add_f32_e32 v25, 1.0, v29
	v_pk_mul_f32 v[20:21], v[20:21], v[26:27]
	v_rcp_f32_e32 v29, v25
	v_cvt_pk_bf16_f32 v20, v20, v21
	v_mul_f32_e32 v21, 0xbfb8aa3b, v16
	v_exp_f32_e32 v25, v21
	v_mul_f32_e32 v21, 0xbfb8aa3b, v17
	v_exp_f32_e32 v26, v21
	v_pk_mul_f32 v[22:23], v[22:23], v[28:29]
	v_pk_mul_f32 v[16:17], v[0:1], v[16:17]
	v_cvt_pk_bf16_f32 v21, v22, v23
	v_add_f32_e32 v22, 1.0, v25
	v_mul_f32_e32 v25, 0xbfb8aa3b, v18
	v_add_f32_e32 v23, 1.0, v26
	v_exp_f32_e32 v25, v25
	v_mul_f32_e32 v26, 0xbfb8aa3b, v19
	v_exp_f32_e32 v27, v26
	v_rcp_f32_e32 v22, v22
	v_add_f32_e32 v25, 1.0, v25
	v_rcp_f32_e32 v23, v23
	v_rcp_f32_e32 v26, v25
	v_add_f32_e32 v25, 1.0, v27
	v_rcp_f32_e32 v27, v25
	v_pk_mul_f32 v[18:19], v[2:3], v[18:19]
	v_pk_mul_f32 v[16:17], v[16:17], v[22:23]
	s_nop 0
	v_cvt_pk_bf16_f32 v22, v16, v17
	v_pk_mul_f32 v[16:17], v[18:19], v[26:27]
	s_nop 0
	v_cvt_pk_bf16_f32 v23, v16, v17
	v_mov_b64_e32 v[16:17], s[54:55]
	v_mad_i64_i32 v[16:17], s[42:43], v24, s60, v[16:17]
	v_lshl_add_u64 v[16:17], v[184:185], 1, v[16:17]
	global_store_dwordx4 v[16:17], v[20:23], off

; #define PG8_STAGE(bufoff, gbase, voff) do { _Pragma("unroll") for (int _i = 0; _i < 2; ++_i) \
;         __builtin_amdgcn_global_load_lds((const unsigned*)((const char*)(gbase) + (voff)[_i]), (LAS unsigned*)(lds + (bufoff) + ldsw + _i * 8192), 16, 0, 0); } while (0)
; #define PG8_LDA(dst, b, h) do { _Pragma("unroll") for (int m = 0; m < 4; ++m) _Pragma("unroll") for (int k = 0; k < 2; ++k) dst[m][k] = *(const LAS bf16x8*)(lds + PG8_SA(b, h) + aoff + m * 2048 + k * 1024); } while (0)
; #define PG8_LDB(dst, b, h) do { _Pragma("unroll") for (int n = 0; n < 2; ++n) _Pragma("unroll") for (int k = 0; k < 2; ++k) dst[n][k] = *(const LAS bf16x8*)(lds + PG8_SB(b, h) + boff + n * 2048 + k * 1024); } while (0)
; #define PG8_MMA(ai, bj, At, Bt) do { __builtin_amdgcn_s_setprio(1); _Pragma("unroll") for (int m = 0; m < 4; ++m) _Pragma("unroll") for (int n = 0; n < 2; ++n) _Pragma("unroll") for (int k = 0; k < 2; ++k) \
;         acc[ai][bj][m][n] = __builtin_amdgcn_mfma_f32_16x16x32_bf16(Bt[n][k], At[m][k], acc[ai][bj][m][n], 0, 0, 0); __builtin_amdgcn_s_setprio(0); } while (0)
; #define PG8_WAIT_V(n) asm volatile("s_waitcnt vmcnt(" #n ")" ::: "memory")
; #define PG8_WAIT_L(n) asm volatile("s_waitcnt lgkmcnt(" #n ")" ::: "memory")
; #define PG8_BAR __builtin_amdgcn_s_barrier()
; #define PG8_SCHED __builtin_amdgcn_sched_barrier(0)
; template <class Map, class Epi>
; DI void gemm_phase(LAS unsigned char* lds, const Map& MP, const Epi& E, const int nM, const int nN, const int K, const int lda, const int ldb) {
;     ...
;             PG8_LDB(B0, 0, 0); PG8_SCHED; PG8_LDA(At, 0, 0); PG8_STAGE(PG8_SA(1, 1), a1 + hstepA, voffA);
;             PG8_WAIT_L(8); PG8_BAR; PG8_WAIT_L(0); PG8_MMA(0, 0, At, B0); PG8_BAR; PG8_SCHED;
;             PG8_LDB(B1, 0, 1); PG8_STAGE(PG8_SB(0, 0), b2, voffB);
;             PG8_BAR; PG8_WAIT_L(0); PG8_MMA(0, 1, At, B1); PG8_BAR;
;             PG8_LDA(At, 0, 1); PG8_STAGE(PG8_SA(0, 0), a2, voffA);
;             PG8_BAR; PG8_WAIT_L(0); PG8_MMA(1, 0, At, B0); PG8_BAR; PG8_SCHED;
;             PG8_STAGE(PG8_SB(0, 1), b2 + hstepB, voffB);
;             PG8_WAIT_V(6); PG8_BAR; PG8_MMA(1, 1, At, B1); PG8_BAR;
.LBB1_1908:
	s_add_u32 s28, s42, 0xfff80080
	s_addc_u32 s29, s43, -1
	s_cmp_eq_u32 s3, 28
	s_cselect_b32 s47, s23, s29
	s_cselect_b32 s46, s58, s28
	s_cselect_b32 s29, s21, vcc_hi
	s_cselect_b32 s28, s59, vcc_lo
	s_add_i32 m0, s38, 0xc000
	ds_read_b128 v[96:99], v190
	ds_read_b128 v[100:103], v190 offset:1024
	ds_read_b128 v[108:111], v190 offset:2048
	ds_read_b128 v[112:115], v190 offset:3072
	ds_read_b128 v[160:163], v190 offset:4096
	ds_read_b128 v[164:167], v190 offset:5120
	ds_read_b128 v[198:201], v190 offset:6144
	ds_read_b128 v[202:205], v190 offset:7168
	global_load_lds_dwordx4 v178, s[42:43]
	s_add_i32 m0, s38, 0xe000
	s_nop 0
	global_load_lds_dwordx4 v176, s[42:43]
	s_waitcnt lgkmcnt(8)
	s_setprio 1
	s_barrier
	s_waitcnt lgkmcnt(7)
	v_mfma_f32_16x16x32_bf16 v[148:151], v[80:83], v[96:99], v[148:151]
	v_mfma_f32_16x16x32_bf16 v[144:147], v[88:91], v[96:99], v[144:147]
	s_waitcnt lgkmcnt(5)
	v_mfma_f32_16x16x32_bf16 v[136:139], v[80:83], v[108:111], v[136:139]
	v_mfma_f32_16x16x32_bf16 v[128:131], v[88:91], v[108:111], v[128:131]
	s_waitcnt lgkmcnt(3)
	v_mfma_f32_16x16x32_bf16 v[120:123], v[80:83], v[160:163], v[120:123]
	v_mfma_f32_16x16x32_bf16 v[104:107], v[88:91], v[160:163], v[104:107]
	s_waitcnt lgkmcnt(1)
	v_mfma_f32_16x16x32_bf16 v[76:79], v[80:83], v[198:201], v[76:79]
	v_mfma_f32_16x16x32_bf16 v[72:75], v[88:91], v[198:201], v[72:75]
	v_mfma_f32_16x16x32_bf16 v[148:151], v[84:87], v[100:103], v[148:151]
	v_mfma_f32_16x16x32_bf16 v[144:147], v[92:95], v[100:103], v[144:147]
	v_mfma_f32_16x16x32_bf16 v[136:139], v[84:87], v[112:115], v[136:139]
	v_mfma_f32_16x16x32_bf16 v[128:131], v[92:95], v[112:115], v[128:131]
	v_mfma_f32_16x16x32_bf16 v[120:123], v[84:87], v[164:167], v[120:123]
	v_mfma_f32_16x16x32_bf16 v[104:107], v[92:95], v[164:167], v[104:107]
	s_waitcnt lgkmcnt(0)
	v_mfma_f32_16x16x32_bf16 v[76:79], v[84:87], v[202:205], v[76:79]
	v_mfma_f32_16x16x32_bf16 v[72:75], v[92:95], v[202:205], v[72:75]
	s_barrier
	s_setprio 0
	s_add_i32 s68, s2, s54
	v_lshl_add_u64 v[184:185], s[28:29], 0, v[172:173]
	s_mov_b32 m0, s68
	ds_read_b128 v[206:209], v191
	ds_read_b128 v[210:213], v191 offset:1024
	ds_read_b128 v[214:217], v191 offset:2048
	ds_read_b128 v[218:221], v191 offset:3072
	global_load_lds_dwordx4 v[184:185], off
	v_lshl_add_u64 v[194:195], s[28:29], 0, v[168:169]
	s_add_i32 m0, s68, 0x2000
	s_nop 0
	global_load_lds_dwordx4 v[194:195], off
	s_setprio 1
	s_barrier
	s_waitcnt lgkmcnt(3)
	v_mfma_f32_16x16x32_bf16 v[156:159], v[206:209], v[96:99], v[156:159]
	s_waitcnt lgkmcnt(1)
	v_mfma_f32_16x16x32_bf16 v[96:99], v[214:217], v[96:99], v[152:155]
	v_mfma_f32_16x16x32_bf16 v[156:159], v[210:213], v[100:103], v[156:159]
	s_waitcnt lgkmcnt(0)
	v_mfma_f32_16x16x32_bf16 v[96:99], v[218:221], v[100:103], v[96:99]
	v_mfma_f32_16x16x32_bf16 v[100:103], v[206:209], v[108:111], v[140:143]
	v_mfma_f32_16x16x32_bf16 v[108:111], v[214:217], v[108:111], v[132:135]
	v_mfma_f32_16x16x32_bf16 v[116:119], v[214:217], v[160:163], v[116:119]
	v_mfma_f32_16x16x32_bf16 v[68:71], v[206:209], v[198:201], v[68:71]
	v_mfma_f32_16x16x32_bf16 v[64:67], v[214:217], v[198:201], v[64:67]
	s_mov_b32 m0, s38
	v_mfma_f32_16x16x32_bf16 v[100:103], v[210:213], v[112:115], v[100:103]
	v_lshl_add_u64 v[226:227], s[46:47], 0, v[174:175]
	v_mfma_f32_16x16x32_bf16 v[108:111], v[218:221], v[112:115], v[108:111]
	v_mfma_f32_16x16x32_bf16 v[112:115], v[206:209], v[160:163], v[124:127]
	v_mfma_f32_16x16x32_bf16 v[116:119], v[218:221], v[164:167], v[116:119]
	v_mfma_f32_16x16x32_bf16 v[68:71], v[210:213], v[202:205], v[68:71]
	v_mfma_f32_16x16x32_bf16 v[64:67], v[218:221], v[202:205], v[64:67]
	v_mfma_f32_16x16x32_bf16 v[112:115], v[210:213], v[164:167], v[112:115]
	s_barrier
	s_setprio 0
	ds_read_b128 v[124:127], v190 offset:16384
	ds_read_b128 v[132:135], v190 offset:17408
	ds_read_b128 v[140:143], v190 offset:18432
	ds_read_b128 v[152:155], v190 offset:19456
	ds_read_b128 v[160:163], v190 offset:20480
	ds_read_b128 v[164:167], v190 offset:21504
	ds_read_b128 v[198:201], v190 offset:22528
	ds_read_b128 v[202:205], v190 offset:23552
	global_load_lds_dwordx4 v[226:227], off
	v_lshl_add_u64 v[234:235], s[46:47], 0, v[170:171]
	s_mov_b32 m0, s39
	s_nop 0
	global_load_lds_dwordx4 v[234:235], off
	s_waitcnt vmcnt(10)
	s_setprio 1
	s_barrier
	s_waitcnt lgkmcnt(7)
	v_mfma_f32_16x16x32_bf16 v[60:63], v[80:83], v[124:127], v[60:63]
	v_mfma_f32_16x16x32_bf16 v[48:51], v[88:91], v[124:127], v[48:51]
	s_waitcnt lgkmcnt(5)
	v_mfma_f32_16x16x32_bf16 v[40:43], v[80:83], v[140:143], v[40:43]
	v_mfma_f32_16x16x32_bf16 v[32:35], v[88:91], v[140:143], v[32:35]
	s_waitcnt lgkmcnt(3)
	v_mfma_f32_16x16x32_bf16 v[24:27], v[80:83], v[160:163], v[24:27]
	v_mfma_f32_16x16x32_bf16 v[16:19], v[88:91], v[160:163], v[16:19]
	s_waitcnt lgkmcnt(1)
	v_mfma_f32_16x16x32_bf16 v[12:15], v[80:83], v[198:201], v[12:15]
	v_mfma_f32_16x16x32_bf16 v[8:11], v[88:91], v[198:201], v[8:11]
	v_mfma_f32_16x16x32_bf16 v[60:63], v[84:87], v[132:135], v[60:63]
	v_mfma_f32_16x16x32_bf16 v[48:51], v[92:95], v[132:135], v[48:51]
	v_mfma_f32_16x16x32_bf16 v[40:43], v[84:87], v[152:155], v[40:43]
	v_mfma_f32_16x16x32_bf16 v[32:35], v[92:95], v[152:155], v[32:35]
	v_mfma_f32_16x16x32_bf16 v[24:27], v[84:87], v[164:167], v[24:27]
	v_mfma_f32_16x16x32_bf16 v[16:19], v[92:95], v[164:167], v[16:19]
	s_waitcnt lgkmcnt(0)
	v_mfma_f32_16x16x32_bf16 v[12:15], v[84:87], v[202:205], v[12:15]
	v_mfma_f32_16x16x32_bf16 v[8:11], v[92:95], v[202:205], v[8:11]
	s_barrier
	s_setprio 0
	s_add_u32 s68, s28, 0x80000
	s_addc_u32 s69, s29, 0
	s_add_i32 s70, s31, s54
	s_mov_b32 m0, s70
	s_nop 0
	global_load_lds_dwordx4 v172, s[68:69]
	s_add_i32 m0, s70, 0x2000
	s_nop 0
	global_load_lds_dwordx4 v168, s[68:69]
	s_waitcnt vmcnt(6)
	s_setprio 1
	s_barrier
; #define PG8_STAGE(bufoff, gbase, voff) do { _Pragma("unroll") for (int _i = 0; _i < 2; ++_i) \
;         __builtin_amdgcn_global_load_lds((const unsigned*)((const char*)(gbase) + (voff)[_i]), (LAS unsigned*)(lds + (bufoff) + ldsw + _i * 8192), 16, 0, 0); } while (0)
; #define PG8_LDA(dst, b, h) do { _Pragma("unroll") for (int m = 0; m < 4; ++m) _Pragma("unroll") for (int k = 0; k < 2; ++k) dst[m][k] = *(const LAS bf16x8*)(lds + PG8_SA(b, h) + aoff + m * 2048 + k * 1024); } while (0)
; #define PG8_LDB(dst, b, h) do { _Pragma("unroll") for (int n = 0; n < 2; ++n) _Pragma("unroll") for (int k = 0; k < 2; ++k) dst[n][k] = *(const LAS bf16x8*)(lds + PG8_SB(b, h) + boff + n * 2048 + k * 1024); } while (0)
; #define PG8_MMA(ai, bj, At, Bt) do { __builtin_amdgcn_s_setprio(1); _Pragma("unroll") for (int m = 0; m < 4; ++m) _Pragma("unroll") for (int n = 0; n < 2; ++n) _Pragma("unroll") for (int k = 0; k < 2; ++k) \
;         acc[ai][bj][m][n] = __builtin_amdgcn_mfma_f32_16x16x32_bf16(Bt[n][k], At[m][k], acc[ai][bj][m][n], 0, 0, 0); __builtin_amdgcn_s_setprio(0); } while (0)
; #define PG8_WAIT_V(n) asm volatile("s_waitcnt vmcnt(" #n ")" ::: "memory")
; #define PG8_WAIT_L(n) asm volatile("s_waitcnt lgkmcnt(" #n ")" ::: "memory")
; #define PG8_BAR __builtin_amdgcn_s_barrier()
; #define PG8_SCHED __builtin_amdgcn_sched_barrier(0)
; template <class Map, class Epi>
; DI void gemm_phase(LAS unsigned char* lds, const Map& MP, const Epi& E, const int nM, const int nN, const int K, const int lda, const int ldb) {
;     ...
;             PG8_WAIT_V(6); PG8_BAR; PG8_MMA(1, 1, At, B1); PG8_BAR;
;             PG8_LDB(B0, 1, 0); PG8_SCHED; PG8_LDA(At, 1, 0); PG8_STAGE(PG8_SA(0, 1), a2 + hstepA, voffA);
;             PG8_WAIT_L(8); PG8_BAR; PG8_WAIT_L(0); PG8_MMA(0, 0, At, B0); PG8_BAR; PG8_SCHED;
;             PG8_LDB(B1, 1, 1); PG8_STAGE(PG8_SB(1, 0), b3, voffB);
;             PG8_BAR; PG8_WAIT_L(0); PG8_MMA(0, 1, At, B1); PG8_BAR;
;             PG8_LDA(At, 1, 1); PG8_STAGE(PG8_SA(1, 0), a3, voffA);
;             PG8_BAR; PG8_WAIT_L(0); PG8_MMA(1, 0, At, B0); PG8_BAR; PG8_SCHED;
	v_mfma_f32_16x16x32_bf16 v[56:59], v[206:209], v[124:127], v[56:59]
	v_mfma_f32_16x16x32_bf16 v[52:55], v[214:217], v[124:127], v[52:55]
	s_add_i32 s68, 0, 0x18000
	v_add_u32_e32 v92, s68, v188
	ds_read_b128 v[80:83], v92
	v_mfma_f32_16x16x32_bf16 v[44:47], v[206:209], v[140:143], v[44:47]
	v_mfma_f32_16x16x32_bf16 v[36:39], v[214:217], v[140:143], v[36:39]
	ds_read_b128 v[84:87], v92 offset:1024
	v_mfma_f32_16x16x32_bf16 v[28:31], v[206:209], v[160:163], v[28:31]
	v_mfma_f32_16x16x32_bf16 v[20:23], v[214:217], v[160:163], v[20:23]
	ds_read_b128 v[88:91], v92 offset:2048
	v_mfma_f32_16x16x32_bf16 v[4:7], v[206:209], v[198:201], v[4:7]
	v_mfma_f32_16x16x32_bf16 v[0:3], v[214:217], v[198:201], v[0:3]
	ds_read_b128 v[92:95], v92 offset:3072
	v_mfma_f32_16x16x32_bf16 v[56:59], v[210:213], v[132:135], v[56:59]
	v_mfma_f32_16x16x32_bf16 v[52:55], v[218:221], v[132:135], v[52:55]
	v_mfma_f32_16x16x32_bf16 v[44:47], v[210:213], v[152:155], v[44:47]
	v_mfma_f32_16x16x32_bf16 v[36:39], v[218:221], v[152:155], v[36:39]
	v_mfma_f32_16x16x32_bf16 v[28:31], v[210:213], v[164:167], v[28:31]
	v_mfma_f32_16x16x32_bf16 v[20:23], v[218:221], v[164:167], v[20:23]
	v_mfma_f32_16x16x32_bf16 v[4:7], v[210:213], v[202:205], v[4:7]
	v_mfma_f32_16x16x32_bf16 v[0:3], v[218:221], v[202:205], v[0:3]
	s_barrier
	s_setprio 0
	s_add_u32 s46, s46, 0x80000
	s_addc_u32 s47, s47, 0
	s_mov_b32 m0, s56
	ds_read_b128 v[124:127], v190 offset:32768
	ds_read_b128 v[132:135], v190 offset:33792
	ds_read_b128 v[160:163], v190 offset:34816
	ds_read_b128 v[164:167], v190 offset:35840
	ds_read_b128 v[198:201], v190 offset:36864
	ds_read_b128 v[202:205], v190 offset:37888
	ds_read_b128 v[206:209], v190 offset:38912
	ds_read_b128 v[210:213], v190 offset:39936
	global_load_lds_dwordx4 v174, s[46:47]
	s_mov_b32 m0, s57
	s_nop 0
	global_load_lds_dwordx4 v170, s[46:47]
	s_waitcnt lgkmcnt(8)
	s_setprio 1
	s_barrier
	s_waitcnt lgkmcnt(7)
	v_mfma_f32_16x16x32_bf16 v[140:143], v[80:83], v[124:127], v[148:151]
	s_waitcnt lgkmcnt(6)
	v_mfma_f32_16x16x32_bf16 v[148:151], v[84:87], v[132:135], v[140:143]
	v_mfma_f32_16x16x32_bf16 v[140:143], v[88:91], v[124:127], v[144:147]
	s_waitcnt lgkmcnt(5)
	v_mfma_f32_16x16x32_bf16 v[136:139], v[80:83], v[160:163], v[136:139]
	v_mfma_f32_16x16x32_bf16 v[128:131], v[88:91], v[160:163], v[128:131]
	s_waitcnt lgkmcnt(3)
	v_mfma_f32_16x16x32_bf16 v[120:123], v[80:83], v[198:201], v[120:123]
	v_mfma_f32_16x16x32_bf16 v[104:107], v[88:91], v[198:201], v[104:107]
	s_waitcnt lgkmcnt(1)
	v_mfma_f32_16x16x32_bf16 v[76:79], v[80:83], v[206:209], v[76:79]
	v_mfma_f32_16x16x32_bf16 v[72:75], v[88:91], v[206:209], v[72:75]
	v_mfma_f32_16x16x32_bf16 v[144:147], v[92:95], v[132:135], v[140:143]
	v_mfma_f32_16x16x32_bf16 v[136:139], v[84:87], v[164:167], v[136:139]
	v_mfma_f32_16x16x32_bf16 v[128:131], v[92:95], v[164:167], v[128:131]
	v_mfma_f32_16x16x32_bf16 v[120:123], v[84:87], v[202:205], v[120:123]
	v_mfma_f32_16x16x32_bf16 v[104:107], v[92:95], v[202:205], v[104:107]
	s_waitcnt lgkmcnt(0)
	v_mfma_f32_16x16x32_bf16 v[76:79], v[84:87], v[210:213], v[76:79]
	v_mfma_f32_16x16x32_bf16 v[72:75], v[92:95], v[210:213], v[72:75]
	s_barrier
	s_setprio 0
	s_add_i32 s46, 0, 0x1c000
	v_add_u32_e32 v140, s46, v188
	s_add_i32 s47, s68, s54
	ds_read_b128 v[214:217], v140
	ds_read_b128 v[218:221], v140 offset:1024
	ds_read_b128 v[222:225], v140 offset:2048
	ds_read_b128 v[230:233], v140 offset:3072
	v_lshl_add_u64 v[140:141], v[184:185], 0, s[14:15]
	s_mov_b32 m0, s47
	s_nop 0
	global_load_lds_dwordx4 v[140:141], off
	v_lshl_add_u64 v[140:141], v[194:195], 0, s[14:15]
	s_add_i32 m0, s47, 0x2000
	s_nop 0
	global_load_lds_dwordx4 v[140:141], off
	s_setprio 1
	s_barrier
	s_waitcnt lgkmcnt(1)
	v_mfma_f32_16x16x32_bf16 v[96:99], v[222:225], v[124:127], v[96:99]
	v_mfma_f32_16x16x32_bf16 v[140:143], v[214:217], v[124:127], v[156:159]
	s_waitcnt lgkmcnt(0)
	v_mfma_f32_16x16x32_bf16 v[152:155], v[230:233], v[132:135], v[96:99]
	v_mfma_f32_16x16x32_bf16 v[96:99], v[214:217], v[160:163], v[100:103]
	v_mfma_f32_16x16x32_bf16 v[156:159], v[218:221], v[132:135], v[140:143]
	v_mfma_f32_16x16x32_bf16 v[140:143], v[218:221], v[164:167], v[96:99]
	v_mfma_f32_16x16x32_bf16 v[96:99], v[222:225], v[160:163], v[108:111]
	v_mfma_f32_16x16x32_bf16 v[132:135], v[230:233], v[164:167], v[96:99]
	v_mfma_f32_16x16x32_bf16 v[96:99], v[214:217], v[198:201], v[112:115]
	s_mov_b32 m0, s63
	v_mfma_f32_16x16x32_bf16 v[124:127], v[218:221], v[202:205], v[96:99]
	v_lshl_add_u64 v[184:185], v[226:227], 0, s[14:15]
	v_mfma_f32_16x16x32_bf16 v[96:99], v[222:225], v[198:201], v[116:119]
	v_mfma_f32_16x16x32_bf16 v[68:71], v[214:217], v[206:209], v[68:71]
	v_mfma_f32_16x16x32_bf16 v[64:67], v[222:225], v[206:209], v[64:67]
	v_mfma_f32_16x16x32_bf16 v[116:119], v[230:233], v[202:205], v[96:99]
	v_mfma_f32_16x16x32_bf16 v[68:71], v[218:221], v[210:213], v[68:71]
	v_mfma_f32_16x16x32_bf16 v[64:67], v[230:233], v[210:213], v[64:67]
	s_barrier
	s_setprio 0
	ds_read_b128 v[96:99], v190 offset:49152
	ds_read_b128 v[100:103], v190 offset:50176
	ds_read_b128 v[108:111], v190 offset:51200
	ds_read_b128 v[112:115], v190 offset:52224
	ds_read_b128 v[160:163], v190 offset:53248
	ds_read_b128 v[164:167], v190 offset:54272
	ds_read_b128 v[198:201], v190 offset:55296
	ds_read_b128 v[202:205], v190 offset:56320
	global_load_lds_dwordx4 v[184:185], off
	v_lshl_add_u64 v[184:185], v[234:235], 0, s[14:15]
	s_mov_b32 m0, s66
	s_nop 0
	global_load_lds_dwordx4 v[184:185], off
	s_waitcnt vmcnt(10)
	s_setprio 1
	s_barrier
; #define PG8_STAGE(bufoff, gbase, voff) do { _Pragma("unroll") for (int _i = 0; _i < 2; ++_i) \
;         __builtin_amdgcn_global_load_lds((const unsigned*)((const char*)(gbase) + (voff)[_i]), (LAS unsigned*)(lds + (bufoff) + ldsw + _i * 8192), 16, 0, 0); } while (0)
; #define PG8_LDA(dst, b, h) do { _Pragma("unroll") for (int m = 0; m < 4; ++m) _Pragma("unroll") for (int k = 0; k < 2; ++k) dst[m][k] = *(const LAS bf16x8*)(lds + PG8_SA(b, h) + aoff + m * 2048 + k * 1024); } while (0)
; #define PG8_LDB(dst, b, h) do { _Pragma("unroll") for (int n = 0; n < 2; ++n) _Pragma("unroll") for (int k = 0; k < 2; ++k) dst[n][k] = *(const LAS bf16x8*)(lds + PG8_SB(b, h) + boff + n * 2048 + k * 1024); } while (0)
; #define PG8_WAIT_V(n) asm volatile("s_waitcnt vmcnt(" #n ")" ::: "memory")
; #define PG8_WAIT_L(n) asm volatile("s_waitcnt lgkmcnt(" #n ")" ::: "memory")
; #define PG8_BAR __builtin_amdgcn_s_barrier()
; #define PG8_SCHED __builtin_amdgcn_sched_barrier(0)
; template <class Map, class Epi>
; DI void gemm_phase(LAS unsigned char* lds, const Map& MP, const Epi& E, const int nM, const int nN, const int K, const int lda, const int ldb) {
;     ...
;             PG8_LDB(B0, 0, 0); PG8_SCHED; PG8_LDA(At, 0, 0); PG8_STAGE(PG8_SA(1, 1), a1 + hstepA, voffA);
;             PG8_WAIT_L(8); PG8_BAR; PG8_WAIT_L(0); PG8_MMA(0, 0, At, B0); PG8_BAR; PG8_SCHED;
;             PG8_LDB(B1, 0, 1); PG8_STAGE(PG8_SB(0, 0), b2, voffB);
;             PG8_BAR; PG8_WAIT_L(0); PG8_MMA(0, 1, At, B1); PG8_BAR;
;             PG8_LDA(At, 0, 1); PG8_STAGE(PG8_SA(0, 0), a2, voffA);
;             PG8_BAR; PG8_WAIT_L(0); PG8_MMA(1, 0, At, B0); PG8_BAR; PG8_SCHED;
;             PG8_STAGE(PG8_SB(0, 1), b2 + hstepB, voffB);
;             PG8_WAIT_V(6); PG8_BAR; PG8_MMA(1, 1, At, B1); PG8_BAR;
;             PG8_LDB(B0, 1, 0); PG8_SCHED; PG8_LDA(At, 1, 0); PG8_STAGE(PG8_SA(0, 1), a2 + hstepA, voffA);
;             PG8_WAIT_L(8); PG8_BAR; PG8_WAIT_L(0); PG8_MMA(0, 0, At, B0); PG8_BAR; PG8_SCHED;
;             PG8_LDB(B1, 1, 1); PG8_STAGE(PG8_SB(1, 0), b3, voffB);
;             PG8_BAR; PG8_WAIT_L(0); PG8_MMA(0, 1, At, B1); PG8_BAR;
;             PG8_LDA(At, 1, 1); PG8_STAGE(PG8_SA(1, 0), a3, voffA);
;             PG8_BAR; PG8_WAIT_L(0); PG8_MMA(1, 0, At, B0); PG8_BAR; PG8_SCHED;
;             PG8_STAGE(PG8_SB(1, 1), b3 + hstepB, voffB);
;             PG8_WAIT_V(6); PG8_BAR; PG8_MMA(1, 1, At, B1); PG8_BAR;
	s_waitcnt lgkmcnt(7)
	v_mfma_f32_16x16x32_bf16 v[60:63], v[80:83], v[96:99], v[60:63]
	v_mfma_f32_16x16x32_bf16 v[48:51], v[88:91], v[96:99], v[48:51]
	s_waitcnt lgkmcnt(5)
	v_mfma_f32_16x16x32_bf16 v[40:43], v[80:83], v[108:111], v[40:43]
	v_mfma_f32_16x16x32_bf16 v[32:35], v[88:91], v[108:111], v[32:35]
	s_waitcnt lgkmcnt(3)
	v_mfma_f32_16x16x32_bf16 v[24:27], v[80:83], v[160:163], v[24:27]
	v_mfma_f32_16x16x32_bf16 v[16:19], v[88:91], v[160:163], v[16:19]
	s_waitcnt lgkmcnt(1)
	v_mfma_f32_16x16x32_bf16 v[12:15], v[80:83], v[198:201], v[12:15]
	v_mfma_f32_16x16x32_bf16 v[8:11], v[88:91], v[198:201], v[8:11]
	v_mfma_f32_16x16x32_bf16 v[60:63], v[84:87], v[100:103], v[60:63]
	v_mfma_f32_16x16x32_bf16 v[48:51], v[92:95], v[100:103], v[48:51]
	v_mfma_f32_16x16x32_bf16 v[40:43], v[84:87], v[112:115], v[40:43]
	v_mfma_f32_16x16x32_bf16 v[32:35], v[92:95], v[112:115], v[32:35]
	v_mfma_f32_16x16x32_bf16 v[24:27], v[84:87], v[164:167], v[24:27]
	v_mfma_f32_16x16x32_bf16 v[16:19], v[92:95], v[164:167], v[16:19]
	s_waitcnt lgkmcnt(0)
	v_mfma_f32_16x16x32_bf16 v[12:15], v[84:87], v[202:205], v[12:15]
	v_mfma_f32_16x16x32_bf16 v[8:11], v[92:95], v[202:205], v[8:11]
	s_barrier
	s_setprio 0
	s_add_u32 s28, s28, 0x80080
	s_addc_u32 s29, s29, 0
	s_add_i32 s46, s46, s54
	s_mov_b32 m0, s46
	s_nop 0
	global_load_lds_dwordx4 v172, s[28:29]
	s_add_i32 m0, s46, 0x2000
	s_nop 0
	global_load_lds_dwordx4 v168, s[28:29]
	s_waitcnt vmcnt(6)
	s_setprio 1
	s_barrier
	v_mfma_f32_16x16x32_bf16 v[56:59], v[214:217], v[96:99], v[56:59]
	v_mfma_f32_16x16x32_bf16 v[52:55], v[222:225], v[96:99], v[52:55]
	ds_read_b128 v[80:83], v189
	v_mfma_f32_16x16x32_bf16 v[44:47], v[214:217], v[108:111], v[44:47]
	v_mfma_f32_16x16x32_bf16 v[36:39], v[222:225], v[108:111], v[36:39]
	ds_read_b128 v[84:87], v189 offset:1024
	v_mfma_f32_16x16x32_bf16 v[28:31], v[214:217], v[160:163], v[28:31]
	v_mfma_f32_16x16x32_bf16 v[20:23], v[222:225], v[160:163], v[20:23]
	ds_read_b128 v[88:91], v189 offset:2048
	v_mfma_f32_16x16x32_bf16 v[4:7], v[214:217], v[198:201], v[4:7]
	v_mfma_f32_16x16x32_bf16 v[0:3], v[222:225], v[198:201], v[0:3]
	ds_read_b128 v[92:95], v189 offset:3072
	v_mfma_f32_16x16x32_bf16 v[56:59], v[218:221], v[100:103], v[56:59]
	s_add_i32 s3, s3, 2
	v_mfma_f32_16x16x32_bf16 v[52:55], v[230:233], v[100:103], v[52:55]
	s_add_u32 vcc_lo, vcc_lo, 0x100
	s_addc_u32 vcc_hi, vcc_hi, 0
	v_mfma_f32_16x16x32_bf16 v[44:47], v[218:221], v[112:115], v[44:47]
	s_add_u32 s42, s42, 0x100
	s_addc_u32 s43, s43, 0
	v_mfma_f32_16x16x32_bf16 v[36:39], v[230:233], v[112:115], v[36:39]
	s_cmp_gt_u32 s3, 29
	v_mfma_f32_16x16x32_bf16 v[28:31], v[218:221], v[164:167], v[28:31]
	v_mfma_f32_16x16x32_bf16 v[20:23], v[230:233], v[164:167], v[20:23]
	v_mfma_f32_16x16x32_bf16 v[4:7], v[218:221], v[202:205], v[4:7]
	v_mfma_f32_16x16x32_bf16 v[0:3], v[230:233], v[202:205], v[0:3]
	s_barrier
	s_setprio 0
	s_cbranch_scc0 .LBB1_1908
; DI float silu_mul(float g, float v) { return g * v * __builtin_amdgcn_rcpf(1.0f + __builtin_amdgcn_exp2f(-LOG2E * g)); }
;     DI void operator()(const f32x4 (&acc)[2][2][4][2], const Unit& u, int wr, int wc, int fr, int fq) const {
;         const int row0 = u.pm * BM + wr * 64 + fr, ch0 = u.pn * 128 + wc * 32 + 8 * fq;
;         f32x4 w0[2], w1[2], w2[2], bb[2];
; #pragma unroll
;         for (int n = 0; n < 2; ++n) { w0[n] = *(const f32x4*)(cw + ch0 + 4 * n); w1[n] = *(const f32x4*)(cw + DFF + ch0 + 4 * n); w2[n] = *(const f32x4*)(cw + 2 * DFF + ch0 + 4 * n); bb[n] = *(const f32x4*)(cb + ch0 + 4 * n); }
; #pragma unroll
;         for (int ai = 0; ai < 2; ++ai)
; #pragma unroll
;             for (int m = 0; m < 4; ++m) {
;                 const bool efirst = (m == 0) && (fr == 0), elast = (m == 3) && (fr == 15);
;                 const int row = row0 + ai * HALF + m * 16;
;                 f32x4 gc[2];
; #pragma unroll
;                 for (int n = 0; n < 2; ++n) {
;                     const f32x4 g = acc[ai][0][m][n];
;                     const f32x4 gprev = acc[ai][0][m > 0 ? m - 1 : 0][n], gnext = acc[ai][0][m < 3 ? m + 1 : 3][n];
;                     f32x4 up, dn;
; #pragma unroll
;                     for (int e = 0; e < 4; ++e) {
;                         const float pu = (m > 0 && fr == 15) ? gprev[e] : g[e];
;                         const float pd = (m < 3 && fr == 0) ? gnext[e] : g[e];
;                         up[e] = dpp_ror1(pu); dn[e] = dpp_ror15(pd);
;                     }
;                     if (efirst) up = (f32x4){0.f, 0.f, 0.f, 0.f};
;                     if (elast) dn = (f32x4){0.f, 0.f, 0.f, 0.f};
;                     gc[n] = w0[n] * up + w1[n] * g + w2[n] * dn + bb[n];
;                 }
;                 if (efirst || elast) {
;                     const size_t eo = (size_t)((row >> 6) * 2 + (elast ? 1 : 0)) * DFF + ch0;
; #pragma unroll
;                     for (int n = 0; n < 2; ++n) { *(f32x4*)(EP + eo + 4 * n) = gc[n]; *(f32x4*)(ER + eo + 4 * n) = acc[ai][0][m][n]; *(f32x4*)(EV + eo + 4 * n) = acc[ai][1][m][n]; }
;                 } else {
;                     const f32x4 v0 = acc[ai][1][m][0], v1 = acc[ai][1][m][1];
;                     u32x4 o;
;                     o[0] = pack2(silu_mul(gc[0][0], v0[0]), silu_mul(gc[0][1], v0[1])); o[1] = pack2(silu_mul(gc[0][2], v0[2]), silu_mul(gc[0][3], v0[3]));
	s_waitcnt lgkmcnt(0)
	s_lshl_b32 s21, s45, 7
	v_mov_b32_e32 v194, v186
	v_mov_b32_e32 v80, v187
	s_or_b32 s21, s21, s62
	v_lshl_add_u32 v184, v80, 3, s21
	v_ashrrev_i32_e32 v185, 31, v184
	v_lshlrev_b64 v[80:81], 2, v[184:185]
	v_lshl_add_u64 v[84:85], s[4:5], 0, v[80:81]
	v_lshl_add_u64 v[88:89], s[16:17], 0, v[80:81]
	v_lshl_add_u64 v[92:93], s[18:19], 0, v[80:81]
	v_lshl_add_u64 v[112:113], s[6:7], 0, v[80:81]
	global_load_dwordx4 v[80:83], v[84:85], off offset:16
	global_load_dwordx4 v[96:99], v[84:85], off
	s_nop 0
	global_load_dwordx4 v[84:87], v[88:89], off offset:16
	global_load_dwordx4 v[100:103], v[88:89], off
	s_nop 0
	global_load_dwordx4 v[88:91], v[92:93], off offset:16
	global_load_dwordx4 v[108:111], v[92:93], off
	s_nop 0
	global_load_dwordx4 v[92:95], v[112:113], off offset:16
	s_nop 0
	global_load_dwordx4 v[112:115], v[112:113], off
	v_cmp_eq_u32_e32 vcc, 0, v194
	s_nop 0
	s_nop 0
	v_cndmask_b32_e32 v161, v148, v136, vcc
	v_cndmask_b32_e32 v162, v149, v137, vcc
	v_cndmask_b32_e32 v163, v150, v138, vcc
	v_mov_b32_dpp v160, v161 row_ror:15 row_mask:0xf bank_mask:0xf
	s_nop 0
	s_nop 0
	v_mov_b32_dpp v161, v162 row_ror:15 row_mask:0xf bank_mask:0xf
	v_mov_b32_dpp v164, v150 row_ror:1 row_mask:0xf bank_mask:0xf
	v_cndmask_b32_e32 v165, v151, v139, vcc
	v_mov_b32_dpp v162, v163 row_ror:15 row_mask:0xf bank_mask:0xf
	v_mov_b32_dpp v195, v151 row_ror:1 row_mask:0xf bank_mask:0xf
	v_mov_b32_dpp v166, v148 row_ror:1 row_mask:0xf bank_mask:0xf
	v_mov_b32_dpp v167, v149 row_ror:1 row_mask:0xf bank_mask:0xf
	v_mov_b32_dpp v163, v165 row_ror:15 row_mask:0xf bank_mask:0xf
	v_cndmask_b32_e64 v165, v195, 0, vcc
	v_cndmask_b32_e64 v164, v164, 0, vcc
	v_cndmask_b32_e64 v167, v167, 0, vcc
	v_cndmask_b32_e64 v166, v166, 0, vcc
	s_nop 0
	s_nop 0
	v_mov_b32_dpp v195, v144 row_ror:1 row_mask:0xf bank_mask:0xf
	v_mov_b32_dpp v196, v145 row_ror:1 row_mask:0xf bank_mask:0xf
	v_mov_b32_dpp v198, v146 row_ror:1 row_mask:0xf bank_mask:0xf
	v_cndmask_b32_e32 v199, v147, v131, vcc
	v_mov_b32_dpp v200, v147 row_ror:1 row_mask:0xf bank_mask:0xf
	v_cndmask_b32_e64 v198, v198, 0, vcc
	v_cndmask_b32_e64 v201, v196, 0, vcc
	s_lshl_b32 s3, s44, 8
	s_add_i32 s3, s3, s49
	v_add_u32_e32 v193, s3, v194
	v_cmp_ne_u32_e64 s[46:47], 0, v194
	s_waitcnt vmcnt(0)
	v_pk_mul_f32 v[164:165], v[98:99], v[164:165]
	v_pk_mul_f32 v[166:167], v[96:97], v[166:167]
	v_pk_fma_f32 v[164:165], v[150:151], v[102:103], v[164:165]
	v_pk_fma_f32 v[166:167], v[148:149], v[100:101], v[166:167]
	v_pk_fma_f32 v[162:163], v[110:111], v[162:163], v[164:165]
	v_cndmask_b32_e32 v165, v144, v128, vcc
	v_pk_fma_f32 v[160:161], v[108:109], v[160:161], v[166:167]
	v_cndmask_b32_e32 v166, v145, v129, vcc
	v_mov_b32_dpp v164, v165 row_ror:15 row_mask:0xf bank_mask:0xf
	v_cndmask_b32_e32 v167, v146, v130, vcc
	v_pk_add_f32 v[162:163], v[114:115], v[162:163]
	v_mov_b32_dpp v165, v166 row_ror:15 row_mask:0xf bank_mask:0xf
	v_pk_add_f32 v[160:161], v[112:113], v[160:161]
	s_nop 0
	v_mov_b32_dpp v166, v167 row_ror:15 row_mask:0xf bank_mask:0xf
	s_nop 1
	v_mov_b32_dpp v167, v199 row_ror:15 row_mask:0xf bank_mask:0xf
	v_cndmask_b32_e64 v199, v200, 0, vcc
	v_cndmask_b32_e64 v200, v195, 0, vcc
	v_pk_mul_f32 v[200:201], v[80:81], v[200:201]
	v_pk_mul_f32 v[198:199], v[82:83], v[198:199]
	v_pk_fma_f32 v[200:201], v[144:145], v[84:85], v[200:201]
	v_pk_fma_f32 v[198:199], v[146:147], v[86:87], v[198:199]
	v_pk_fma_f32 v[164:165], v[88:89], v[164:165], v[200:201]
	v_pk_fma_f32 v[166:167], v[90:91], v[166:167], v[198:199]
	v_pk_add_f32 v[164:165], v[92:93], v[164:165]
	v_pk_add_f32 v[166:167], v[94:95], v[166:167]
	s_and_saveexec_b64 s[28:29], s[46:47]
	s_xor_b64 s[28:29], exec, s[28:29]
	s_cbranch_execz .LBB1_1911
	v_mul_f32_e32 v195, 0xbfb8aa3b, v160
	v_exp_f32_e32 v195, v195
	v_mul_f32_e32 v196, 0xbfb8aa3b, v161
	v_exp_f32_e32 v196, v196
	v_pk_mul_f32 v[160:161], v[156:157], v[160:161]
	v_add_f32_e32 v195, 1.0, v195
	v_rcp_f32_e32 v198, v195
	v_add_f32_e32 v196, 1.0, v196
	v_mul_f32_e32 v195, 0xbfb8aa3b, v162
	v_rcp_f32_e32 v199, v196
	v_exp_f32_e32 v195, v195
	v_mul_f32_e32 v196, 0xbfb8aa3b, v163
	v_exp_f32_e32 v196, v196
	v_pk_mul_f32 v[160:161], v[160:161], v[198:199]
	v_add_f32_e32 v195, 1.0, v195
	v_rcp_f32_e32 v200, v195
	v_add_f32_e32 v195, 1.0, v196
	v_rcp_f32_e32 v201, v195
	v_cvt_pk_bf16_f32 v160, v160, v161
	v_mul_f32_e32 v161, 0xbfb8aa3b, v164
	v_exp_f32_e32 v195, v161
	v_mul_f32_e32 v161, 0xbfb8aa3b, v165
	v_exp_f32_e32 v196, v161
	v_pk_mul_f32 v[162:163], v[158:159], v[162:163]
	v_pk_mul_f32 v[164:165], v[152:153], v[164:165]
	v_pk_mul_f32 v[162:163], v[162:163], v[200:201]
	s_nop 0
	v_cvt_pk_bf16_f32 v161, v162, v163
	v_add_f32_e32 v162, 1.0, v195
	v_mul_f32_e32 v195, 0xbfb8aa3b, v166
	v_add_f32_e32 v163, 1.0, v196
	v_exp_f32_e32 v195, v195
	v_mul_f32_e32 v196, 0xbfb8aa3b, v167
	v_exp_f32_e32 v196, v196
	v_rcp_f32_e32 v162, v162
	v_add_f32_e32 v195, 1.0, v195
	v_rcp_f32_e32 v198, v195
	v_add_f32_e32 v195, 1.0, v196
	v_rcp_f32_e32 v163, v163
	v_rcp_f32_e32 v199, v195
	v_pk_mul_f32 v[166:167], v[154:155], v[166:167]
	v_pk_mul_f32 v[162:163], v[164:165], v[162:163]
	v_pk_mul_f32 v[164:165], v[166:167], v[198:199]
	v_cvt_pk_bf16_f32 v162, v162, v163
	v_cvt_pk_bf16_f32 v163, v164, v165
	v_mov_b64_e32 v[164:165], s[52:53]
	v_mad_i64_i32 v[164:165], s[42:43], v193, s60, v[164:165]
	v_lshl_add_u64 v[164:165], v[184:185], 1, v[164:165]
	global_store_dwordx4 v[164:165], v[160:163], off

; DI unsigned pack2(float a, float b) { f32x2 v = {a, b}; hwbf16x2 r = __builtin_convertvector(v, hwbf16x2); return __builtin_bit_cast(unsigned, r); }
; DI float dpp_ror1(float v)  { return __builtin_bit_cast(float, __builtin_amdgcn_update_dpp(0, __builtin_bit_cast(int, v), 0x121, 0xf, 0xf, false)); }
;     DI void operator()(const f32x4 (&acc)[2][2][4][2], const Unit& u, int wr, int wc, int fr, int fq) const {
;     ...
;             for (int m = 0; m < 4; ++m) {
;                 const bool efirst = (m == 0) && (fr == 0), elast = (m == 3) && (fr == 15);
;                 const int row = row0 + ai * HALF + m * 16;
;                 f32x4 gc[2];
; #pragma unroll
;                 for (int n = 0; n < 2; ++n) {
;                     const f32x4 g = acc[ai][0][m][n];
;                     const f32x4 gprev = acc[ai][0][m > 0 ? m - 1 : 0][n], gnext = acc[ai][0][m < 3 ? m + 1 : 3][n];
;                     f32x4 up, dn;
; #pragma unroll
;                     for (int e = 0; e < 4; ++e) {
;                         const float pu = (m > 0 && fr == 15) ? gprev[e] : g[e];
;                         const float pd = (m < 3 && fr == 0) ? gnext[e] : g[e];
;                         up[e] = dpp_ror1(pu); dn[e] = dpp_ror15(pd);
;                     }
;                     if (efirst) up = (f32x4){0.f, 0.f, 0.f, 0.f};
;                     if (elast) dn = (f32x4){0.f, 0.f, 0.f, 0.f};
;                     gc[n] = w0[n] * up + w1[n] * g + w2[n] * dn + bb[n];
;                 }
;                 if (efirst || elast) {
;                     const size_t eo = (size_t)((row >> 6) * 2 + (elast ? 1 : 0)) * DFF + ch0;
; #pragma unroll
;                     for (int n = 0; n < 2; ++n) { *(f32x4*)(EP + eo + 4 * n) = gc[n]; *(f32x4*)(ER + eo + 4 * n) = acc[ai][0][m][n]; *(f32x4*)(EV + eo + 4 * n) = acc[ai][1][m][n]; }
;                 } else {
;                     const f32x4 v0 = acc[ai][1][m][0], v1 = acc[ai][1][m][1];
;                     u32x4 o;
;                     o[0] = pack2(silu_mul(gc[0][0], v0[0]), silu_mul(gc[0][1], v0[1])); o[1] = pack2(silu_mul(gc[0][2], v0[2]), silu_mul(gc[0][3], v0[3]));
;                     o[2] = pack2(silu_mul(gc[1][0], v1[0]), silu_mul(gc[1][1], v1[1])); o[3] = pack2(silu_mul(gc[1][2], v1[2]), silu_mul(gc[1][3], v1[3]));
;                     *(u32x4*)(ACT + (size_t)row * DFF + ch0) = o;
.LBB1_1913:
	s_or_b64 exec, exec, s[28:29]
	v_cmp_eq_u32_e64 s[44:45], 15, v194
	v_cndmask_b32_e32 v153, v136, v120, vcc
	v_cndmask_b32_e32 v154, v137, v121, vcc
	v_cndmask_b32_e64 v152, v136, v148, s[44:45]
	v_cndmask_b32_e32 v155, v138, v122, vcc
	v_cndmask_b32_e32 v156, v139, v123, vcc
	v_mov_b32_dpp v148, v152 row_ror:1 row_mask:0xf bank_mask:0xf
	v_cndmask_b32_e32 v157, v128, v104, vcc
	v_cndmask_b32_e32 v158, v129, v105, vcc
	v_mov_b32_dpp v152, v153 row_ror:15 row_mask:0xf bank_mask:0xf
	v_cndmask_b32_e64 v153, v137, v149, s[44:45]
	v_cndmask_b32_e32 v159, v130, v106, vcc
	v_cndmask_b32_e32 v160, v131, v107, vcc
	v_mov_b32_dpp v149, v153 row_ror:1 row_mask:0xf bank_mask:0xf
	v_pk_mul_f32 v[148:149], v[96:97], v[148:149]
	v_cmp_ne_u32_e64 s[42:43], 15, v194
	v_mov_b32_dpp v153, v154 row_ror:15 row_mask:0xf bank_mask:0xf
	v_pk_fma_f32 v[148:149], v[136:137], v[100:101], v[148:149]
	v_cndmask_b32_e64 v154, v138, v150, s[44:45]
	v_pk_fma_f32 v[148:149], v[108:109], v[152:153], v[148:149]
	s_nop 0
	v_mov_b32_dpp v150, v154 row_ror:1 row_mask:0xf bank_mask:0xf
	v_pk_add_f32 v[148:149], v[112:113], v[148:149]
	s_nop 0
	v_mov_b32_dpp v154, v155 row_ror:15 row_mask:0xf bank_mask:0xf
	v_cndmask_b32_e64 v155, v139, v151, s[44:45]
	v_mul_f32_e32 v152, 0xbfb8aa3b, v148
	v_mul_f32_e32 v153, 0xbfb8aa3b, v149
	v_mov_b32_dpp v151, v155 row_ror:1 row_mask:0xf bank_mask:0xf
	v_exp_f32_e32 v152, v152
	v_exp_f32_e32 v153, v153
	v_pk_mul_f32 v[150:151], v[98:99], v[150:151]
	v_add_f32_e32 v152, 1.0, v152
	v_mov_b32_dpp v155, v156 row_ror:15 row_mask:0xf bank_mask:0xf
	v_cndmask_b32_e64 v156, v128, v144, s[44:45]
	v_pk_fma_f32 v[150:151], v[138:139], v[102:103], v[150:151]
	v_add_f32_e32 v153, 1.0, v153
	v_mov_b32_dpp v144, v156 row_ror:1 row_mask:0xf bank_mask:0xf
	v_pk_fma_f32 v[150:151], v[110:111], v[154:155], v[150:151]
	v_rcp_f32_e32 v152, v152
	v_mov_b32_dpp v156, v157 row_ror:15 row_mask:0xf bank_mask:0xf
	v_cndmask_b32_e64 v157, v129, v145, s[44:45]
	v_pk_add_f32 v[150:151], v[114:115], v[150:151]
	v_rcp_f32_e32 v153, v153
	v_mov_b32_dpp v145, v157 row_ror:1 row_mask:0xf bank_mask:0xf
	v_mul_f32_e32 v154, 0xbfb8aa3b, v150
	v_mul_f32_e32 v155, 0xbfb8aa3b, v151
	v_pk_mul_f32 v[144:145], v[80:81], v[144:145]
	v_exp_f32_e32 v154, v154
	v_exp_f32_e32 v155, v155
	v_mov_b32_dpp v157, v158 row_ror:15 row_mask:0xf bank_mask:0xf
	v_pk_fma_f32 v[144:145], v[128:129], v[84:85], v[144:145]
	v_cndmask_b32_e64 v158, v130, v146, s[44:45]
	v_pk_fma_f32 v[144:145], v[88:89], v[156:157], v[144:145]
	v_pk_mul_f32 v[140:141], v[140:141], v[148:149]
	v_mov_b32_dpp v146, v158 row_ror:1 row_mask:0xf bank_mask:0xf
	v_pk_add_f32 v[144:145], v[92:93], v[144:145]
	v_pk_mul_f32 v[140:141], v[140:141], v[152:153]
	v_mov_b32_dpp v158, v159 row_ror:15 row_mask:0xf bank_mask:0xf
	v_cndmask_b32_e64 v159, v131, v147, s[44:45]
	v_pk_mul_f32 v[142:143], v[142:143], v[150:151]
	v_add_f32_e32 v150, 1.0, v154
	v_add_f32_e32 v151, 1.0, v155
	v_cvt_pk_bf16_f32 v140, v140, v141
	v_mul_f32_e32 v141, 0xbfb8aa3b, v144
	v_mov_b32_dpp v147, v159 row_ror:1 row_mask:0xf bank_mask:0xf
	v_rcp_f32_e32 v150, v150
	v_rcp_f32_e32 v151, v151
	v_exp_f32_e32 v148, v141
	v_mul_f32_e32 v141, 0xbfb8aa3b, v145
	v_pk_mul_f32 v[146:147], v[82:83], v[146:147]
	v_exp_f32_e32 v149, v141
	v_mov_b32_dpp v159, v160 row_ror:15 row_mask:0xf bank_mask:0xf
	v_pk_fma_f32 v[146:147], v[130:131], v[86:87], v[146:147]
	v_pk_mul_f32 v[142:143], v[142:143], v[150:151]
	v_pk_fma_f32 v[146:147], v[90:91], v[158:159], v[146:147]
	v_cvt_pk_bf16_f32 v141, v142, v143
	v_pk_add_f32 v[146:147], v[94:95], v[146:147]
	v_add_f32_e32 v142, 1.0, v148
	v_add_f32_e32 v143, 1.0, v149
	v_mul_f32_e32 v148, 0xbfb8aa3b, v146
	v_mul_f32_e32 v149, 0xbfb8aa3b, v147
	v_exp_f32_e32 v148, v148
	v_exp_f32_e32 v149, v149
	v_rcp_f32_e32 v142, v142
	v_rcp_f32_e32 v143, v143
	v_pk_mul_f32 v[134:135], v[134:135], v[146:147]
	v_add_f32_e32 v146, 1.0, v148
	v_add_f32_e32 v147, 1.0, v149
	v_rcp_f32_e32 v146, v146
	v_rcp_f32_e32 v147, v147
	v_pk_mul_f32 v[132:133], v[132:133], v[144:145]
	v_add_u32_e32 v160, 16, v193
	v_pk_mul_f32 v[132:133], v[132:133], v[142:143]
	v_cndmask_b32_e32 v148, v107, v75, vcc
	v_cvt_pk_bf16_f32 v142, v132, v133
	v_pk_mul_f32 v[132:133], v[134:135], v[146:147]
	v_mov_b64_e32 v[134:135], s[52:53]
	v_cvt_pk_bf16_f32 v143, v132, v133
	v_mad_i64_i32 v[144:145], s[28:29], v160, s60, v[134:135]
	v_lshlrev_b64 v[132:133], 1, v[184:185]
	v_lshl_add_u64 v[144:145], v[144:145], 0, v[132:133]
	global_store_dwordx4 v[144:145], v[140:143], off
	v_cndmask_b32_e32 v144, v123, v79, vcc
	v_cndmask_b32_e32 v145, v104, v72, vcc
	v_cndmask_b32_e64 v140, v120, v136, s[44:45]
	v_cndmask_b32_e32 v141, v120, v76, vcc
	v_cndmask_b32_e32 v142, v121, v77, vcc
	v_mov_b32_dpp v136, v140 row_ror:1 row_mask:0xf bank_mask:0xf
	v_cndmask_b32_e32 v143, v122, v78, vcc
	v_cndmask_b32_e32 v146, v105, v73, vcc
	v_mov_b32_dpp v140, v141 row_ror:15 row_mask:0xf bank_mask:0xf
	v_cndmask_b32_e64 v141, v121, v137, s[44:45]
	v_cndmask_b32_e32 v147, v106, v74, vcc
	s_nop 0
	v_mov_b32_dpp v137, v141 row_ror:1 row_mask:0xf bank_mask:0xf
	v_pk_mul_f32 v[136:137], v[96:97], v[136:137]
	s_nop 0
	v_mov_b32_dpp v141, v142 row_ror:15 row_mask:0xf bank_mask:0xf
	v_pk_fma_f32 v[136:137], v[120:121], v[100:101], v[136:137]
	v_cndmask_b32_e64 v142, v122, v138, s[44:45]
	v_pk_fma_f32 v[136:137], v[108:109], v[140:141], v[136:137]
	s_nop 0
	v_mov_b32_dpp v138, v142 row_ror:1 row_mask:0xf bank_mask:0xf
	v_pk_add_f32 v[136:137], v[112:113], v[136:137]
	s_nop 0
	v_mov_b32_dpp v142, v143 row_ror:15 row_mask:0xf bank_mask:0xf
	v_cndmask_b32_e64 v143, v123, v139, s[44:45]
	v_mul_f32_e32 v140, 0xbfb8aa3b, v136
; DI unsigned pack2(float a, float b) { f32x2 v = {a, b}; hwbf16x2 r = __builtin_convertvector(v, hwbf16x2); return __builtin_bit_cast(unsigned, r); }
; DI float dpp_ror1(float v)  { return __builtin_bit_cast(float, __builtin_amdgcn_update_dpp(0, __builtin_bit_cast(int, v), 0x121, 0xf, 0xf, false)); }
;     DI void operator()(const f32x4 (&acc)[2][2][4][2], const Unit& u, int wr, int wc, int fr, int fq) const {
;     ...
;             for (int m = 0; m < 4; ++m) {
;                 const bool efirst = (m == 0) && (fr == 0), elast = (m == 3) && (fr == 15);
;                 const int row = row0 + ai * HALF + m * 16;
;                 f32x4 gc[2];
; #pragma unroll
;                 for (int n = 0; n < 2; ++n) {
;                     const f32x4 g = acc[ai][0][m][n];
;                     const f32x4 gprev = acc[ai][0][m > 0 ? m - 1 : 0][n], gnext = acc[ai][0][m < 3 ? m + 1 : 3][n];
;                     f32x4 up, dn;
; #pragma unroll
;                     for (int e = 0; e < 4; ++e) {
;                         const float pu = (m > 0 && fr == 15) ? gprev[e] : g[e];
;                         const float pd = (m < 3 && fr == 0) ? gnext[e] : g[e];
;                         up[e] = dpp_ror1(pu); dn[e] = dpp_ror15(pd);
;                     }
;                     if (efirst) up = (f32x4){0.f, 0.f, 0.f, 0.f};
;                     if (elast) dn = (f32x4){0.f, 0.f, 0.f, 0.f};
;                     gc[n] = w0[n] * up + w1[n] * g + w2[n] * dn + bb[n];
;                 }
;                 if (efirst || elast) {
;                     const size_t eo = (size_t)((row >> 6) * 2 + (elast ? 1 : 0)) * DFF + ch0;
; #pragma unroll
;                     for (int n = 0; n < 2; ++n) { *(f32x4*)(EP + eo + 4 * n) = gc[n]; *(f32x4*)(ER + eo + 4 * n) = acc[ai][0][m][n]; *(f32x4*)(EV + eo + 4 * n) = acc[ai][1][m][n]; }
;                 } else {
;                     const f32x4 v0 = acc[ai][1][m][0], v1 = acc[ai][1][m][1];
;                     u32x4 o;
;                     o[0] = pack2(silu_mul(gc[0][0], v0[0]), silu_mul(gc[0][1], v0[1])); o[1] = pack2(silu_mul(gc[0][2], v0[2]), silu_mul(gc[0][3], v0[3]));
;                     o[2] = pack2(silu_mul(gc[1][0], v1[0]), silu_mul(gc[1][1], v1[1])); o[3] = pack2(silu_mul(gc[1][2], v1[2]), silu_mul(gc[1][3], v1[3]));
;                     *(u32x4*)(ACT + (size_t)row * DFF + ch0) = o;
;                 }
	v_mul_f32_e32 v141, 0xbfb8aa3b, v137
	v_mov_b32_dpp v139, v143 row_ror:1 row_mask:0xf bank_mask:0xf
	v_exp_f32_e32 v140, v140
	v_exp_f32_e32 v141, v141
	v_pk_mul_f32 v[138:139], v[98:99], v[138:139]
	v_add_f32_e32 v140, 1.0, v140
	v_mov_b32_dpp v143, v144 row_ror:15 row_mask:0xf bank_mask:0xf
	v_cndmask_b32_e64 v144, v104, v128, s[44:45]
	v_pk_fma_f32 v[138:139], v[122:123], v[102:103], v[138:139]
	v_add_f32_e32 v141, 1.0, v141
	v_mov_b32_dpp v128, v144 row_ror:1 row_mask:0xf bank_mask:0xf
	v_pk_fma_f32 v[138:139], v[110:111], v[142:143], v[138:139]
	v_rcp_f32_e32 v140, v140
	v_mov_b32_dpp v144, v145 row_ror:15 row_mask:0xf bank_mask:0xf
	v_cndmask_b32_e64 v145, v105, v129, s[44:45]
	v_pk_add_f32 v[138:139], v[114:115], v[138:139]
	v_rcp_f32_e32 v141, v141
	v_mov_b32_dpp v129, v145 row_ror:1 row_mask:0xf bank_mask:0xf
	v_mul_f32_e32 v142, 0xbfb8aa3b, v138
	v_mul_f32_e32 v143, 0xbfb8aa3b, v139
	v_pk_mul_f32 v[128:129], v[80:81], v[128:129]
	v_exp_f32_e32 v142, v142
	v_exp_f32_e32 v143, v143
	v_mov_b32_dpp v145, v146 row_ror:15 row_mask:0xf bank_mask:0xf
	v_pk_fma_f32 v[128:129], v[104:105], v[84:85], v[128:129]
	v_cndmask_b32_e64 v146, v106, v130, s[44:45]
	v_pk_fma_f32 v[128:129], v[88:89], v[144:145], v[128:129]
	v_pk_mul_f32 v[124:125], v[124:125], v[136:137]
	v_mov_b32_dpp v130, v146 row_ror:1 row_mask:0xf bank_mask:0xf
	v_pk_add_f32 v[128:129], v[92:93], v[128:129]
	v_pk_mul_f32 v[124:125], v[124:125], v[140:141]
	v_mov_b32_dpp v146, v147 row_ror:15 row_mask:0xf bank_mask:0xf
	v_cndmask_b32_e64 v147, v107, v131, s[44:45]
	v_pk_mul_f32 v[126:127], v[126:127], v[138:139]
	v_add_f32_e32 v138, 1.0, v142
	v_add_f32_e32 v139, 1.0, v143
	v_cvt_pk_bf16_f32 v124, v124, v125
	v_mul_f32_e32 v125, 0xbfb8aa3b, v128
	v_mov_b32_dpp v131, v147 row_ror:1 row_mask:0xf bank_mask:0xf
	v_rcp_f32_e32 v138, v138
	v_rcp_f32_e32 v139, v139
	v_exp_f32_e32 v136, v125
	v_mul_f32_e32 v125, 0xbfb8aa3b, v129
	v_pk_mul_f32 v[130:131], v[82:83], v[130:131]
	v_exp_f32_e32 v137, v125
	v_mov_b32_dpp v147, v148 row_ror:15 row_mask:0xf bank_mask:0xf
	v_pk_fma_f32 v[130:131], v[106:107], v[86:87], v[130:131]
	v_pk_mul_f32 v[126:127], v[126:127], v[138:139]
	v_pk_fma_f32 v[130:131], v[90:91], v[146:147], v[130:131]
	v_cvt_pk_bf16_f32 v125, v126, v127
	v_pk_add_f32 v[130:131], v[94:95], v[130:131]
	v_add_f32_e32 v126, 1.0, v136
	v_add_f32_e32 v127, 1.0, v137
	v_mul_f32_e32 v136, 0xbfb8aa3b, v130
	v_mul_f32_e32 v137, 0xbfb8aa3b, v131
	v_exp_f32_e32 v136, v136
	v_exp_f32_e32 v137, v137
	v_rcp_f32_e32 v126, v126
	v_rcp_f32_e32 v127, v127
	v_pk_mul_f32 v[118:119], v[118:119], v[130:131]
	v_add_f32_e32 v130, 1.0, v136
	v_add_f32_e32 v131, 1.0, v137
	v_rcp_f32_e32 v130, v130
	v_rcp_f32_e32 v131, v131
	v_pk_mul_f32 v[116:117], v[116:117], v[128:129]
	v_add_u32_e32 v148, 32, v193
	v_pk_mul_f32 v[116:117], v[116:117], v[126:127]
	s_nop 0
	v_cvt_pk_bf16_f32 v126, v116, v117
	v_pk_mul_f32 v[116:117], v[118:119], v[130:131]
	v_cndmask_b32_e64 v118, v77, v121, s[44:45]
	v_cvt_pk_bf16_f32 v127, v116, v117
	v_mad_i64_i32 v[116:117], s[28:29], v148, s60, v[134:135]
	v_lshl_add_u64 v[116:117], v[116:117], 0, v[132:133]
	global_store_dwordx4 v[116:117], v[124:127], off
	v_cndmask_b32_e64 v117, v76, v120, s[44:45]
	v_cndmask_b32_e64 v119, v78, v122, s[44:45]
	v_cndmask_b32_e64 v121, v79, v123, s[44:45]
	v_mov_b32_dpp v116, v117 row_ror:1 row_mask:0xf bank_mask:0xf
	s_nop 0
	s_nop 0
	v_mov_b32_dpp v117, v118 row_ror:1 row_mask:0xf bank_mask:0xf
	v_mov_b32_dpp v120, v78 row_ror:15 row_mask:0xf bank_mask:0xf
	v_cndmask_b32_e64 v120, v120, 0, s[44:45]
	v_mov_b32_dpp v118, v119 row_ror:1 row_mask:0xf bank_mask:0xf
	s_nop 0
	v_mov_b32_dpp v124, v76 row_ror:15 row_mask:0xf bank_mask:0xf
	v_mov_b32_dpp v119, v121 row_ror:1 row_mask:0xf bank_mask:0xf
	v_pk_mul_f32 v[118:119], v[98:99], v[118:119]
	v_mov_b32_dpp v125, v77 row_ror:15 row_mask:0xf bank_mask:0xf
	v_mov_b32_dpp v121, v79 row_ror:15 row_mask:0xf bank_mask:0xf
	v_cndmask_b32_e64 v121, v121, 0, s[44:45]
	v_pk_fma_f32 v[118:119], v[78:79], v[102:103], v[118:119]
	v_pk_mul_f32 v[116:117], v[96:97], v[116:117]
	v_pk_fma_f32 v[118:119], v[110:111], v[120:121], v[118:119]
	v_cndmask_b32_e64 v120, v72, v104, s[44:45]
	v_cndmask_b32_e64 v123, v125, 0, s[44:45]
	v_cndmask_b32_e64 v122, v124, 0, s[44:45]
	v_mov_b32_dpp v104, v120 row_ror:1 row_mask:0xf bank_mask:0xf
	v_cndmask_b32_e64 v120, v73, v105, s[44:45]
	v_pk_fma_f32 v[116:117], v[76:77], v[100:101], v[116:117]
	v_cndmask_b32_e64 v121, v75, v107, s[44:45]
	v_mov_b32_dpp v105, v120 row_ror:1 row_mask:0xf bank_mask:0xf
	v_cndmask_b32_e64 v120, v74, v106, s[44:45]
	s_nop 0
	v_pk_fma_f32 v[116:117], v[108:109], v[122:123], v[116:117]
	v_mov_b32_dpp v106, v120 row_ror:1 row_mask:0xf bank_mask:0xf
	v_mov_b32_dpp v107, v121 row_ror:1 row_mask:0xf bank_mask:0xf
	v_mov_b32_dpp v122, v72 row_ror:15 row_mask:0xf bank_mask:0xf
	v_mov_b32_dpp v123, v73 row_ror:15 row_mask:0xf bank_mask:0xf
	v_mov_b32_dpp v120, v74 row_ror:15 row_mask:0xf bank_mask:0xf
	v_mov_b32_dpp v121, v75 row_ror:15 row_mask:0xf bank_mask:0xf
	v_pk_mul_f32 v[104:105], v[80:81], v[104:105]
	v_pk_mul_f32 v[106:107], v[82:83], v[106:107]
	v_cndmask_b32_e64 v121, v121, 0, s[44:45]
	v_cndmask_b32_e64 v120, v120, 0, s[44:45]
	v_cndmask_b32_e64 v123, v123, 0, s[44:45]
	v_cndmask_b32_e64 v122, v122, 0, s[44:45]
	v_pk_fma_f32 v[106:107], v[74:75], v[86:87], v[106:107]
	v_pk_fma_f32 v[104:105], v[72:73], v[84:85], v[104:105]
	v_pk_fma_f32 v[106:107], v[90:91], v[120:121], v[106:107]
	v_pk_fma_f32 v[104:105], v[88:89], v[122:123], v[104:105]
	v_pk_add_f32 v[118:119], v[114:115], v[118:119]
	v_pk_add_f32 v[116:117], v[112:113], v[116:117]
	v_pk_add_f32 v[106:107], v[94:95], v[106:107]
	v_pk_add_f32 v[104:105], v[92:93], v[104:105]
	v_add_u32_e32 v120, 48, v193
	s_and_saveexec_b64 s[28:29], s[42:43]
	s_xor_b64 s[28:29], exec, s[28:29]
	s_cbranch_execz .LBB1_1915
; DI unsigned pack2(float a, float b) { f32x2 v = {a, b}; hwbf16x2 r = __builtin_convertvector(v, hwbf16x2); return __builtin_bit_cast(unsigned, r); }
; DI float silu_mul(float g, float v) { return g * v * __builtin_amdgcn_rcpf(1.0f + __builtin_amdgcn_exp2f(-LOG2E * g)); }
;     DI void operator()(const f32x4 (&acc)[2][2][4][2], const Unit& u, int wr, int wc, int fr, int fq) const {
;     ...
;                     const f32x4 v0 = acc[ai][1][m][0], v1 = acc[ai][1][m][1];
;                     u32x4 o;
;                     o[0] = pack2(silu_mul(gc[0][0], v0[0]), silu_mul(gc[0][1], v0[1])); o[1] = pack2(silu_mul(gc[0][2], v0[2]), silu_mul(gc[0][3], v0[3]));
;                     o[2] = pack2(silu_mul(gc[1][0], v1[0]), silu_mul(gc[1][1], v1[1])); o[3] = pack2(silu_mul(gc[1][2], v1[2]), silu_mul(gc[1][3], v1[3]));
;                     *(u32x4*)(ACT + (size_t)row * DFF + ch0) = o;
	v_mul_f32_e32 v121, 0xbfb8aa3b, v116
	v_exp_f32_e32 v121, v121
	v_mul_f32_e32 v122, 0xbfb8aa3b, v117
	v_exp_f32_e32 v122, v122
	v_mul_f32_e32 v124, 0xbfb8aa3b, v119
	v_add_f32_e32 v121, 1.0, v121
	v_exp_f32_e32 v125, v124
	v_add_f32_e32 v123, 1.0, v122
	v_rcp_f32_e32 v122, v121
	v_mul_f32_e32 v121, 0xbfb8aa3b, v118
	v_exp_f32_e32 v121, v121
	v_rcp_f32_e32 v123, v123
	v_pk_mul_f32 v[116:117], v[68:69], v[116:117]
	v_pk_mul_f32 v[118:119], v[70:71], v[118:119]
	v_add_f32_e32 v121, 1.0, v121
	v_rcp_f32_e32 v124, v121
	v_add_f32_e32 v121, 1.0, v125
	v_pk_mul_f32 v[116:117], v[116:117], v[122:123]
	v_rcp_f32_e32 v125, v121
	v_cvt_pk_bf16_f32 v116, v116, v117
	v_mul_f32_e32 v117, 0xbfb8aa3b, v104
	v_exp_f32_e32 v121, v117
	v_mul_f32_e32 v117, 0xbfb8aa3b, v105
	v_exp_f32_e32 v122, v117
	v_pk_mul_f32 v[118:119], v[118:119], v[124:125]
	v_pk_mul_f32 v[104:105], v[64:65], v[104:105]
	v_cvt_pk_bf16_f32 v117, v118, v119
	v_add_f32_e32 v118, 1.0, v121
	v_mul_f32_e32 v121, 0xbfb8aa3b, v106
	v_add_f32_e32 v119, 1.0, v122
	v_exp_f32_e32 v121, v121
	v_mul_f32_e32 v122, 0xbfb8aa3b, v107
	v_exp_f32_e32 v123, v122
	v_rcp_f32_e32 v118, v118
	v_add_f32_e32 v121, 1.0, v121
	v_rcp_f32_e32 v119, v119
	v_rcp_f32_e32 v122, v121
	v_add_f32_e32 v121, 1.0, v123
	v_rcp_f32_e32 v123, v121
	v_pk_mul_f32 v[106:107], v[66:67], v[106:107]
	v_pk_mul_f32 v[104:105], v[104:105], v[118:119]
	s_nop 0
	v_cvt_pk_bf16_f32 v118, v104, v105
	v_pk_mul_f32 v[104:105], v[106:107], v[122:123]
	s_nop 0
	v_cvt_pk_bf16_f32 v119, v104, v105
	v_mov_b64_e32 v[104:105], s[52:53]
	v_mad_i64_i32 v[104:105], s[58:59], v120, s60, v[104:105]
	v_lshl_add_u64 v[104:105], v[184:185], 1, v[104:105]
	global_store_dwordx4 v[104:105], v[116:119], off

; DI unsigned pack2(float a, float b) { f32x2 v = {a, b}; hwbf16x2 r = __builtin_convertvector(v, hwbf16x2); return __builtin_bit_cast(unsigned, r); }
; DI float dpp_ror1(float v)  { return __builtin_bit_cast(float, __builtin_amdgcn_update_dpp(0, __builtin_bit_cast(int, v), 0x121, 0xf, 0xf, false)); }
;     DI void operator()(const f32x4 (&acc)[2][2][4][2], const Unit& u, int wr, int wc, int fr, int fq) const {
;     ...
;             for (int m = 0; m < 4; ++m) {
;                 const bool efirst = (m == 0) && (fr == 0), elast = (m == 3) && (fr == 15);
;                 const int row = row0 + ai * HALF + m * 16;
;                 f32x4 gc[2];
; #pragma unroll
;                 for (int n = 0; n < 2; ++n) {
;                     const f32x4 g = acc[ai][0][m][n];
;                     const f32x4 gprev = acc[ai][0][m > 0 ? m - 1 : 0][n], gnext = acc[ai][0][m < 3 ? m + 1 : 3][n];
;                     f32x4 up, dn;
; #pragma unroll
;                     for (int e = 0; e < 4; ++e) {
;                         const float pu = (m > 0 && fr == 15) ? gprev[e] : g[e];
;                         const float pd = (m < 3 && fr == 0) ? gnext[e] : g[e];
;                         up[e] = dpp_ror1(pu); dn[e] = dpp_ror15(pd);
;                     }
;                     if (efirst) up = (f32x4){0.f, 0.f, 0.f, 0.f};
;                     if (elast) dn = (f32x4){0.f, 0.f, 0.f, 0.f};
;                     gc[n] = w0[n] * up + w1[n] * g + w2[n] * dn + bb[n];
;                 }
;                 if (efirst || elast) {
;                     const size_t eo = (size_t)((row >> 6) * 2 + (elast ? 1 : 0)) * DFF + ch0;
; #pragma unroll
;                     for (int n = 0; n < 2; ++n) { *(f32x4*)(EP + eo + 4 * n) = gc[n]; *(f32x4*)(ER + eo + 4 * n) = acc[ai][0][m][n]; *(f32x4*)(EV + eo + 4 * n) = acc[ai][1][m][n]; }
;                 } else {
;                     const f32x4 v0 = acc[ai][1][m][0], v1 = acc[ai][1][m][1];
;                     u32x4 o;
;                     o[0] = pack2(silu_mul(gc[0][0], v0[0]), silu_mul(gc[0][1], v0[1])); o[1] = pack2(silu_mul(gc[0][2], v0[2]), silu_mul(gc[0][3], v0[3]));
;                     o[2] = pack2(silu_mul(gc[1][0], v1[0]), silu_mul(gc[1][1], v1[1])); o[3] = pack2(silu_mul(gc[1][2], v1[2]), silu_mul(gc[1][3], v1[3]));
;                     *(u32x4*)(ACT + (size_t)row * DFF + ch0) = o;
;                 }
.LBB1_1917:
	s_or_b64 exec, exec, s[28:29]
	s_nop 0
	v_cndmask_b32_e32 v65, v60, v40, vcc
	v_cndmask_b32_e32 v66, v61, v41, vcc
	v_cndmask_b32_e32 v67, v62, v42, vcc
	v_mov_b32_dpp v64, v65 row_ror:15 row_mask:0xf bank_mask:0xf
	s_nop 0
	s_nop 0
	v_mov_b32_dpp v65, v66 row_ror:15 row_mask:0xf bank_mask:0xf
	s_nop 0
	v_mov_b32_dpp v68, v62 row_ror:1 row_mask:0xf bank_mask:0xf
	v_mov_b32_dpp v66, v67 row_ror:15 row_mask:0xf bank_mask:0xf
	v_cndmask_b32_e32 v69, v63, v43, vcc
	v_mov_b32_dpp v73, v63 row_ror:1 row_mask:0xf bank_mask:0xf
	v_mov_b32_dpp v70, v60 row_ror:1 row_mask:0xf bank_mask:0xf
	v_mov_b32_dpp v71, v61 row_ror:1 row_mask:0xf bank_mask:0xf
	v_mov_b32_dpp v67, v69 row_ror:15 row_mask:0xf bank_mask:0xf
	v_cndmask_b32_e64 v69, v73, 0, vcc
	v_cndmask_b32_e64 v68, v68, 0, vcc
	v_cndmask_b32_e64 v71, v71, 0, vcc
	v_cndmask_b32_e64 v70, v70, 0, vcc
	v_pk_mul_f32 v[68:69], v[98:99], v[68:69]
	v_pk_mul_f32 v[70:71], v[96:97], v[70:71]
	v_pk_fma_f32 v[68:69], v[62:63], v[102:103], v[68:69]
	v_pk_fma_f32 v[70:71], v[60:61], v[100:101], v[70:71]
	v_pk_fma_f32 v[66:67], v[110:111], v[66:67], v[68:69]
	v_cndmask_b32_e32 v69, v48, v32, vcc
	v_pk_fma_f32 v[64:65], v[108:109], v[64:65], v[70:71]
	v_cndmask_b32_e32 v70, v49, v33, vcc
	v_mov_b32_dpp v68, v69 row_ror:15 row_mask:0xf bank_mask:0xf
	s_nop 0
	s_nop 0
	v_mov_b32_dpp v69, v70 row_ror:15 row_mask:0xf bank_mask:0xf
	v_cndmask_b32_e32 v71, v50, v34, vcc
	v_mov_b32_dpp v73, v48 row_ror:1 row_mask:0xf bank_mask:0xf
	v_mov_b32_dpp v76, v49 row_ror:1 row_mask:0xf bank_mask:0xf
	v_mov_b32_dpp v74, v50 row_ror:1 row_mask:0xf bank_mask:0xf
	v_mov_b32_dpp v70, v71 row_ror:15 row_mask:0xf bank_mask:0xf
	v_cndmask_b32_e32 v75, v51, v35, vcc
	v_mov_b32_dpp v77, v51 row_ror:1 row_mask:0xf bank_mask:0xf
	v_cndmask_b32_e64 v74, v74, 0, vcc
	v_add_u32_e32 v72, 0x80, v193
	v_mov_b32_dpp v71, v75 row_ror:15 row_mask:0xf bank_mask:0xf
	v_cndmask_b32_e64 v75, v77, 0, vcc
	v_cndmask_b32_e64 v77, v76, 0, vcc
	v_cndmask_b32_e64 v76, v73, 0, vcc
	v_pk_mul_f32 v[76:77], v[80:81], v[76:77]
	v_pk_mul_f32 v[74:75], v[82:83], v[74:75]
	v_pk_fma_f32 v[76:77], v[48:49], v[84:85], v[76:77]
	v_pk_fma_f32 v[74:75], v[50:51], v[86:87], v[74:75]
	v_pk_fma_f32 v[68:69], v[88:89], v[68:69], v[76:77]
	v_pk_fma_f32 v[70:71], v[90:91], v[70:71], v[74:75]
	v_pk_add_f32 v[66:67], v[114:115], v[66:67]
	v_pk_add_f32 v[64:65], v[112:113], v[64:65]
	v_pk_add_f32 v[70:71], v[94:95], v[70:71]
	v_pk_add_f32 v[68:69], v[92:93], v[68:69]
	s_and_saveexec_b64 s[28:29], s[46:47]
	s_xor_b64 s[28:29], exec, s[28:29]
	s_cbranch_execz .LBB1_1919
	v_mul_f32_e32 v73, 0xbfb8aa3b, v64
	v_exp_f32_e32 v73, v73
	v_mul_f32_e32 v74, 0xbfb8aa3b, v65
	v_exp_f32_e32 v74, v74
	v_mul_f32_e32 v76, 0xbfb8aa3b, v67
	v_add_f32_e32 v73, 1.0, v73
	v_exp_f32_e32 v77, v76
	v_add_f32_e32 v75, 1.0, v74
	v_rcp_f32_e32 v74, v73
	v_mul_f32_e32 v73, 0xbfb8aa3b, v66
	v_exp_f32_e32 v73, v73
	v_rcp_f32_e32 v75, v75
	v_pk_mul_f32 v[64:65], v[56:57], v[64:65]
	v_pk_mul_f32 v[66:67], v[58:59], v[66:67]
	v_add_f32_e32 v73, 1.0, v73
	v_rcp_f32_e32 v76, v73
	v_add_f32_e32 v73, 1.0, v77
	v_pk_mul_f32 v[64:65], v[64:65], v[74:75]
	v_rcp_f32_e32 v77, v73
	v_cvt_pk_bf16_f32 v64, v64, v65
	v_mul_f32_e32 v65, 0xbfb8aa3b, v68
	v_exp_f32_e32 v73, v65
	v_mul_f32_e32 v65, 0xbfb8aa3b, v69
	v_exp_f32_e32 v74, v65
	v_pk_mul_f32 v[66:67], v[66:67], v[76:77]
	v_pk_mul_f32 v[68:69], v[52:53], v[68:69]
	v_cvt_pk_bf16_f32 v65, v66, v67
	v_add_f32_e32 v66, 1.0, v73
	v_mul_f32_e32 v73, 0xbfb8aa3b, v70
	v_add_f32_e32 v67, 1.0, v74
	v_exp_f32_e32 v73, v73
	v_mul_f32_e32 v74, 0xbfb8aa3b, v71
	v_exp_f32_e32 v75, v74
	v_rcp_f32_e32 v66, v66
	v_add_f32_e32 v73, 1.0, v73
	v_rcp_f32_e32 v74, v73
	v_add_f32_e32 v73, 1.0, v75
	v_rcp_f32_e32 v67, v67
	v_rcp_f32_e32 v75, v73
	v_pk_mul_f32 v[70:71], v[54:55], v[70:71]
	v_pk_mul_f32 v[66:67], v[68:69], v[66:67]
	v_pk_mul_f32 v[68:69], v[70:71], v[74:75]
	v_cvt_pk_bf16_f32 v66, v66, v67
	v_cvt_pk_bf16_f32 v67, v68, v69
	v_mov_b64_e32 v[68:69], s[52:53]
	v_mad_i64_i32 v[68:69], s[46:47], v72, s60, v[68:69]
	v_lshl_add_u64 v[68:69], v[184:185], 1, v[68:69]
	global_store_dwordx4 v[68:69], v[64:67], off

; DI unsigned pack2(float a, float b) { f32x2 v = {a, b}; hwbf16x2 r = __builtin_convertvector(v, hwbf16x2); return __builtin_bit_cast(unsigned, r); }
; DI float dpp_ror1(float v)  { return __builtin_bit_cast(float, __builtin_amdgcn_update_dpp(0, __builtin_bit_cast(int, v), 0x121, 0xf, 0xf, false)); }
; DI float dpp_ror15(float v) { return __builtin_bit_cast(float, __builtin_amdgcn_update_dpp(0, __builtin_bit_cast(int, v), 0x12F, 0xf, 0xf, false)); }
; DI float silu_mul(float g, float v) { return g * v * __builtin_amdgcn_rcpf(1.0f + __builtin_amdgcn_exp2f(-LOG2E * g)); }
;     DI void operator()(const f32x4 (&acc)[2][2][4][2], const Unit& u, int wr, int wc, int fr, int fq) const {
;     ...
;                 for (int n = 0; n < 2; ++n) {
;                     const f32x4 g = acc[ai][0][m][n];
;                     const f32x4 gprev = acc[ai][0][m > 0 ? m - 1 : 0][n], gnext = acc[ai][0][m < 3 ? m + 1 : 3][n];
;                     f32x4 up, dn;
; #pragma unroll
;                     for (int e = 0; e < 4; ++e) {
;                         const float pu = (m > 0 && fr == 15) ? gprev[e] : g[e];
;                         const float pd = (m < 3 && fr == 0) ? gnext[e] : g[e];
;                         up[e] = dpp_ror1(pu); dn[e] = dpp_ror15(pd);
;                     }
;                     if (efirst) up = (f32x4){0.f, 0.f, 0.f, 0.f};
;                     if (elast) dn = (f32x4){0.f, 0.f, 0.f, 0.f};
;                     gc[n] = w0[n] * up + w1[n] * g + w2[n] * dn + bb[n];
;                 }
;                 if (efirst || elast) {
;                     const size_t eo = (size_t)((row >> 6) * 2 + (elast ? 1 : 0)) * DFF + ch0;
; #pragma unroll
;                     for (int n = 0; n < 2; ++n) { *(f32x4*)(EP + eo + 4 * n) = gc[n]; *(f32x4*)(ER + eo + 4 * n) = acc[ai][0][m][n]; *(f32x4*)(EV + eo + 4 * n) = acc[ai][1][m][n]; }
;                 } else {
;                     const f32x4 v0 = acc[ai][1][m][0], v1 = acc[ai][1][m][1];
;                     u32x4 o;
;                     o[0] = pack2(silu_mul(gc[0][0], v0[0]), silu_mul(gc[0][1], v0[1])); o[1] = pack2(silu_mul(gc[0][2], v0[2]), silu_mul(gc[0][3], v0[3]));
;                     o[2] = pack2(silu_mul(gc[1][0], v1[0]), silu_mul(gc[1][1], v1[1])); o[3] = pack2(silu_mul(gc[1][2], v1[2]), silu_mul(gc[1][3], v1[3]));
;                     *(u32x4*)(ACT + (size_t)row * DFF + ch0) = o;
.LBB1_1921:
	s_or_b64 exec, exec, s[28:29]
	s_nop 0
	v_cndmask_b32_e64 v53, v40, v60, s[44:45]
	v_cndmask_b32_e32 v55, v40, v24, vcc
	s_nop 0
	v_cndmask_b32_e32 v56, v41, v25, vcc
	v_mov_b32_dpp v52, v53 row_ror:1 row_mask:0xf bank_mask:0xf
	v_mov_b32_dpp v54, v55 row_ror:15 row_mask:0xf bank_mask:0xf
	v_cndmask_b32_e64 v55, v41, v61, s[44:45]
	v_cndmask_b32_e64 v57, v42, v62, s[44:45]
	v_cndmask_b32_e32 v59, v42, v26, vcc
	v_mov_b32_dpp v53, v55 row_ror:1 row_mask:0xf bank_mask:0xf
	s_nop 0
	v_pk_mul_f32 v[52:53], v[96:97], v[52:53]
	v_mov_b32_dpp v55, v56 row_ror:15 row_mask:0xf bank_mask:0xf
	v_mov_b32_dpp v58, v59 row_ror:15 row_mask:0xf bank_mask:0xf
	v_cndmask_b32_e64 v59, v43, v63, s[44:45]
	v_mov_b32_dpp v56, v57 row_ror:1 row_mask:0xf bank_mask:0xf
	v_pk_fma_f32 v[52:53], v[40:41], v[100:101], v[52:53]
	v_cndmask_b32_e32 v60, v43, v27, vcc
	v_mov_b32_dpp v57, v59 row_ror:1 row_mask:0xf bank_mask:0xf
	v_pk_fma_f32 v[52:53], v[108:109], v[54:55], v[52:53]
	v_pk_mul_f32 v[56:57], v[98:99], v[56:57]
	v_pk_add_f32 v[52:53], v[112:113], v[52:53]
	v_mov_b32_dpp v59, v60 row_ror:15 row_mask:0xf bank_mask:0xf
	v_pk_fma_f32 v[56:57], v[42:43], v[102:103], v[56:57]
	v_mul_f32_e32 v54, 0xbfb8aa3b, v52
	v_pk_fma_f32 v[56:57], v[110:111], v[58:59], v[56:57]
	v_exp_f32_e32 v58, v54
	v_mul_f32_e32 v54, 0xbfb8aa3b, v53
	v_exp_f32_e32 v59, v54
	v_cndmask_b32_e64 v60, v32, v48, s[44:45]
	v_cndmask_b32_e32 v61, v32, v16, vcc
	v_pk_add_f32 v[54:55], v[114:115], v[56:57]
	v_mov_b32_dpp v48, v60 row_ror:1 row_mask:0xf bank_mask:0xf
	v_add_f32_e32 v56, 1.0, v58
	v_add_f32_e32 v57, 1.0, v59
	v_mov_b32_dpp v60, v61 row_ror:15 row_mask:0xf bank_mask:0xf
	v_cndmask_b32_e64 v61, v33, v49, s[44:45]
	v_rcp_f32_e32 v56, v56
	v_rcp_f32_e32 v57, v57
	v_mov_b32_dpp v49, v61 row_ror:1 row_mask:0xf bank_mask:0xf
	v_mul_f32_e32 v58, 0xbfb8aa3b, v54
	v_mul_f32_e32 v59, 0xbfb8aa3b, v55
	v_cndmask_b32_e32 v62, v33, v17, vcc
	v_pk_mul_f32 v[48:49], v[80:81], v[48:49]
	v_exp_f32_e32 v58, v58
	v_exp_f32_e32 v59, v59
	v_mov_b32_dpp v61, v62 row_ror:15 row_mask:0xf bank_mask:0xf
	v_pk_fma_f32 v[48:49], v[32:33], v[84:85], v[48:49]
	v_cndmask_b32_e64 v62, v34, v50, s[44:45]
	v_pk_fma_f32 v[48:49], v[88:89], v[60:61], v[48:49]
	v_pk_mul_f32 v[44:45], v[44:45], v[52:53]
	v_cndmask_b32_e32 v63, v34, v18, vcc
	v_mov_b32_dpp v50, v62 row_ror:1 row_mask:0xf bank_mask:0xf
	v_pk_add_f32 v[48:49], v[92:93], v[48:49]
	v_pk_mul_f32 v[44:45], v[44:45], v[56:57]
	v_mov_b32_dpp v62, v63 row_ror:15 row_mask:0xf bank_mask:0xf
	v_cndmask_b32_e64 v63, v35, v51, s[44:45]
	v_pk_mul_f32 v[46:47], v[46:47], v[54:55]
	v_add_f32_e32 v54, 1.0, v58
	v_add_f32_e32 v55, 1.0, v59
	v_cvt_pk_bf16_f32 v44, v44, v45
	v_mul_f32_e32 v45, 0xbfb8aa3b, v48
	v_mov_b32_dpp v51, v63 row_ror:1 row_mask:0xf bank_mask:0xf
	v_rcp_f32_e32 v54, v54
	v_rcp_f32_e32 v55, v55
	v_exp_f32_e32 v52, v45
	v_mul_f32_e32 v45, 0xbfb8aa3b, v49
	v_cndmask_b32_e32 v64, v35, v19, vcc
	v_pk_mul_f32 v[50:51], v[82:83], v[50:51]
	v_exp_f32_e32 v53, v45
	v_mov_b32_dpp v63, v64 row_ror:15 row_mask:0xf bank_mask:0xf
	v_pk_fma_f32 v[50:51], v[34:35], v[86:87], v[50:51]
	v_pk_mul_f32 v[46:47], v[46:47], v[54:55]
	v_pk_fma_f32 v[50:51], v[90:91], v[62:63], v[50:51]
	v_cvt_pk_bf16_f32 v45, v46, v47
	v_pk_add_f32 v[50:51], v[94:95], v[50:51]
	v_add_f32_e32 v46, 1.0, v52
	v_add_f32_e32 v47, 1.0, v53
	v_mul_f32_e32 v52, 0xbfb8aa3b, v50
	v_mul_f32_e32 v53, 0xbfb8aa3b, v51
	v_exp_f32_e32 v52, v52
	v_exp_f32_e32 v53, v53
	v_rcp_f32_e32 v46, v46
	v_rcp_f32_e32 v47, v47
	v_pk_mul_f32 v[38:39], v[38:39], v[50:51]
	v_add_f32_e32 v50, 1.0, v52
	v_add_f32_e32 v51, 1.0, v53
	v_rcp_f32_e32 v50, v50
	v_rcp_f32_e32 v51, v51
	v_pk_mul_f32 v[36:37], v[36:37], v[48:49]
	v_add_u32_e32 v64, 0x90, v193
	v_pk_mul_f32 v[36:37], v[36:37], v[46:47]
	v_cndmask_b32_e64 v41, v25, v41, s[44:45]
	v_cvt_pk_bf16_f32 v46, v36, v37
	v_pk_mul_f32 v[36:37], v[38:39], v[50:51]
	v_cndmask_b32_e32 v48, v17, v9, vcc
	v_cvt_pk_bf16_f32 v47, v36, v37
	v_mov_b64_e32 v[36:37], s[52:53]
	v_mad_i64_i32 v[38:39], s[28:29], v64, s60, v[36:37]
	v_lshl_add_u64 v[38:39], v[38:39], 0, v[132:133]
	global_store_dwordx4 v[38:39], v[44:47], off
	v_cndmask_b32_e64 v39, v24, v40, s[44:45]
	s_nop 0
	v_cndmask_b32_e32 v44, v24, v12, vcc
	s_nop 0
	v_mov_b32_dpp v38, v39 row_ror:1 row_mask:0xf bank_mask:0xf
	s_nop 0
	v_mov_b32_dpp v40, v44 row_ror:15 row_mask:0xf bank_mask:0xf
	v_cndmask_b32_e32 v44, v25, v13, vcc
	v_mov_b32_dpp v39, v41 row_ror:1 row_mask:0xf bank_mask:0xf
	v_cndmask_b32_e32 v45, v26, v14, vcc
	v_pk_mul_f32 v[38:39], v[96:97], v[38:39]
	v_mov_b32_dpp v41, v44 row_ror:15 row_mask:0xf bank_mask:0xf
	v_cndmask_b32_e64 v44, v26, v42, s[44:45]
	v_pk_fma_f32 v[38:39], v[24:25], v[100:101], v[38:39]
	v_cndmask_b32_e32 v46, v27, v15, vcc
	v_mov_b32_dpp v42, v44 row_ror:1 row_mask:0xf bank_mask:0xf
	v_pk_fma_f32 v[38:39], v[108:109], v[40:41], v[38:39]
	v_cndmask_b32_e32 v47, v16, v8, vcc
	v_mov_b32_dpp v44, v45 row_ror:15 row_mask:0xf bank_mask:0xf
	v_cndmask_b32_e64 v45, v27, v43, s[44:45]
	v_pk_add_f32 v[38:39], v[112:113], v[38:39]
	v_cndmask_b32_e32 v49, v18, v10, vcc
	v_mov_b32_dpp v43, v45 row_ror:1 row_mask:0xf bank_mask:0xf
	v_pk_mul_f32 v[42:43], v[98:99], v[42:43]
	v_mul_f32_e32 v40, 0xbfb8aa3b, v38
	v_mov_b32_dpp v45, v46 row_ror:15 row_mask:0xf bank_mask:0xf
	v_pk_fma_f32 v[42:43], v[26:27], v[102:103], v[42:43]
	v_cndmask_b32_e64 v46, v16, v32, s[44:45]
	v_pk_fma_f32 v[42:43], v[110:111], v[44:45], v[42:43]
	v_exp_f32_e32 v44, v40
	v_mul_f32_e32 v40, 0xbfb8aa3b, v39
	v_exp_f32_e32 v45, v40
	v_pk_add_f32 v[40:41], v[114:115], v[42:43]
	v_add_f32_e32 v42, 1.0, v44
; DI unsigned pack2(float a, float b) { f32x2 v = {a, b}; hwbf16x2 r = __builtin_convertvector(v, hwbf16x2); return __builtin_bit_cast(unsigned, r); }
; DI float dpp_ror1(float v)  { return __builtin_bit_cast(float, __builtin_amdgcn_update_dpp(0, __builtin_bit_cast(int, v), 0x121, 0xf, 0xf, false)); }
; DI float dpp_ror15(float v) { return __builtin_bit_cast(float, __builtin_amdgcn_update_dpp(0, __builtin_bit_cast(int, v), 0x12F, 0xf, 0xf, false)); }
; DI float silu_mul(float g, float v) { return g * v * __builtin_amdgcn_rcpf(1.0f + __builtin_amdgcn_exp2f(-LOG2E * g)); }
;     DI void operator()(const f32x4 (&acc)[2][2][4][2], const Unit& u, int wr, int wc, int fr, int fq) const {
;     ...
;                 for (int n = 0; n < 2; ++n) {
;                     const f32x4 g = acc[ai][0][m][n];
;                     const f32x4 gprev = acc[ai][0][m > 0 ? m - 1 : 0][n], gnext = acc[ai][0][m < 3 ? m + 1 : 3][n];
;                     f32x4 up, dn;
; #pragma unroll
;                     for (int e = 0; e < 4; ++e) {
;                         const float pu = (m > 0 && fr == 15) ? gprev[e] : g[e];
;                         const float pd = (m < 3 && fr == 0) ? gnext[e] : g[e];
;                         up[e] = dpp_ror1(pu); dn[e] = dpp_ror15(pd);
;                     }
;                     if (efirst) up = (f32x4){0.f, 0.f, 0.f, 0.f};
;                     if (elast) dn = (f32x4){0.f, 0.f, 0.f, 0.f};
;                     gc[n] = w0[n] * up + w1[n] * g + w2[n] * dn + bb[n];
;                 }
;                 if (efirst || elast) {
;                     const size_t eo = (size_t)((row >> 6) * 2 + (elast ? 1 : 0)) * DFF + ch0;
; #pragma unroll
;                     for (int n = 0; n < 2; ++n) { *(f32x4*)(EP + eo + 4 * n) = gc[n]; *(f32x4*)(ER + eo + 4 * n) = acc[ai][0][m][n]; *(f32x4*)(EV + eo + 4 * n) = acc[ai][1][m][n]; }
;                 } else {
;                     const f32x4 v0 = acc[ai][1][m][0], v1 = acc[ai][1][m][1];
;                     u32x4 o;
;                     o[0] = pack2(silu_mul(gc[0][0], v0[0]), silu_mul(gc[0][1], v0[1])); o[1] = pack2(silu_mul(gc[0][2], v0[2]), silu_mul(gc[0][3], v0[3]));
;                     o[2] = pack2(silu_mul(gc[1][0], v1[0]), silu_mul(gc[1][1], v1[1])); o[3] = pack2(silu_mul(gc[1][2], v1[2]), silu_mul(gc[1][3], v1[3]));
;                     *(u32x4*)(ACT + (size_t)row * DFF + ch0) = o;
	v_mov_b32_dpp v32, v46 row_ror:1 row_mask:0xf bank_mask:0xf
	v_add_f32_e32 v43, 1.0, v45
	v_rcp_f32_e32 v42, v42
	v_mov_b32_dpp v46, v47 row_ror:15 row_mask:0xf bank_mask:0xf
	v_cndmask_b32_e64 v47, v17, v33, s[44:45]
	v_rcp_f32_e32 v43, v43
	v_mul_f32_e32 v44, 0xbfb8aa3b, v40
	v_mov_b32_dpp v33, v47 row_ror:1 row_mask:0xf bank_mask:0xf
	v_mul_f32_e32 v45, 0xbfb8aa3b, v41
	v_pk_mul_f32 v[32:33], v[80:81], v[32:33]
	v_exp_f32_e32 v44, v44
	v_exp_f32_e32 v45, v45
	v_mov_b32_dpp v47, v48 row_ror:15 row_mask:0xf bank_mask:0xf
	v_pk_fma_f32 v[32:33], v[16:17], v[84:85], v[32:33]
	v_cndmask_b32_e64 v48, v18, v34, s[44:45]
	v_pk_fma_f32 v[32:33], v[88:89], v[46:47], v[32:33]
	v_pk_mul_f32 v[28:29], v[28:29], v[38:39]
	v_mov_b32_dpp v34, v48 row_ror:1 row_mask:0xf bank_mask:0xf
	v_pk_add_f32 v[32:33], v[92:93], v[32:33]
	v_pk_mul_f32 v[28:29], v[28:29], v[42:43]
	v_mov_b32_dpp v48, v49 row_ror:15 row_mask:0xf bank_mask:0xf
	v_cndmask_b32_e64 v49, v19, v35, s[44:45]
	v_pk_mul_f32 v[30:31], v[30:31], v[40:41]
	v_add_f32_e32 v40, 1.0, v44
	v_add_f32_e32 v41, 1.0, v45
	v_cvt_pk_bf16_f32 v28, v28, v29
	v_mul_f32_e32 v29, 0xbfb8aa3b, v32
	v_mov_b32_dpp v35, v49 row_ror:1 row_mask:0xf bank_mask:0xf
	v_rcp_f32_e32 v40, v40
	v_rcp_f32_e32 v41, v41
	v_exp_f32_e32 v38, v29
	v_mul_f32_e32 v29, 0xbfb8aa3b, v33
	v_cndmask_b32_e32 v50, v19, v11, vcc
	v_pk_mul_f32 v[34:35], v[82:83], v[34:35]
	v_exp_f32_e32 v39, v29
	v_mov_b32_dpp v49, v50 row_ror:15 row_mask:0xf bank_mask:0xf
	v_pk_fma_f32 v[34:35], v[18:19], v[86:87], v[34:35]
	v_pk_mul_f32 v[30:31], v[30:31], v[40:41]
	v_pk_fma_f32 v[34:35], v[90:91], v[48:49], v[34:35]
	v_cvt_pk_bf16_f32 v29, v30, v31
	v_pk_add_f32 v[34:35], v[94:95], v[34:35]
	v_add_f32_e32 v30, 1.0, v38
	v_add_f32_e32 v31, 1.0, v39
	v_mul_f32_e32 v38, 0xbfb8aa3b, v34
	v_mul_f32_e32 v39, 0xbfb8aa3b, v35
	v_exp_f32_e32 v38, v38
	v_exp_f32_e32 v39, v39
	v_rcp_f32_e32 v30, v30
	v_rcp_f32_e32 v31, v31
	v_pk_mul_f32 v[22:23], v[22:23], v[34:35]
	v_add_f32_e32 v34, 1.0, v38
	v_add_f32_e32 v35, 1.0, v39
	v_rcp_f32_e32 v34, v34
	v_rcp_f32_e32 v35, v35
	v_pk_mul_f32 v[20:21], v[20:21], v[32:33]
	v_add_u32_e32 v50, 0xa0, v193
	v_pk_mul_f32 v[20:21], v[20:21], v[30:31]
	s_nop 0
	v_cvt_pk_bf16_f32 v30, v20, v21
	v_pk_mul_f32 v[20:21], v[22:23], v[34:35]
	v_cndmask_b32_e64 v22, v13, v25, s[44:45]
	v_cvt_pk_bf16_f32 v31, v20, v21
	v_mad_i64_i32 v[20:21], s[28:29], v50, s60, v[36:37]
	v_lshl_add_u64 v[20:21], v[20:21], 0, v[132:133]
	global_store_dwordx4 v[20:21], v[28:31], off
	v_cndmask_b32_e64 v21, v12, v24, s[44:45]
	v_cndmask_b32_e64 v23, v14, v26, s[44:45]
	v_cndmask_b32_e64 v25, v15, v27, s[44:45]
	v_mov_b32_dpp v20, v21 row_ror:1 row_mask:0xf bank_mask:0xf
	s_nop 0
	s_nop 0
	v_mov_b32_dpp v21, v22 row_ror:1 row_mask:0xf bank_mask:0xf
	v_mov_b32_dpp v24, v14 row_ror:15 row_mask:0xf bank_mask:0xf
	v_cndmask_b32_e64 v24, v24, 0, s[44:45]
	v_mov_b32_dpp v22, v23 row_ror:1 row_mask:0xf bank_mask:0xf
	s_nop 0
	v_mov_b32_dpp v28, v12 row_ror:15 row_mask:0xf bank_mask:0xf
	v_mov_b32_dpp v23, v25 row_ror:1 row_mask:0xf bank_mask:0xf
	v_pk_mul_f32 v[22:23], v[98:99], v[22:23]
	v_mov_b32_dpp v29, v13 row_ror:15 row_mask:0xf bank_mask:0xf
	v_mov_b32_dpp v25, v15 row_ror:15 row_mask:0xf bank_mask:0xf
	v_cndmask_b32_e64 v25, v25, 0, s[44:45]
	v_pk_fma_f32 v[22:23], v[14:15], v[102:103], v[22:23]
	v_pk_mul_f32 v[20:21], v[96:97], v[20:21]
	v_pk_fma_f32 v[22:23], v[110:111], v[24:25], v[22:23]
	v_cndmask_b32_e64 v24, v8, v16, s[44:45]
	v_cndmask_b32_e64 v27, v29, 0, s[44:45]
	v_cndmask_b32_e64 v26, v28, 0, s[44:45]
	v_mov_b32_dpp v16, v24 row_ror:1 row_mask:0xf bank_mask:0xf
	v_cndmask_b32_e64 v24, v9, v17, s[44:45]
	v_pk_fma_f32 v[20:21], v[12:13], v[100:101], v[20:21]
	v_cndmask_b32_e64 v25, v11, v19, s[44:45]
	v_mov_b32_dpp v17, v24 row_ror:1 row_mask:0xf bank_mask:0xf
	v_cndmask_b32_e64 v24, v10, v18, s[44:45]
	s_nop 0
	v_pk_fma_f32 v[20:21], v[108:109], v[26:27], v[20:21]
	v_mov_b32_dpp v18, v24 row_ror:1 row_mask:0xf bank_mask:0xf
	v_mov_b32_dpp v19, v25 row_ror:1 row_mask:0xf bank_mask:0xf
	v_mov_b32_dpp v26, v8 row_ror:15 row_mask:0xf bank_mask:0xf
	v_mov_b32_dpp v27, v9 row_ror:15 row_mask:0xf bank_mask:0xf
	v_mov_b32_dpp v24, v10 row_ror:15 row_mask:0xf bank_mask:0xf
	v_mov_b32_dpp v25, v11 row_ror:15 row_mask:0xf bank_mask:0xf
	v_pk_mul_f32 v[16:17], v[80:81], v[16:17]
	v_pk_mul_f32 v[18:19], v[82:83], v[18:19]
	v_cndmask_b32_e64 v25, v25, 0, s[44:45]
	v_cndmask_b32_e64 v24, v24, 0, s[44:45]
	v_cndmask_b32_e64 v27, v27, 0, s[44:45]
	v_cndmask_b32_e64 v26, v26, 0, s[44:45]
	v_pk_fma_f32 v[18:19], v[10:11], v[86:87], v[18:19]
	v_pk_fma_f32 v[16:17], v[8:9], v[84:85], v[16:17]
	v_pk_fma_f32 v[18:19], v[90:91], v[24:25], v[18:19]
	v_pk_fma_f32 v[16:17], v[88:89], v[26:27], v[16:17]
	v_pk_add_f32 v[22:23], v[114:115], v[22:23]
	v_pk_add_f32 v[20:21], v[112:113], v[20:21]
	v_pk_add_f32 v[18:19], v[94:95], v[18:19]
	v_pk_add_f32 v[16:17], v[92:93], v[16:17]
	v_add_u32_e32 v24, 0xb0, v193
	s_and_saveexec_b64 s[28:29], s[42:43]
	s_xor_b64 s[28:29], exec, s[28:29]
	s_cbranch_execz .LBB1_1923
	v_mul_f32_e32 v25, 0xbfb8aa3b, v20
	v_exp_f32_e32 v25, v25
	v_mul_f32_e32 v26, 0xbfb8aa3b, v21
	v_exp_f32_e32 v26, v26
	v_mul_f32_e32 v28, 0xbfb8aa3b, v23
	v_add_f32_e32 v25, 1.0, v25
	v_exp_f32_e32 v29, v28
	v_add_f32_e32 v27, 1.0, v26
	v_rcp_f32_e32 v26, v25
	v_mul_f32_e32 v25, 0xbfb8aa3b, v22
	v_exp_f32_e32 v25, v25
	v_rcp_f32_e32 v27, v27
	v_pk_mul_f32 v[20:21], v[4:5], v[20:21]
	v_pk_mul_f32 v[22:23], v[6:7], v[22:23]
	v_add_f32_e32 v25, 1.0, v25
	v_rcp_f32_e32 v28, v25
	v_add_f32_e32 v25, 1.0, v29
	v_pk_mul_f32 v[20:21], v[20:21], v[26:27]
	v_rcp_f32_e32 v29, v25
	v_cvt_pk_bf16_f32 v20, v20, v21
	v_mul_f32_e32 v21, 0xbfb8aa3b, v16
	v_exp_f32_e32 v25, v21
	v_mul_f32_e32 v21, 0xbfb8aa3b, v17
	v_exp_f32_e32 v26, v21
	v_pk_mul_f32 v[22:23], v[22:23], v[28:29]
	v_pk_mul_f32 v[16:17], v[0:1], v[16:17]
	v_cvt_pk_bf16_f32 v21, v22, v23
	v_add_f32_e32 v22, 1.0, v25
	v_mul_f32_e32 v25, 0xbfb8aa3b, v18
	v_add_f32_e32 v23, 1.0, v26
	v_exp_f32_e32 v25, v25
	v_mul_f32_e32 v26, 0xbfb8aa3b, v19
	v_exp_f32_e32 v27, v26
	v_rcp_f32_e32 v22, v22
	v_add_f32_e32 v25, 1.0, v25
	v_rcp_f32_e32 v23, v23
	v_rcp_f32_e32 v26, v25
	v_add_f32_e32 v25, 1.0, v27
	v_rcp_f32_e32 v27, v25
	v_pk_mul_f32 v[18:19], v[2:3], v[18:19]
	v_pk_mul_f32 v[16:17], v[16:17], v[22:23]
	s_nop 0
	v_cvt_pk_bf16_f32 v22, v16, v17
	v_pk_mul_f32 v[16:17], v[18:19], v[26:27]
	s_nop 0
	v_cvt_pk_bf16_f32 v23, v16, v17
	v_mov_b64_e32 v[16:17], s[52:53]
	v_mad_i64_i32 v[16:17], s[42:43], v24, s60, v[16:17]
	v_lshl_add_u64 v[16:17], v[184:185], 1, v[16:17]
	global_store_dwordx4 v[16:17], v[20:23], off

; #define PG8_STAGE(bufoff, gbase, voff) do { _Pragma("unroll") for (int _i = 0; _i < 2; ++_i) \
;         __builtin_amdgcn_global_load_lds((const unsigned*)((const char*)(gbase) + (voff)[_i]), (LAS unsigned*)(lds + (bufoff) + ldsw + _i * 8192), 16, 0, 0); } while (0)
; #define PG8_LDA(dst, b, h) do { _Pragma("unroll") for (int m = 0; m < 4; ++m) _Pragma("unroll") for (int k = 0; k < 2; ++k) dst[m][k] = *(const LAS bf16x8*)(lds + PG8_SA(b, h) + aoff + m * 2048 + k * 1024); } while (0)
; #define PG8_LDB(dst, b, h) do { _Pragma("unroll") for (int n = 0; n < 2; ++n) _Pragma("unroll") for (int k = 0; k < 2; ++k) dst[n][k] = *(const LAS bf16x8*)(lds + PG8_SB(b, h) + boff + n * 2048 + k * 1024); } while (0)
; #define PG8_MMA(ai, bj, At, Bt) do { __builtin_amdgcn_s_setprio(1); _Pragma("unroll") for (int m = 0; m < 4; ++m) _Pragma("unroll") for (int n = 0; n < 2; ++n) _Pragma("unroll") for (int k = 0; k < 2; ++k) \
;         acc[ai][bj][m][n] = __builtin_amdgcn_mfma_f32_16x16x32_bf16(Bt[n][k], At[m][k], acc[ai][bj][m][n], 0, 0, 0); __builtin_amdgcn_s_setprio(0); } while (0)
; #define PG8_WAIT_V(n) asm volatile("s_waitcnt vmcnt(" #n ")" ::: "memory")
; #define PG8_BAR __builtin_amdgcn_s_barrier()
; template <class Map, class Epi>
; DI void gemm_phase(LAS unsigned char* lds, const Map& MP, const Epi& E, const int nM, const int nN, const int K, const int lda, const int ldb) {
;     ...
;             const char* a1 = cA + (size_t)(t + 1) * kstep;
;             const char* a2 = last ? nA : cA + (size_t)(t + 2) * kstep; const char* b2 = last ? nB : cB + (size_t)(t + 2) * kstep;
;             const char* a3 = a2 + kstep; const char* b3 = b2 + kstep;
;             PG8_LDB(B0, 0, 0); PG8_SCHED; PG8_LDA(At, 0, 0); PG8_STAGE(PG8_SA(1, 1), a1 + hstepA, voffA);
;             PG8_WAIT_L(8); PG8_BAR; PG8_WAIT_L(0); PG8_MMA(0, 0, At, B0); PG8_BAR; PG8_SCHED;
;             PG8_LDB(B1, 0, 1); PG8_STAGE(PG8_SB(0, 0), b2, voffB);
;             PG8_BAR; PG8_WAIT_L(0); PG8_MMA(0, 1, At, B1); PG8_BAR;
;             PG8_LDA(At, 0, 1); PG8_STAGE(PG8_SA(0, 0), a2, voffA);
;             PG8_BAR; PG8_WAIT_L(0); PG8_MMA(1, 0, At, B0); PG8_BAR; PG8_SCHED;
;             PG8_STAGE(PG8_SB(0, 1), b2 + hstepB, voffB);
;             PG8_WAIT_V(6); PG8_BAR; PG8_MMA(1, 1, At, B1); PG8_BAR;
;             PG8_LDB(B0, 1, 0); PG8_SCHED; PG8_LDA(At, 1, 0); PG8_STAGE(PG8_SA(0, 1), a2 + hstepA, voffA);
.LBB1_2483:
	s_add_u32 s28, s42, 0xfff80080
	s_addc_u32 s29, s43, -1
	s_cmp_eq_u32 s3, 28
	s_cselect_b32 s47, s23, s29
	s_cselect_b32 s46, s58, s28
	s_cselect_b32 s29, s21, vcc_hi
	s_cselect_b32 s28, s59, vcc_lo
	s_add_i32 m0, s38, 0xc000
	ds_read_b128 v[96:99], v190
	ds_read_b128 v[100:103], v190 offset:1024
	ds_read_b128 v[108:111], v190 offset:2048
	ds_read_b128 v[112:115], v190 offset:3072
	ds_read_b128 v[160:163], v190 offset:4096
	ds_read_b128 v[164:167], v190 offset:5120
	ds_read_b128 v[198:201], v190 offset:6144
	ds_read_b128 v[202:205], v190 offset:7168
	global_load_lds_dwordx4 v178, s[42:43]
	s_add_i32 m0, s38, 0xe000
	s_nop 0
	global_load_lds_dwordx4 v176, s[42:43]
	s_waitcnt lgkmcnt(8)
	s_setprio 1
	s_barrier
	s_waitcnt lgkmcnt(7)
	v_mfma_f32_16x16x32_bf16 v[148:151], v[80:83], v[96:99], v[148:151]
	v_mfma_f32_16x16x32_bf16 v[144:147], v[88:91], v[96:99], v[144:147]
	s_waitcnt lgkmcnt(5)
	v_mfma_f32_16x16x32_bf16 v[136:139], v[80:83], v[108:111], v[136:139]
	v_mfma_f32_16x16x32_bf16 v[128:131], v[88:91], v[108:111], v[128:131]
	s_waitcnt lgkmcnt(3)
	v_mfma_f32_16x16x32_bf16 v[120:123], v[80:83], v[160:163], v[120:123]
	v_mfma_f32_16x16x32_bf16 v[104:107], v[88:91], v[160:163], v[104:107]
	s_waitcnt lgkmcnt(1)
	v_mfma_f32_16x16x32_bf16 v[76:79], v[80:83], v[198:201], v[76:79]
	v_mfma_f32_16x16x32_bf16 v[72:75], v[88:91], v[198:201], v[72:75]
	v_mfma_f32_16x16x32_bf16 v[148:151], v[84:87], v[100:103], v[148:151]
	v_mfma_f32_16x16x32_bf16 v[144:147], v[92:95], v[100:103], v[144:147]
	v_mfma_f32_16x16x32_bf16 v[136:139], v[84:87], v[112:115], v[136:139]
	v_mfma_f32_16x16x32_bf16 v[128:131], v[92:95], v[112:115], v[128:131]
	v_mfma_f32_16x16x32_bf16 v[120:123], v[84:87], v[164:167], v[120:123]
	v_mfma_f32_16x16x32_bf16 v[104:107], v[92:95], v[164:167], v[104:107]
	s_waitcnt lgkmcnt(0)
	v_mfma_f32_16x16x32_bf16 v[76:79], v[84:87], v[202:205], v[76:79]
	v_mfma_f32_16x16x32_bf16 v[72:75], v[92:95], v[202:205], v[72:75]
	s_barrier
	s_setprio 0
	s_add_i32 s68, s2, s37
	v_lshl_add_u64 v[184:185], s[28:29], 0, v[172:173]
	s_mov_b32 m0, s68
	ds_read_b128 v[206:209], v191
	ds_read_b128 v[210:213], v191 offset:1024
	ds_read_b128 v[214:217], v191 offset:2048
	ds_read_b128 v[218:221], v191 offset:3072
	global_load_lds_dwordx4 v[184:185], off
	v_lshl_add_u64 v[194:195], s[28:29], 0, v[168:169]
	s_add_i32 m0, s68, 0x2000
	s_nop 0
	global_load_lds_dwordx4 v[194:195], off
	s_setprio 1
	s_barrier
	s_waitcnt lgkmcnt(3)
	v_mfma_f32_16x16x32_bf16 v[156:159], v[206:209], v[96:99], v[156:159]
	s_waitcnt lgkmcnt(1)
	v_mfma_f32_16x16x32_bf16 v[96:99], v[214:217], v[96:99], v[152:155]
	v_mfma_f32_16x16x32_bf16 v[156:159], v[210:213], v[100:103], v[156:159]
	s_waitcnt lgkmcnt(0)
	v_mfma_f32_16x16x32_bf16 v[96:99], v[218:221], v[100:103], v[96:99]
	v_mfma_f32_16x16x32_bf16 v[100:103], v[206:209], v[108:111], v[140:143]
	v_mfma_f32_16x16x32_bf16 v[108:111], v[214:217], v[108:111], v[132:135]
	v_mfma_f32_16x16x32_bf16 v[116:119], v[214:217], v[160:163], v[116:119]
	v_mfma_f32_16x16x32_bf16 v[68:71], v[206:209], v[198:201], v[68:71]
	v_mfma_f32_16x16x32_bf16 v[64:67], v[214:217], v[198:201], v[64:67]
	s_mov_b32 m0, s38
	v_mfma_f32_16x16x32_bf16 v[100:103], v[210:213], v[112:115], v[100:103]
	v_lshl_add_u64 v[230:231], s[46:47], 0, v[174:175]
	v_mfma_f32_16x16x32_bf16 v[108:111], v[218:221], v[112:115], v[108:111]
	v_mfma_f32_16x16x32_bf16 v[112:115], v[206:209], v[160:163], v[124:127]
	v_mfma_f32_16x16x32_bf16 v[116:119], v[218:221], v[164:167], v[116:119]
	v_mfma_f32_16x16x32_bf16 v[68:71], v[210:213], v[202:205], v[68:71]
	v_mfma_f32_16x16x32_bf16 v[64:67], v[218:221], v[202:205], v[64:67]
	v_mfma_f32_16x16x32_bf16 v[112:115], v[210:213], v[164:167], v[112:115]
	s_barrier
	s_setprio 0
	ds_read_b128 v[124:127], v190 offset:16384
	ds_read_b128 v[132:135], v190 offset:17408
	ds_read_b128 v[140:143], v190 offset:18432
	ds_read_b128 v[152:155], v190 offset:19456
	ds_read_b128 v[160:163], v190 offset:20480
	ds_read_b128 v[164:167], v190 offset:21504
	ds_read_b128 v[198:201], v190 offset:22528
	ds_read_b128 v[202:205], v190 offset:23552
	global_load_lds_dwordx4 v[230:231], off
	v_lshl_add_u64 v[232:233], s[46:47], 0, v[170:171]
	s_mov_b32 m0, s39
	s_nop 0
	global_load_lds_dwordx4 v[232:233], off
	s_waitcnt vmcnt(10)
	s_setprio 1
	s_barrier
	s_waitcnt lgkmcnt(7)
	v_mfma_f32_16x16x32_bf16 v[60:63], v[80:83], v[124:127], v[60:63]
	v_mfma_f32_16x16x32_bf16 v[48:51], v[88:91], v[124:127], v[48:51]
	s_waitcnt lgkmcnt(5)
	v_mfma_f32_16x16x32_bf16 v[40:43], v[80:83], v[140:143], v[40:43]
	v_mfma_f32_16x16x32_bf16 v[32:35], v[88:91], v[140:143], v[32:35]
	s_waitcnt lgkmcnt(3)
	v_mfma_f32_16x16x32_bf16 v[24:27], v[80:83], v[160:163], v[24:27]
	v_mfma_f32_16x16x32_bf16 v[16:19], v[88:91], v[160:163], v[16:19]
	s_waitcnt lgkmcnt(1)
	v_mfma_f32_16x16x32_bf16 v[12:15], v[80:83], v[198:201], v[12:15]
	v_mfma_f32_16x16x32_bf16 v[8:11], v[88:91], v[198:201], v[8:11]
	v_mfma_f32_16x16x32_bf16 v[60:63], v[84:87], v[132:135], v[60:63]
	v_mfma_f32_16x16x32_bf16 v[48:51], v[92:95], v[132:135], v[48:51]
	v_mfma_f32_16x16x32_bf16 v[40:43], v[84:87], v[152:155], v[40:43]
	v_mfma_f32_16x16x32_bf16 v[32:35], v[92:95], v[152:155], v[32:35]
	v_mfma_f32_16x16x32_bf16 v[24:27], v[84:87], v[164:167], v[24:27]
	v_mfma_f32_16x16x32_bf16 v[16:19], v[92:95], v[164:167], v[16:19]
	s_waitcnt lgkmcnt(0)
	v_mfma_f32_16x16x32_bf16 v[12:15], v[84:87], v[202:205], v[12:15]
	v_mfma_f32_16x16x32_bf16 v[8:11], v[92:95], v[202:205], v[8:11]
	s_barrier
	s_setprio 0
	s_add_u32 s68, s28, 0x80000
	s_addc_u32 s69, s29, 0
	s_add_i32 s70, s67, s37
	s_mov_b32 m0, s70
	s_nop 0
	global_load_lds_dwordx4 v172, s[68:69]
	s_add_i32 m0, s70, 0x2000
	s_nop 0
	global_load_lds_dwordx4 v168, s[68:69]
	s_waitcnt vmcnt(6)
	s_setprio 1
	s_barrier
; #define PG8_STAGE(bufoff, gbase, voff) do { _Pragma("unroll") for (int _i = 0; _i < 2; ++_i) \
;         __builtin_amdgcn_global_load_lds((const unsigned*)((const char*)(gbase) + (voff)[_i]), (LAS unsigned*)(lds + (bufoff) + ldsw + _i * 8192), 16, 0, 0); } while (0)
; #define PG8_LDA(dst, b, h) do { _Pragma("unroll") for (int m = 0; m < 4; ++m) _Pragma("unroll") for (int k = 0; k < 2; ++k) dst[m][k] = *(const LAS bf16x8*)(lds + PG8_SA(b, h) + aoff + m * 2048 + k * 1024); } while (0)
; #define PG8_LDB(dst, b, h) do { _Pragma("unroll") for (int n = 0; n < 2; ++n) _Pragma("unroll") for (int k = 0; k < 2; ++k) dst[n][k] = *(const LAS bf16x8*)(lds + PG8_SB(b, h) + boff + n * 2048 + k * 1024); } while (0)
; #define PG8_MMA(ai, bj, At, Bt) do { __builtin_amdgcn_s_setprio(1); _Pragma("unroll") for (int m = 0; m < 4; ++m) _Pragma("unroll") for (int n = 0; n < 2; ++n) _Pragma("unroll") for (int k = 0; k < 2; ++k) \
;         acc[ai][bj][m][n] = __builtin_amdgcn_mfma_f32_16x16x32_bf16(Bt[n][k], At[m][k], acc[ai][bj][m][n], 0, 0, 0); __builtin_amdgcn_s_setprio(0); } while (0)
; #define PG8_WAIT_V(n) asm volatile("s_waitcnt vmcnt(" #n ")" ::: "memory")
; #define PG8_WAIT_L(n) asm volatile("s_waitcnt lgkmcnt(" #n ")" ::: "memory")
; #define PG8_BAR __builtin_amdgcn_s_barrier()
; #define PG8_SCHED __builtin_amdgcn_sched_barrier(0)
; template <class Map, class Epi>
; DI void gemm_phase(LAS unsigned char* lds, const Map& MP, const Epi& E, const int nM, const int nN, const int K, const int lda, const int ldb) {
;     ...
;             PG8_WAIT_V(6); PG8_BAR; PG8_MMA(1, 1, At, B1); PG8_BAR;
;             PG8_LDB(B0, 1, 0); PG8_SCHED; PG8_LDA(At, 1, 0); PG8_STAGE(PG8_SA(0, 1), a2 + hstepA, voffA);
;             PG8_WAIT_L(8); PG8_BAR; PG8_WAIT_L(0); PG8_MMA(0, 0, At, B0); PG8_BAR; PG8_SCHED;
;             PG8_LDB(B1, 1, 1); PG8_STAGE(PG8_SB(1, 0), b3, voffB);
;             PG8_BAR; PG8_WAIT_L(0); PG8_MMA(0, 1, At, B1); PG8_BAR;
;             PG8_LDA(At, 1, 1); PG8_STAGE(PG8_SA(1, 0), a3, voffA);
;             PG8_BAR; PG8_WAIT_L(0); PG8_MMA(1, 0, At, B0); PG8_BAR; PG8_SCHED;
	v_mfma_f32_16x16x32_bf16 v[56:59], v[206:209], v[124:127], v[56:59]
	v_mfma_f32_16x16x32_bf16 v[52:55], v[214:217], v[124:127], v[52:55]
	s_add_i32 s68, 0, 0x18000
	v_add_u32_e32 v92, s68, v188
	ds_read_b128 v[80:83], v92
	v_mfma_f32_16x16x32_bf16 v[44:47], v[206:209], v[140:143], v[44:47]
	v_mfma_f32_16x16x32_bf16 v[36:39], v[214:217], v[140:143], v[36:39]
	ds_read_b128 v[84:87], v92 offset:1024
	v_mfma_f32_16x16x32_bf16 v[28:31], v[206:209], v[160:163], v[28:31]
	v_mfma_f32_16x16x32_bf16 v[20:23], v[214:217], v[160:163], v[20:23]
	ds_read_b128 v[88:91], v92 offset:2048
	v_mfma_f32_16x16x32_bf16 v[4:7], v[206:209], v[198:201], v[4:7]
	v_mfma_f32_16x16x32_bf16 v[0:3], v[214:217], v[198:201], v[0:3]
	ds_read_b128 v[92:95], v92 offset:3072
	v_mfma_f32_16x16x32_bf16 v[56:59], v[210:213], v[132:135], v[56:59]
	v_mfma_f32_16x16x32_bf16 v[52:55], v[218:221], v[132:135], v[52:55]
	v_mfma_f32_16x16x32_bf16 v[44:47], v[210:213], v[152:155], v[44:47]
	v_mfma_f32_16x16x32_bf16 v[36:39], v[218:221], v[152:155], v[36:39]
	v_mfma_f32_16x16x32_bf16 v[28:31], v[210:213], v[164:167], v[28:31]
	v_mfma_f32_16x16x32_bf16 v[20:23], v[218:221], v[164:167], v[20:23]
	v_mfma_f32_16x16x32_bf16 v[4:7], v[210:213], v[202:205], v[4:7]
	v_mfma_f32_16x16x32_bf16 v[0:3], v[218:221], v[202:205], v[0:3]
	s_barrier
	s_setprio 0
	s_add_u32 s46, s46, 0x80000
	s_addc_u32 s47, s47, 0
	s_mov_b32 m0, s55
	ds_read_b128 v[124:127], v190 offset:32768
	ds_read_b128 v[132:135], v190 offset:33792
	ds_read_b128 v[160:163], v190 offset:34816
	ds_read_b128 v[164:167], v190 offset:35840
	ds_read_b128 v[198:201], v190 offset:36864
	ds_read_b128 v[202:205], v190 offset:37888
	ds_read_b128 v[206:209], v190 offset:38912
	ds_read_b128 v[210:213], v190 offset:39936
	global_load_lds_dwordx4 v174, s[46:47]
	s_mov_b32 m0, s56
	s_nop 0
	global_load_lds_dwordx4 v170, s[46:47]
	s_waitcnt lgkmcnt(8)
	s_setprio 1
	s_barrier
	s_waitcnt lgkmcnt(7)
	v_mfma_f32_16x16x32_bf16 v[140:143], v[80:83], v[124:127], v[148:151]
	s_waitcnt lgkmcnt(6)
	v_mfma_f32_16x16x32_bf16 v[148:151], v[84:87], v[132:135], v[140:143]
	v_mfma_f32_16x16x32_bf16 v[140:143], v[88:91], v[124:127], v[144:147]
	s_waitcnt lgkmcnt(5)
	v_mfma_f32_16x16x32_bf16 v[136:139], v[80:83], v[160:163], v[136:139]
	v_mfma_f32_16x16x32_bf16 v[128:131], v[88:91], v[160:163], v[128:131]
	s_waitcnt lgkmcnt(3)
	v_mfma_f32_16x16x32_bf16 v[120:123], v[80:83], v[198:201], v[120:123]
	v_mfma_f32_16x16x32_bf16 v[104:107], v[88:91], v[198:201], v[104:107]
	s_waitcnt lgkmcnt(1)
	v_mfma_f32_16x16x32_bf16 v[76:79], v[80:83], v[206:209], v[76:79]
	v_mfma_f32_16x16x32_bf16 v[72:75], v[88:91], v[206:209], v[72:75]
	v_mfma_f32_16x16x32_bf16 v[144:147], v[92:95], v[132:135], v[140:143]
	v_mfma_f32_16x16x32_bf16 v[136:139], v[84:87], v[164:167], v[136:139]
	v_mfma_f32_16x16x32_bf16 v[128:131], v[92:95], v[164:167], v[128:131]
	v_mfma_f32_16x16x32_bf16 v[120:123], v[84:87], v[202:205], v[120:123]
	v_mfma_f32_16x16x32_bf16 v[104:107], v[92:95], v[202:205], v[104:107]
	s_waitcnt lgkmcnt(0)
	v_mfma_f32_16x16x32_bf16 v[76:79], v[84:87], v[210:213], v[76:79]
	v_mfma_f32_16x16x32_bf16 v[72:75], v[92:95], v[210:213], v[72:75]
	s_barrier
	s_setprio 0
	s_add_i32 s46, 0, 0x1c000
	v_add_u32_e32 v140, s46, v188
	s_add_i32 s47, s68, s37
	ds_read_b128 v[214:217], v140
	ds_read_b128 v[218:221], v140 offset:1024
	ds_read_b128 v[222:225], v140 offset:2048
	ds_read_b128 v[226:229], v140 offset:3072
	v_lshl_add_u64 v[140:141], v[184:185], 0, s[14:15]
	s_mov_b32 m0, s47
	s_nop 0
	global_load_lds_dwordx4 v[140:141], off
	v_lshl_add_u64 v[140:141], v[194:195], 0, s[14:15]
	s_add_i32 m0, s47, 0x2000
	s_nop 0
	global_load_lds_dwordx4 v[140:141], off
	s_setprio 1
	s_barrier
	s_waitcnt lgkmcnt(1)
	v_mfma_f32_16x16x32_bf16 v[96:99], v[222:225], v[124:127], v[96:99]
	v_mfma_f32_16x16x32_bf16 v[140:143], v[214:217], v[124:127], v[156:159]
	s_waitcnt lgkmcnt(0)
	v_mfma_f32_16x16x32_bf16 v[152:155], v[226:229], v[132:135], v[96:99]
	v_mfma_f32_16x16x32_bf16 v[96:99], v[214:217], v[160:163], v[100:103]
	v_mfma_f32_16x16x32_bf16 v[156:159], v[218:221], v[132:135], v[140:143]
	v_mfma_f32_16x16x32_bf16 v[140:143], v[218:221], v[164:167], v[96:99]
	v_mfma_f32_16x16x32_bf16 v[96:99], v[222:225], v[160:163], v[108:111]
	v_mfma_f32_16x16x32_bf16 v[132:135], v[226:229], v[164:167], v[96:99]
	v_mfma_f32_16x16x32_bf16 v[96:99], v[214:217], v[198:201], v[112:115]
	s_mov_b32 m0, s62
	v_mfma_f32_16x16x32_bf16 v[124:127], v[218:221], v[202:205], v[96:99]
	v_lshl_add_u64 v[184:185], v[230:231], 0, s[14:15]
	v_mfma_f32_16x16x32_bf16 v[96:99], v[222:225], v[198:201], v[116:119]
	v_mfma_f32_16x16x32_bf16 v[68:71], v[214:217], v[206:209], v[68:71]
	v_mfma_f32_16x16x32_bf16 v[64:67], v[222:225], v[206:209], v[64:67]
	v_mfma_f32_16x16x32_bf16 v[116:119], v[226:229], v[202:205], v[96:99]
	v_mfma_f32_16x16x32_bf16 v[68:71], v[218:221], v[210:213], v[68:71]
	v_mfma_f32_16x16x32_bf16 v[64:67], v[226:229], v[210:213], v[64:67]
	s_barrier
	s_setprio 0
	ds_read_b128 v[96:99], v190 offset:49152
	ds_read_b128 v[100:103], v190 offset:50176
	ds_read_b128 v[108:111], v190 offset:51200
	ds_read_b128 v[112:115], v190 offset:52224
	ds_read_b128 v[160:163], v190 offset:53248
	ds_read_b128 v[164:167], v190 offset:54272
	ds_read_b128 v[198:201], v190 offset:55296
	ds_read_b128 v[202:205], v190 offset:56320
	global_load_lds_dwordx4 v[184:185], off
	v_lshl_add_u64 v[184:185], v[232:233], 0, s[14:15]
	s_mov_b32 m0, s63
	s_nop 0
	global_load_lds_dwordx4 v[184:185], off
	s_waitcnt vmcnt(10)
	s_setprio 1
	s_barrier
; #define PG8_STAGE(bufoff, gbase, voff) do { _Pragma("unroll") for (int _i = 0; _i < 2; ++_i) \
;         __builtin_amdgcn_global_load_lds((const unsigned*)((const char*)(gbase) + (voff)[_i]), (LAS unsigned*)(lds + (bufoff) + ldsw + _i * 8192), 16, 0, 0); } while (0)
; #define PG8_LDA(dst, b, h) do { _Pragma("unroll") for (int m = 0; m < 4; ++m) _Pragma("unroll") for (int k = 0; k < 2; ++k) dst[m][k] = *(const LAS bf16x8*)(lds + PG8_SA(b, h) + aoff + m * 2048 + k * 1024); } while (0)
; #define PG8_MMA(ai, bj, At, Bt) do { __builtin_amdgcn_s_setprio(1); _Pragma("unroll") for (int m = 0; m < 4; ++m) _Pragma("unroll") for (int n = 0; n < 2; ++n) _Pragma("unroll") for (int k = 0; k < 2; ++k) \
;         acc[ai][bj][m][n] = __builtin_amdgcn_mfma_f32_16x16x32_bf16(Bt[n][k], At[m][k], acc[ai][bj][m][n], 0, 0, 0); __builtin_amdgcn_s_setprio(0); } while (0)
; #define PG8_WAIT_V(n) asm volatile("s_waitcnt vmcnt(" #n ")" ::: "memory")
; #define PG8_WAIT_L(n) asm volatile("s_waitcnt lgkmcnt(" #n ")" ::: "memory")
; #define PG8_BAR __builtin_amdgcn_s_barrier()
; #define PG8_SCHED __builtin_amdgcn_sched_barrier(0)
; template <class Map, class Epi>
; DI void gemm_phase(LAS unsigned char* lds, const Map& MP, const Epi& E, const int nM, const int nN, const int K, const int lda, const int ldb) {
;     ...
;             PG8_LDA(At, 1, 1); PG8_STAGE(PG8_SA(1, 0), a3, voffA);
;             PG8_BAR; PG8_WAIT_L(0); PG8_MMA(1, 0, At, B0); PG8_BAR; PG8_SCHED;
;             PG8_STAGE(PG8_SB(1, 1), b3 + hstepB, voffB);
;             PG8_WAIT_V(6); PG8_BAR; PG8_MMA(1, 1, At, B1); PG8_BAR;
	s_waitcnt lgkmcnt(7)
	v_mfma_f32_16x16x32_bf16 v[60:63], v[80:83], v[96:99], v[60:63]
	v_mfma_f32_16x16x32_bf16 v[48:51], v[88:91], v[96:99], v[48:51]
	s_waitcnt lgkmcnt(5)
	v_mfma_f32_16x16x32_bf16 v[40:43], v[80:83], v[108:111], v[40:43]
	v_mfma_f32_16x16x32_bf16 v[32:35], v[88:91], v[108:111], v[32:35]
	s_waitcnt lgkmcnt(3)
	v_mfma_f32_16x16x32_bf16 v[24:27], v[80:83], v[160:163], v[24:27]
	v_mfma_f32_16x16x32_bf16 v[16:19], v[88:91], v[160:163], v[16:19]
	s_waitcnt lgkmcnt(1)
	v_mfma_f32_16x16x32_bf16 v[12:15], v[80:83], v[198:201], v[12:15]
	v_mfma_f32_16x16x32_bf16 v[8:11], v[88:91], v[198:201], v[8:11]
	v_mfma_f32_16x16x32_bf16 v[60:63], v[84:87], v[100:103], v[60:63]
	v_mfma_f32_16x16x32_bf16 v[48:51], v[92:95], v[100:103], v[48:51]
	v_mfma_f32_16x16x32_bf16 v[40:43], v[84:87], v[112:115], v[40:43]
	v_mfma_f32_16x16x32_bf16 v[32:35], v[92:95], v[112:115], v[32:35]
	v_mfma_f32_16x16x32_bf16 v[24:27], v[84:87], v[164:167], v[24:27]
	v_mfma_f32_16x16x32_bf16 v[16:19], v[92:95], v[164:167], v[16:19]
	s_waitcnt lgkmcnt(0)
	v_mfma_f32_16x16x32_bf16 v[12:15], v[84:87], v[202:205], v[12:15]
	v_mfma_f32_16x16x32_bf16 v[8:11], v[92:95], v[202:205], v[8:11]
	s_barrier
	s_setprio 0
	s_add_u32 s28, s28, 0x80080
	s_addc_u32 s29, s29, 0
	s_add_i32 s46, s46, s37
	s_mov_b32 m0, s46
	s_nop 0
	global_load_lds_dwordx4 v172, s[28:29]
	s_add_i32 m0, s46, 0x2000
	s_nop 0
	global_load_lds_dwordx4 v168, s[28:29]
	s_waitcnt vmcnt(6)
	s_setprio 1
	s_barrier
	v_mfma_f32_16x16x32_bf16 v[56:59], v[214:217], v[96:99], v[56:59]
	v_mfma_f32_16x16x32_bf16 v[52:55], v[222:225], v[96:99], v[52:55]
	ds_read_b128 v[80:83], v189
	v_mfma_f32_16x16x32_bf16 v[44:47], v[214:217], v[108:111], v[44:47]
	v_mfma_f32_16x16x32_bf16 v[36:39], v[222:225], v[108:111], v[36:39]
	ds_read_b128 v[84:87], v189 offset:1024
	v_mfma_f32_16x16x32_bf16 v[28:31], v[214:217], v[160:163], v[28:31]
	v_mfma_f32_16x16x32_bf16 v[20:23], v[222:225], v[160:163], v[20:23]
	ds_read_b128 v[88:91], v189 offset:2048
	v_mfma_f32_16x16x32_bf16 v[4:7], v[214:217], v[198:201], v[4:7]
	v_mfma_f32_16x16x32_bf16 v[0:3], v[222:225], v[198:201], v[0:3]
	ds_read_b128 v[92:95], v189 offset:3072
	v_mfma_f32_16x16x32_bf16 v[56:59], v[218:221], v[100:103], v[56:59]
	s_add_i32 s3, s3, 2
	v_mfma_f32_16x16x32_bf16 v[52:55], v[226:229], v[100:103], v[52:55]
	s_add_u32 vcc_lo, vcc_lo, 0x100
	s_addc_u32 vcc_hi, vcc_hi, 0
	v_mfma_f32_16x16x32_bf16 v[44:47], v[218:221], v[112:115], v[44:47]
	s_add_u32 s42, s42, 0x100
	s_addc_u32 s43, s43, 0
	v_mfma_f32_16x16x32_bf16 v[36:39], v[226:229], v[112:115], v[36:39]
	s_cmp_gt_u32 s3, 29
	v_mfma_f32_16x16x32_bf16 v[28:31], v[218:221], v[164:167], v[28:31]
	v_mfma_f32_16x16x32_bf16 v[20:23], v[226:229], v[164:167], v[20:23]
	v_mfma_f32_16x16x32_bf16 v[4:7], v[218:221], v[202:205], v[4:7]
	v_mfma_f32_16x16x32_bf16 v[0:3], v[226:229], v[202:205], v[0:3]
	s_barrier
	s_setprio 0
	s_cbranch_scc0 .LBB1_2483
; DI float silu_mul(float g, float v) { return g * v * __builtin_amdgcn_rcpf(1.0f + __builtin_amdgcn_exp2f(-LOG2E * g)); }
;     DI void operator()(const f32x4 (&acc)[2][2][4][2], const Unit& u, int wr, int wc, int fr, int fq) const {
;         const int row0 = u.pm * BM + wr * 64 + fr, ch0 = u.pn * 128 + wc * 32 + 8 * fq;
;         f32x4 w0[2], w1[2], w2[2], bb[2];
; #pragma unroll
;         for (int n = 0; n < 2; ++n) { w0[n] = *(const f32x4*)(cw + ch0 + 4 * n); w1[n] = *(const f32x4*)(cw + DFF + ch0 + 4 * n); w2[n] = *(const f32x4*)(cw + 2 * DFF + ch0 + 4 * n); bb[n] = *(const f32x4*)(cb + ch0 + 4 * n); }
; #pragma unroll
;         for (int ai = 0; ai < 2; ++ai)
; #pragma unroll
;             for (int m = 0; m < 4; ++m) {
;                 const bool efirst = (m == 0) && (fr == 0), elast = (m == 3) && (fr == 15);
;                 const int row = row0 + ai * HALF + m * 16;
;                 f32x4 gc[2];
; #pragma unroll
;                 for (int n = 0; n < 2; ++n) {
;                     const f32x4 g = acc[ai][0][m][n];
;                     const f32x4 gprev = acc[ai][0][m > 0 ? m - 1 : 0][n], gnext = acc[ai][0][m < 3 ? m + 1 : 3][n];
;                     f32x4 up, dn;
; #pragma unroll
;                     for (int e = 0; e < 4; ++e) {
;                         const float pu = (m > 0 && fr == 15) ? gprev[e] : g[e];
;                         const float pd = (m < 3 && fr == 0) ? gnext[e] : g[e];
;                         up[e] = dpp_ror1(pu); dn[e] = dpp_ror15(pd);
;                     }
;                     if (efirst) up = (f32x4){0.f, 0.f, 0.f, 0.f};
;                     if (elast) dn = (f32x4){0.f, 0.f, 0.f, 0.f};
;                     gc[n] = w0[n] * up + w1[n] * g + w2[n] * dn + bb[n];
;                 }
;                 if (efirst || elast) {
;                     const size_t eo = (size_t)((row >> 6) * 2 + (elast ? 1 : 0)) * DFF + ch0;
; #pragma unroll
;                     for (int n = 0; n < 2; ++n) { *(f32x4*)(EP + eo + 4 * n) = gc[n]; *(f32x4*)(ER + eo + 4 * n) = acc[ai][0][m][n]; *(f32x4*)(EV + eo + 4 * n) = acc[ai][1][m][n]; }
;                 } else {
;                     const f32x4 v0 = acc[ai][1][m][0], v1 = acc[ai][1][m][1];
;                     u32x4 o;
;                     o[0] = pack2(silu_mul(gc[0][0], v0[0]), silu_mul(gc[0][1], v0[1])); o[1] = pack2(silu_mul(gc[0][2], v0[2]), silu_mul(gc[0][3], v0[3]));
	s_waitcnt lgkmcnt(0)
	s_lshl_b32 s21, s45, 7
	v_mov_b32_e32 v80, v187
	v_mov_b32_e32 v194, v186
	s_or_b32 s21, s21, s57
	v_lshl_add_u32 v184, v80, 3, s21
	v_ashrrev_i32_e32 v185, 31, v184
	v_lshlrev_b64 v[80:81], 2, v[184:185]
	v_lshl_add_u64 v[84:85], s[4:5], 0, v[80:81]
	v_lshl_add_u64 v[88:89], s[16:17], 0, v[80:81]
	v_lshl_add_u64 v[92:93], s[18:19], 0, v[80:81]
	v_lshl_add_u64 v[112:113], s[6:7], 0, v[80:81]
	global_load_dwordx4 v[80:83], v[84:85], off offset:16
	global_load_dwordx4 v[96:99], v[84:85], off
	s_nop 0
	global_load_dwordx4 v[84:87], v[88:89], off offset:16
	global_load_dwordx4 v[100:103], v[88:89], off
	s_nop 0
	global_load_dwordx4 v[88:91], v[92:93], off offset:16
	global_load_dwordx4 v[108:111], v[92:93], off
	s_nop 0
	global_load_dwordx4 v[92:95], v[112:113], off offset:16
	s_nop 0
	global_load_dwordx4 v[112:115], v[112:113], off
	v_cmp_eq_u32_e32 vcc, 0, v194
	s_nop 0
	s_nop 0
	v_cndmask_b32_e32 v161, v148, v136, vcc
	v_cndmask_b32_e32 v162, v149, v137, vcc
	v_cndmask_b32_e32 v163, v150, v138, vcc
	v_mov_b32_dpp v160, v161 row_ror:15 row_mask:0xf bank_mask:0xf
	s_nop 0
	s_nop 0
	v_mov_b32_dpp v161, v162 row_ror:15 row_mask:0xf bank_mask:0xf
	v_mov_b32_dpp v164, v150 row_ror:1 row_mask:0xf bank_mask:0xf
	v_cndmask_b32_e32 v165, v151, v139, vcc
	v_mov_b32_dpp v162, v163 row_ror:15 row_mask:0xf bank_mask:0xf
	v_mov_b32_dpp v195, v151 row_ror:1 row_mask:0xf bank_mask:0xf
	v_mov_b32_dpp v166, v148 row_ror:1 row_mask:0xf bank_mask:0xf
	v_mov_b32_dpp v167, v149 row_ror:1 row_mask:0xf bank_mask:0xf
	v_mov_b32_dpp v163, v165 row_ror:15 row_mask:0xf bank_mask:0xf
	v_cndmask_b32_e64 v165, v195, 0, vcc
	v_cndmask_b32_e64 v164, v164, 0, vcc
	v_cndmask_b32_e64 v167, v167, 0, vcc
	v_cndmask_b32_e64 v166, v166, 0, vcc
	s_nop 0
	s_nop 0
	v_mov_b32_dpp v195, v144 row_ror:1 row_mask:0xf bank_mask:0xf
	v_mov_b32_dpp v196, v145 row_ror:1 row_mask:0xf bank_mask:0xf
	v_mov_b32_dpp v198, v146 row_ror:1 row_mask:0xf bank_mask:0xf
	v_cndmask_b32_e32 v199, v147, v131, vcc
	v_mov_b32_dpp v200, v147 row_ror:1 row_mask:0xf bank_mask:0xf
	v_cndmask_b32_e64 v198, v198, 0, vcc
	v_cndmask_b32_e64 v201, v196, 0, vcc
	s_lshl_b32 s3, s44, 8
	s_add_i32 s3, s3, s49
	v_add_u32_e32 v193, s3, v194
	v_cmp_ne_u32_e64 s[46:47], 0, v194
	s_waitcnt vmcnt(0)
	v_pk_mul_f32 v[164:165], v[98:99], v[164:165]
	v_pk_mul_f32 v[166:167], v[96:97], v[166:167]
	v_pk_fma_f32 v[164:165], v[150:151], v[102:103], v[164:165]
	v_pk_fma_f32 v[166:167], v[148:149], v[100:101], v[166:167]
	v_pk_fma_f32 v[162:163], v[110:111], v[162:163], v[164:165]
	v_cndmask_b32_e32 v165, v144, v128, vcc
	v_pk_fma_f32 v[160:161], v[108:109], v[160:161], v[166:167]
	v_cndmask_b32_e32 v166, v145, v129, vcc
	v_mov_b32_dpp v164, v165 row_ror:15 row_mask:0xf bank_mask:0xf
	v_cndmask_b32_e32 v167, v146, v130, vcc
	v_pk_add_f32 v[162:163], v[114:115], v[162:163]
	v_mov_b32_dpp v165, v166 row_ror:15 row_mask:0xf bank_mask:0xf
	v_pk_add_f32 v[160:161], v[112:113], v[160:161]
	s_nop 0
	v_mov_b32_dpp v166, v167 row_ror:15 row_mask:0xf bank_mask:0xf
	s_nop 1
	v_mov_b32_dpp v167, v199 row_ror:15 row_mask:0xf bank_mask:0xf
	v_cndmask_b32_e64 v199, v200, 0, vcc
	v_cndmask_b32_e64 v200, v195, 0, vcc
	v_pk_mul_f32 v[200:201], v[80:81], v[200:201]
	v_pk_mul_f32 v[198:199], v[82:83], v[198:199]
	v_pk_fma_f32 v[200:201], v[144:145], v[84:85], v[200:201]
	v_pk_fma_f32 v[198:199], v[146:147], v[86:87], v[198:199]
	v_pk_fma_f32 v[164:165], v[88:89], v[164:165], v[200:201]
	v_pk_fma_f32 v[166:167], v[90:91], v[166:167], v[198:199]
	v_pk_add_f32 v[164:165], v[92:93], v[164:165]
	v_pk_add_f32 v[166:167], v[94:95], v[166:167]
	s_and_saveexec_b64 s[28:29], s[46:47]
	s_xor_b64 s[28:29], exec, s[28:29]
	s_cbranch_execz .LBB1_2486
	v_mul_f32_e32 v195, 0xbfb8aa3b, v160
	v_exp_f32_e32 v195, v195
	v_mul_f32_e32 v196, 0xbfb8aa3b, v161
	v_exp_f32_e32 v196, v196
	v_pk_mul_f32 v[160:161], v[156:157], v[160:161]
	v_add_f32_e32 v195, 1.0, v195
	v_rcp_f32_e32 v198, v195
	v_add_f32_e32 v196, 1.0, v196
	v_mul_f32_e32 v195, 0xbfb8aa3b, v162
	v_rcp_f32_e32 v199, v196
	v_exp_f32_e32 v195, v195
	v_mul_f32_e32 v196, 0xbfb8aa3b, v163
	v_exp_f32_e32 v196, v196
	v_pk_mul_f32 v[160:161], v[160:161], v[198:199]
	v_add_f32_e32 v195, 1.0, v195
	v_rcp_f32_e32 v200, v195
	v_add_f32_e32 v195, 1.0, v196
	v_rcp_f32_e32 v201, v195
	v_cvt_pk_bf16_f32 v160, v160, v161
	v_mul_f32_e32 v161, 0xbfb8aa3b, v164
	v_exp_f32_e32 v195, v161
	v_mul_f32_e32 v161, 0xbfb8aa3b, v165
	v_exp_f32_e32 v196, v161
	v_pk_mul_f32 v[162:163], v[158:159], v[162:163]
	v_pk_mul_f32 v[164:165], v[152:153], v[164:165]
	v_pk_mul_f32 v[162:163], v[162:163], v[200:201]
	s_nop 0
	v_cvt_pk_bf16_f32 v161, v162, v163
	v_add_f32_e32 v162, 1.0, v195
	v_mul_f32_e32 v195, 0xbfb8aa3b, v166
	v_add_f32_e32 v163, 1.0, v196
	v_exp_f32_e32 v195, v195
	v_mul_f32_e32 v196, 0xbfb8aa3b, v167
	v_exp_f32_e32 v196, v196
	v_rcp_f32_e32 v162, v162
	v_add_f32_e32 v195, 1.0, v195
	v_rcp_f32_e32 v198, v195
	v_add_f32_e32 v195, 1.0, v196
	v_rcp_f32_e32 v163, v163
	v_rcp_f32_e32 v199, v195
	v_pk_mul_f32 v[166:167], v[154:155], v[166:167]
	v_pk_mul_f32 v[162:163], v[164:165], v[162:163]
	v_pk_mul_f32 v[164:165], v[166:167], v[198:199]
	v_cvt_pk_bf16_f32 v162, v162, v163
	v_cvt_pk_bf16_f32 v163, v164, v165
	v_mov_b64_e32 v[164:165], s[52:53]
	v_mad_i64_i32 v[164:165], s[42:43], v193, s60, v[164:165]
	v_lshl_add_u64 v[164:165], v[184:185], 1, v[164:165]
	global_store_dwordx4 v[164:165], v[160:163], off
